# compressed branch: K/V^T groups staged once per workgroup in LDS via LDS-DMA (3-stage ring) instead of per-wave global loads
# speedup vs baseline: 1.0879x; 1.0339x over previous
; #define LAS __attribute__((address_space(3)))
; __device__ __forceinline__ void nsa_quad_pre(int bg, int quad, const bf16_t* Q, const bf16_t* KV, const bf16_t* KCMP, const bf16_t* VCMPT, const float* GN, bf16_t* ONSA, ...
;     const int r16 = lane & 15, q4 = lane >> 4, b = bg >> 2, g = bg & 3, t0 = quad * 4;
;     const unsigned koff = (unsigned)(r16 * 64 + q4 * 8) * 2u, voffS = (unsigned)(r16 * SEQ + q4 * 8) * 2u, voffC = (unsigned)(r16 * 512 + q4 * 8) * 2u;
;     const char* KWb = (const char*)(KV + 4 * (size_t)MTOK * 256 + (size_t)bg * SEQ * 64); const char* VWb = (const char*)(KV + 5 * (size_t)MTOK * 256 + (size_t)bg * 64 * SEQ);
;     const char* KCb = (const char*)(KCMP + (size_t)bg * 512 * 64); const char* VCb = (const char*)(VCMPT + (size_t)bg * 64 * 512);
;     ...
;     const size_t qoff = (size_t)(b * SEQ + t0 + (r16 & 3)) * 1024 + (g * 4 + (r16 >> 2)) * 64 + q4 * 8;
;     { const bf16x8 a0 = *(const bf16x8*)(Q + qoff), a1 = *(const bf16x8*)(Q + qoff + 32); *(LAS bf16x8*)(qfw + lane * 8) = a0; *(LAS bf16x8*)(qfw + 512 + lane * 8) = a1; }
;     const LAS bf16_t* qf = qfw + lane * 8;
;     const LAS float* bt = btab + q4 * 1028;
;     const f32x4 z4 = {0.f, 0.f, 0.f, 0.f};
;     KFrag KF; VFrag VF; f32x4 sc[4];
;     const int w_lo = (t0 - 511 > 0 ? t0 - 511 : 0) >> 6, w_hi = t0 >> 6;
;     f32x4 oc[4] = {z4, z4, z4, z4};
;     const int tl = t0 + 3, nvmax = tl >= 31 ? ((tl - 31) >> 4) + 1 : 0, ngr = (nvmax + 63) >> 6;
;     if (ngr > 0) {
;         float ls[4] = {0.f, 0.f, 0.f, 0.f};
;         load_k(KF, KP_C(0));
; __device__ __forceinline__ void nsa_phase(LAS unsigned char* lds, const bf16_t* Q, const bf16_t* KV, const bf16_t* KCMP, const bf16_t* VCMPT, const float* GN, const float* rel_bias, bf16_t* ONSA,
;                                           int tid, int lane, int wave) {
;     ...
;                 const int qb = (kk & 1) ? (32 * kk + 31 - idx) : (32 * kk + idx);
;                 nsa_quad_pre(bg, qb * 16 + wave * 2, Q, KV, KCMP, VCMPT, GN, ONSA, btab, Pb, psum, selall + (wave * 2) * 64, qfw, lane);
.LBB0_738:
	s_lshl_b32 s1, s3, 5
	s_sub_i32 s14, s1, s91
	s_and_b32 s0, s3, 1
	s_add_i32 s14, s14, 31
	s_add_i32 s1, s1, s91
	s_cmp_eq_u32 s0, 0
	s_cselect_b32 s18, s1, s14
	v_and_b32_e32 v232, 15, v184
	v_lshrrev_b32_e32 v233, 4, v184
	v_and_b32_e32 v234, 3, v232
	v_lshrrev_b32_e32 v235, 2, v232
	v_mul_u32_u24_e32 v173, 0x1010, v235
	ds_read_b32 v225, v173 offset:4096
	v_mov_b32_e32 v252, 0xf149f2ca
	v_and_b32_e32 v253, 1, v235
	v_xor_b32_e32 v0, v233, v234
	v_lshlrev_b32_e32 v0, 4, v0
	v_lshl_add_u32 v0, v253, 6, v0
	v_lshl_add_u32 v98, v235, 3, v234
	v_lshl_add_u32 v176, v98, 7, v0
	s_lshl_b32 s33, s80, 7
	v_lshl_add_u32 v177, v232, 7, v0
	v_subrev_u32_e32 v177, s33, v177
	v_lshlrev_b32_e32 v98, 7, v253
	v_sub_u32_e32 v178, 64, v98
	v_lshrrev_b32_e32 v98, 3, v184
	v_and_b32_e32 v99, 7, v184
	s_lshr_b32 s0, s80, 3
	s_and_b32 s1, s0, 1
	s_lshl_b32 s1, s1, 2
	v_and_b32_e32 v253, 3, v98
	v_or_b32_e32 v253, s1, v253
	v_xor_b32_e32 v253, v99, v253
	v_add_u32_e32 v0, s80, v98
	v_lshlrev_b32_e32 v174, 7, v0
	v_lshl_add_u32 v174, v253, 4, v174
	v_xor_b32_e32 v253, v99, v98
	v_lshlrev_b32_e32 v175, 10, v0
	v_lshl_add_u32 v175, v253, 4, v175
	s_add_i32 s94, s33, 0xa040
	s_add_i32 s95, s33, 0x1dc40
	s_add_i32 s46, s33, 0x20200
	s_lshr_b32 s15, s97, 13
	s_lshl_b32 s15, s15, 2
	s_and_b32 s1, s88, 3
	s_or_b32 s15, s15, s1
	s_lshl_b32 s15, s15, 16
	s_add_u32 s68, s30, 0x38110000
	s_addc_u32 s69, s31, 0
	s_add_u32 s68, s68, s15
	s_addc_u32 s69, s69, 0
	s_add_u32 s70, s30, 0x38210000
	s_addc_u32 s71, s31, 0
	s_add_u32 s70, s70, s15
	s_addc_u32 s71, s71, 0
	s_lshl_b32 s74, s18, 2
	s_add_i32 s74, s74, 66
	s_lshr_b32 s74, s74, 6
	s_mov_b32 s75, 0
	s_mov_b32 s92, 0
	s_mov_b32 s93, 0
	s_lshl_b32 s0, s92, 13
	s_add_i32 s0, s0, s33
	s_add_i32 m0, s0, 16448
	s_lshl_b32 s1, s93, 13
	s_add_u32 s72, s68, s1
	s_addc_u32 s73, s69, 0
	global_load_lds_dwordx4 v174, s[72:73]
	s_cmp_eq_u32 s92, 1
	s_cselect_b32 s0, s95, s94
	s_cmp_eq_u32 s92, 2
	s_cselect_b32 m0, s46, s0
	s_lshl_b32 s1, s93, 7
	s_add_u32 s72, s70, s1
	s_addc_u32 s73, s71, 0
	global_load_lds_dwordx4 v175, s[72:73]
	s_add_i32 s93, s93, 1
	s_cmp_ge_i32 s93, s74
	s_cselect_b32 s93, 0, s93
	s_add_i32 s92, s92, 1
	s_cmp_eq_u32 s92, 3
	s_cselect_b32 s92, 0, s92
	s_lshl_b32 s0, s92, 13
	s_add_i32 s0, s0, s33
	s_add_i32 m0, s0, 16448
	s_lshl_b32 s1, s93, 13
	s_add_u32 s72, s68, s1
	s_addc_u32 s73, s69, 0
	global_load_lds_dwordx4 v174, s[72:73]
	s_cmp_eq_u32 s92, 1
	s_cselect_b32 s0, s95, s94
	s_cmp_eq_u32 s92, 2
	s_cselect_b32 m0, s46, s0
	s_lshl_b32 s1, s93, 7
	s_add_u32 s72, s70, s1
	s_addc_u32 s73, s71, 0
	global_load_lds_dwordx4 v175, s[72:73]
	s_add_i32 s93, s93, 1
	s_cmp_ge_i32 s93, s74
	s_cselect_b32 s93, 0, s93
	s_add_i32 s92, s92, 1
	s_cmp_eq_u32 s92, 3
	s_cselect_b32 s92, 0, s92
	v_lshlrev_b32_e32 v98, 7, v233
	v_sub_u32_e32 v172, v234, v98
	v_add_u32_e32 v172, 0xffffffe1, v172
	s_lshl_b32 s0, s80, 10
	s_add_i32 s0, s0, 56384
	v_lshlrev_b32_e32 v215, 11, v234
	v_lshl_add_u32 v215, v233, 5, v215
	v_add_u32_e32 v215, s0, v215
	s_lshl_b32 s0, s18, 6
	s_add_i32 s0, s0, s97
	s_add_i32 s0, s0, s80
	v_add_u32_e32 v253, s0, v234
	s_and_b32 s1, s88, 3
	s_lshl_b32 s1, s1, 2
	v_add_u32_e32 v98, s1, v235
	v_lshlrev_b32_e32 v98, 7, v98
	v_lshl_add_u32 v98, v253, 11, v98
	v_lshl_add_u32 v98, v233, 4, v98
	v_add_u32_e32 v99, 0x2000, v98
	s_add_u32 s72, s30, 0x29900000
	s_addc_u32 s73, s31, 0
	global_load_dwordx4 v[34:37], v98, s[72:73] offset:0
	global_load_dwordx4 v[38:41], v98, s[72:73] offset:64
	global_load_dwordx4 v[42:45], v99, s[72:73] offset:0
	global_load_dwordx4 v[46:49], v99, s[72:73] offset:64
	s_waitcnt lgkmcnt(0)
	s_lshl_b32 s47, s18, 6
	s_add_i32 s47, s47, s80
	v_mov_b32_e32 v2, 0
	v_mov_b32_e32 v3, 0
	v_mov_b32_e32 v4, 0
	v_mov_b32_e32 v5, 0
	v_mov_b32_e32 v6, 0
	v_mov_b32_e32 v7, 0
	v_mov_b32_e32 v8, 0
	v_mov_b32_e32 v9, 0
	v_mov_b32_e32 v10, 0
	v_mov_b32_e32 v11, 0
	v_mov_b32_e32 v12, 0
	v_mov_b32_e32 v13, 0
	v_mov_b32_e32 v14, 0
	v_mov_b32_e32 v15, 0
	v_mov_b32_e32 v16, 0
	v_mov_b32_e32 v17, 0
	s_sub_i32 s0, s47, 28
	s_ashr_i32 s0, s0, 4
	s_add_i32 s0, s0, 64
	s_ashr_i32 s53, s0, 6
	s_cmp_gt_i32 s47, 27
	s_cselect_b32 s53, s53, 0
	s_sub_i32 s0, s47, 2063
	s_ashr_i32 s52, s0, 10
	s_add_i32 s52, s52, 1
	s_max_i32 s52, s52, 0
	s_min_i32 s52, s52, s53
	v_add_u32_e32 v99, s47, v172
	v_and_b32_e32 v98, 15, v184
	v_mov_b32_e32 v170, 0
	s_waitcnt vmcnt(0)
	s_barrier
	s_mov_b32 s57, 0
; #define LAS __attribute__((address_space(3)))
; __device__ __forceinline__ float ex2(float x) { return __builtin_amdgcn_exp2f(x); }
; __device__ __forceinline__ void cmp_sm1(const f32x4 (&sc)[4], int gr, int t0, const LAS float* bt, float (&ls)[4], int r16) {
; #pragma unroll
;     for (int cc = 0; cc < 4; ++cc) {
;         const int cend = (gr * 64 + cc * 16 + r16) * 16 + 31;
; #pragma unroll
;         for (int i = 0; i < 4; ++i) { const int dist = t0 + i - cend; ls[i] += dist >= 0 ? ex2(sc[cc][i] + bt[clampd(dist)]) : 0.f; }
;     }
; }
; __device__ __forceinline__ void nsa_quad_pre(int bg, int quad, const bf16_t* Q, const bf16_t* KV, const bf16_t* KCMP, const bf16_t* VCMPT, const float* GN, bf16_t* ONSA, ...
;     ...
;         for (int gr = 0; gr < ngr; ++gr) {
;             qk_scores(KF, qf, sc);
;             load_k(KF, KP_C(gr + 1 < ngr ? gr + 1 : 0));
;             cmp_sm1(sc, gr, t0, bt, ls, r16);
;         }
.Lcmp_top_q0p1:
	s_cmp_ge_i32 s57, s53
	s_cbranch_scc1 .Lcmp_skip_q0p1
	s_lshl_b32 s0, s75, 13
	s_add_i32 s0, s0, 16448
	v_add_u32_e32 v179, s0, v176
	v_add_u32_e32 v226, v179, v178
	ds_read_b128 v[50:53], v179 offset:0
	ds_read_b128 v[54:57], v226 offset:0
	ds_read_b128 v[58:61], v179 offset:512
	ds_read_b128 v[62:65], v226 offset:512
	ds_read_b128 v[66:69], v179 offset:4096
	ds_read_b128 v[70:73], v226 offset:4096
	ds_read_b128 v[74:77], v179 offset:4608
	ds_read_b128 v[78:81], v226 offset:4608
	s_lshl_b32 s0, s92, 13
	s_add_i32 s0, s0, s33
	s_add_i32 m0, s0, 16448
	s_lshl_b32 s1, s93, 13
	s_add_u32 s72, s68, s1
	s_addc_u32 s73, s69, 0
	global_load_lds_dwordx4 v174, s[72:73]
	s_cmp_eq_u32 s92, 1
	s_cselect_b32 s0, s95, s94
	s_cmp_eq_u32 s92, 2
	s_cselect_b32 m0, s46, s0
	s_lshl_b32 s1, s93, 7
	s_add_u32 s72, s70, s1
	s_addc_u32 s73, s71, 0
	global_load_lds_dwordx4 v175, s[72:73]
	s_add_i32 s93, s93, 1
	s_cmp_ge_i32 s93, s74
	s_cselect_b32 s93, 0, s93
	s_add_i32 s92, s92, 1
	s_cmp_eq_u32 s92, 3
	s_cselect_b32 s92, 0, s92
	s_cmp_lt_i32 s57, s52
	s_cbranch_scc0 .Lcmp_gen_q0p1
	v_mov_b32_e32 v228, v225
	v_mov_b32_e32 v229, v225
	v_mov_b32_e32 v230, v225
	v_mov_b32_e32 v231, v225
	s_waitcnt lgkmcnt(7)
	s_nop 0
	v_mfma_f32_16x16x32_bf16 v[18:21], v[50:53], v[34:37], v[228:231]
	s_waitcnt lgkmcnt(6)
	v_mfma_f32_16x16x32_bf16 v[18:21], v[54:57], v[38:41], v[18:21]
	s_waitcnt lgkmcnt(5)
	v_mfma_f32_16x16x32_bf16 v[22:25], v[58:61], v[34:37], v[228:231]
	s_waitcnt lgkmcnt(4)
	v_mfma_f32_16x16x32_bf16 v[22:25], v[62:65], v[38:41], v[22:25]
	s_waitcnt lgkmcnt(3)
	v_mfma_f32_16x16x32_bf16 v[26:29], v[66:69], v[34:37], v[228:231]
	s_waitcnt lgkmcnt(2)
	v_mfma_f32_16x16x32_bf16 v[26:29], v[70:73], v[38:41], v[26:29]
	s_waitcnt lgkmcnt(1)
	v_mfma_f32_16x16x32_bf16 v[30:33], v[74:77], v[34:37], v[228:231]
	s_waitcnt lgkmcnt(0)
	v_mfma_f32_16x16x32_bf16 v[30:33], v[78:81], v[38:41], v[30:33]
	v_exp_f32_e32 v18, v18
	v_exp_f32_e32 v19, v19
	v_exp_f32_e32 v20, v20
	v_exp_f32_e32 v21, v21
	v_exp_f32_e32 v22, v22
	v_exp_f32_e32 v23, v23
	v_exp_f32_e32 v24, v24
	v_exp_f32_e32 v25, v25
	v_exp_f32_e32 v26, v26
	v_exp_f32_e32 v27, v27
	v_exp_f32_e32 v28, v28
	v_exp_f32_e32 v29, v29
	v_exp_f32_e32 v30, v30
	v_exp_f32_e32 v31, v31
	v_exp_f32_e32 v32, v32
	v_exp_f32_e32 v33, v33
	v_add_f32_e32 v18, v18, v19
	v_add_f32_e32 v20, v20, v21
	v_add_f32_e32 v22, v22, v23
	v_add_f32_e32 v24, v24, v25
	v_add_f32_e32 v26, v26, v27
	v_add_f32_e32 v28, v28, v29
	v_add_f32_e32 v30, v30, v31
	v_add_f32_e32 v32, v32, v33
	v_add_f32_e32 v18, v18, v20
	v_add_f32_e32 v22, v22, v24
	v_add_f32_e32 v26, v26, v28
	v_add_f32_e32 v30, v30, v32
	v_add_f32_e32 v18, v18, v22
	v_add_f32_e32 v26, v26, v30
	v_add_f32_e32 v18, v18, v26
	v_add_f32_e32 v170, v170, v18
	s_branch .Lcmp_tail_q0p1
.Lcmp_gen_q0p1:
	s_nop 1
	s_waitcnt lgkmcnt(7)
	v_mfma_f32_16x16x32_bf16 v[18:21], v[50:53], v[34:37], 0
	s_waitcnt lgkmcnt(6)
	v_mfma_f32_16x16x32_bf16 v[18:21], v[54:57], v[38:41], v[18:21]
	s_waitcnt lgkmcnt(5)
	v_mfma_f32_16x16x32_bf16 v[22:25], v[58:61], v[34:37], 0
	s_waitcnt lgkmcnt(4)
	v_mfma_f32_16x16x32_bf16 v[22:25], v[62:65], v[38:41], v[22:25]
	s_waitcnt lgkmcnt(3)
	v_mfma_f32_16x16x32_bf16 v[26:29], v[66:69], v[34:37], 0
	s_waitcnt lgkmcnt(2)
	v_mfma_f32_16x16x32_bf16 v[26:29], v[70:73], v[38:41], v[26:29]
	s_waitcnt lgkmcnt(1)
	v_mfma_f32_16x16x32_bf16 v[30:33], v[74:77], v[34:37], 0
	s_waitcnt lgkmcnt(0)
	v_mfma_f32_16x16x32_bf16 v[30:33], v[78:81], v[38:41], v[30:33]
	s_lshl_b32 s0, s57, 10
	v_subrev_u32_e32 v224, s0, v99
	v_add_u32_e32 v232, 0x0, v224
	v_min_u32_e32 v232, 0x400, v232
	v_lshl_add_u32 v232, v232, 2, v173
	ds_read_b32 v216, v232
	v_add_u32_e32 v232, 0xfffffff0, v224
	v_min_u32_e32 v232, 0x400, v232
	v_lshl_add_u32 v232, v232, 2, v173
	ds_read_b32 v217, v232
	v_add_u32_e32 v232, 0xffffffe0, v224
	v_min_u32_e32 v232, 0x400, v232
	v_lshl_add_u32 v232, v232, 2, v173
	ds_read_b32 v218, v232
	v_add_u32_e32 v232, 0xffffffd0, v224
	v_min_u32_e32 v232, 0x400, v232
	v_lshl_add_u32 v232, v232, 2, v173
	ds_read_b32 v219, v232
	v_add_u32_e32 v232, 0xffffffc0, v224
	v_min_u32_e32 v232, 0x400, v232
	v_lshl_add_u32 v232, v232, 2, v173
	ds_read_b32 v220, v232
	v_add_u32_e32 v232, 0xffffffb0, v224
	v_min_u32_e32 v232, 0x400, v232
	v_lshl_add_u32 v232, v232, 2, v173
	ds_read_b32 v221, v232
	v_add_u32_e32 v232, 0xffffffa0, v224
	v_min_u32_e32 v232, 0x400, v232
	v_lshl_add_u32 v232, v232, 2, v173
	ds_read_b32 v222, v232
	v_add_u32_e32 v232, 0xffffff90, v224
	v_min_u32_e32 v232, 0x400, v232
	v_lshl_add_u32 v232, v232, 2, v173
	ds_read_b32 v223, v232
	s_waitcnt lgkmcnt(7)
	v_add_u32_e32 v232, 0x0, v224
	v_cmp_le_i32_e32 vcc, 0, v232
	s_nop 1
	v_cndmask_b32_e32 v216, v252, v216, vcc
	v_add_f32_e32 v18, v18, v216
	s_waitcnt lgkmcnt(6)
	v_add_u32_e32 v232, 0xfffffff0, v224
	v_cmp_le_i32_e32 vcc, 0, v232
	s_nop 1
	v_cndmask_b32_e32 v217, v252, v217, vcc
	v_add_f32_e32 v19, v19, v217
	s_waitcnt lgkmcnt(5)
	v_add_u32_e32 v232, 0xffffffe0, v224
	v_cmp_le_i32_e32 vcc, 0, v232
	s_nop 1
	v_cndmask_b32_e32 v218, v252, v218, vcc
	v_add_f32_e32 v20, v20, v218
	s_waitcnt lgkmcnt(4)
	v_add_u32_e32 v232, 0xffffffd0, v224
	v_cmp_le_i32_e32 vcc, 0, v232
	s_nop 1
	v_cndmask_b32_e32 v219, v252, v219, vcc
	v_add_f32_e32 v21, v21, v219
	s_waitcnt lgkmcnt(3)
	v_add_u32_e32 v232, 0xffffffc0, v224
	v_cmp_le_i32_e32 vcc, 0, v232
	s_nop 1
	v_cndmask_b32_e32 v220, v252, v220, vcc
	v_add_f32_e32 v22, v22, v220
	s_waitcnt lgkmcnt(2)
	v_add_u32_e32 v232, 0xffffffb0, v224
	v_cmp_le_i32_e32 vcc, 0, v232
	s_nop 1
	v_cndmask_b32_e32 v221, v252, v221, vcc
	v_add_f32_e32 v23, v23, v221
	s_waitcnt lgkmcnt(1)
; #define LAS __attribute__((address_space(3)))
; __device__ __forceinline__ float red16(float v) { v += __shfl_xor(v, 1); v += __shfl_xor(v, 2); v += __shfl_xor(v, 4); v += __shfl_xor(v, 8); return v; }
; __device__ __forceinline__ float ex2(float x) { return __builtin_amdgcn_exp2f(x); }
; __device__ __forceinline__ void cmp_sm1(const f32x4 (&sc)[4], int gr, int t0, const LAS float* bt, float (&ls)[4], int r16) {
; #pragma unroll
;     for (int cc = 0; cc < 4; ++cc) {
;         const int cend = (gr * 64 + cc * 16 + r16) * 16 + 31;
; #pragma unroll
;         for (int i = 0; i < 4; ++i) { const int dist = t0 + i - cend; ls[i] += dist >= 0 ? ex2(sc[cc][i] + bt[clampd(dist)]) : 0.f; }
;     }
; }
; __device__ __forceinline__ void nsa_quad_pre(int bg, int quad, const bf16_t* Q, const bf16_t* KV, const bf16_t* KCMP, const bf16_t* VCMPT, const float* GN, bf16_t* ONSA, ...
;     ...
;         for (int gr = 0; gr < ngr; ++gr) {
;             qk_scores(KF, qf, sc);
;             load_k(KF, KP_C(gr + 1 < ngr ? gr + 1 : 0));
;             cmp_sm1(sc, gr, t0, bt, ls, r16);
;         }
;         load_v(VF, VP_C(0));
;         float inv[4];
; #pragma unroll
;         for (int i = 0; i < 4; ++i) { const float l = red16(ls[i]); inv[i] = l > 0.f ? 1.f / l : 0.f; }
	v_add_u32_e32 v232, 0xffffffa0, v224
	v_cmp_le_i32_e32 vcc, 0, v232
	s_nop 1
	v_cndmask_b32_e32 v222, v252, v222, vcc
	v_add_f32_e32 v24, v24, v222
	s_waitcnt lgkmcnt(0)
	v_add_u32_e32 v232, 0xffffff90, v224
	v_cmp_le_i32_e32 vcc, 0, v232
	s_nop 1
	v_cndmask_b32_e32 v223, v252, v223, vcc
	v_add_f32_e32 v25, v25, v223
	v_add_u32_e32 v232, 0xfffffe00, v224
	v_min_u32_e32 v232, 0x400, v232
	v_lshl_add_u32 v232, v232, 2, v173
	ds_read_b32 v216, v232
	v_add_u32_e32 v232, 0xfffffdf0, v224
	v_min_u32_e32 v232, 0x400, v232
	v_lshl_add_u32 v232, v232, 2, v173
	ds_read_b32 v217, v232
	v_add_u32_e32 v232, 0xfffffde0, v224
	v_min_u32_e32 v232, 0x400, v232
	v_lshl_add_u32 v232, v232, 2, v173
	ds_read_b32 v218, v232
	v_add_u32_e32 v232, 0xfffffdd0, v224
	v_min_u32_e32 v232, 0x400, v232
	v_lshl_add_u32 v232, v232, 2, v173
	ds_read_b32 v219, v232
	v_add_u32_e32 v232, 0xfffffdc0, v224
	v_min_u32_e32 v232, 0x400, v232
	v_lshl_add_u32 v232, v232, 2, v173
	ds_read_b32 v220, v232
	v_add_u32_e32 v232, 0xfffffdb0, v224
	v_min_u32_e32 v232, 0x400, v232
	v_lshl_add_u32 v232, v232, 2, v173
	ds_read_b32 v221, v232
	v_add_u32_e32 v232, 0xfffffda0, v224
	v_min_u32_e32 v232, 0x400, v232
	v_lshl_add_u32 v232, v232, 2, v173
	ds_read_b32 v222, v232
	v_add_u32_e32 v232, 0xfffffd90, v224
	v_min_u32_e32 v232, 0x400, v232
	v_lshl_add_u32 v232, v232, 2, v173
	ds_read_b32 v223, v232
	s_waitcnt lgkmcnt(7)
	v_add_u32_e32 v232, 0xfffffe00, v224
	v_cmp_le_i32_e32 vcc, 0, v232
	s_nop 1
	v_cndmask_b32_e32 v216, v252, v216, vcc
	v_add_f32_e32 v26, v26, v216
	s_waitcnt lgkmcnt(6)
	v_add_u32_e32 v232, 0xfffffdf0, v224
	v_cmp_le_i32_e32 vcc, 0, v232
	s_nop 1
	v_cndmask_b32_e32 v217, v252, v217, vcc
	v_add_f32_e32 v27, v27, v217
	s_waitcnt lgkmcnt(5)
	v_add_u32_e32 v232, 0xfffffde0, v224
	v_cmp_le_i32_e32 vcc, 0, v232
	s_nop 1
	v_cndmask_b32_e32 v218, v252, v218, vcc
	v_add_f32_e32 v28, v28, v218
	s_waitcnt lgkmcnt(4)
	v_add_u32_e32 v232, 0xfffffdd0, v224
	v_cmp_le_i32_e32 vcc, 0, v232
	s_nop 1
	v_cndmask_b32_e32 v219, v252, v219, vcc
	v_add_f32_e32 v29, v29, v219
	s_waitcnt lgkmcnt(3)
	v_add_u32_e32 v232, 0xfffffdc0, v224
	v_cmp_le_i32_e32 vcc, 0, v232
	s_nop 1
	v_cndmask_b32_e32 v220, v252, v220, vcc
	v_add_f32_e32 v30, v30, v220
	s_waitcnt lgkmcnt(2)
	v_add_u32_e32 v232, 0xfffffdb0, v224
	v_cmp_le_i32_e32 vcc, 0, v232
	s_nop 1
	v_cndmask_b32_e32 v221, v252, v221, vcc
	v_add_f32_e32 v31, v31, v221
	s_waitcnt lgkmcnt(1)
	v_add_u32_e32 v232, 0xfffffda0, v224
	v_cmp_le_i32_e32 vcc, 0, v232
	s_nop 1
	v_cndmask_b32_e32 v222, v252, v222, vcc
	v_add_f32_e32 v32, v32, v222
	s_waitcnt lgkmcnt(0)
	v_add_u32_e32 v232, 0xfffffd90, v224
	v_cmp_le_i32_e32 vcc, 0, v232
	s_nop 1
	v_cndmask_b32_e32 v223, v252, v223, vcc
	v_add_f32_e32 v33, v33, v223
	v_exp_f32_e32 v18, v18
	v_exp_f32_e32 v19, v19
	v_exp_f32_e32 v20, v20
	v_exp_f32_e32 v21, v21
	v_exp_f32_e32 v22, v22
	v_exp_f32_e32 v23, v23
	v_exp_f32_e32 v24, v24
	v_exp_f32_e32 v25, v25
	v_exp_f32_e32 v26, v26
	v_exp_f32_e32 v27, v27
	v_exp_f32_e32 v28, v28
	v_exp_f32_e32 v29, v29
	v_exp_f32_e32 v30, v30
	v_exp_f32_e32 v31, v31
	v_exp_f32_e32 v32, v32
	v_exp_f32_e32 v33, v33
	v_add_f32_e32 v18, v18, v19
	v_add_f32_e32 v20, v20, v21
	v_add_f32_e32 v22, v22, v23
	v_add_f32_e32 v24, v24, v25
	v_add_f32_e32 v26, v26, v27
	v_add_f32_e32 v28, v28, v29
	v_add_f32_e32 v30, v30, v31
	v_add_f32_e32 v32, v32, v33
	v_add_f32_e32 v18, v18, v20
	v_add_f32_e32 v22, v22, v24
	v_add_f32_e32 v26, v26, v28
	v_add_f32_e32 v30, v30, v32
	v_add_f32_e32 v18, v18, v22
	v_add_f32_e32 v26, v26, v30
	v_add_f32_e32 v18, v18, v26
	v_add_f32_e32 v170, v170, v18
	s_branch .Lcmp_tail_q0p1
.Lcmp_skip_q0p1:
	s_lshl_b32 s0, s92, 13
	s_add_i32 s0, s0, s33
	s_add_i32 m0, s0, 16448
	s_lshl_b32 s1, s93, 13
	s_add_u32 s72, s68, s1
	s_addc_u32 s73, s69, 0
	global_load_lds_dwordx4 v174, s[72:73]
	s_cmp_eq_u32 s92, 1
	s_cselect_b32 s0, s95, s94
	s_cmp_eq_u32 s92, 2
	s_cselect_b32 m0, s46, s0
	s_lshl_b32 s1, s93, 7
	s_add_u32 s72, s70, s1
	s_addc_u32 s73, s71, 0
	global_load_lds_dwordx4 v175, s[72:73]
	s_add_i32 s93, s93, 1
	s_cmp_ge_i32 s93, s74
	s_cselect_b32 s93, 0, s93
	s_add_i32 s92, s92, 1
	s_cmp_eq_u32 s92, 3
	s_cselect_b32 s92, 0, s92
.Lcmp_tail_q0p1:
	s_waitcnt vmcnt(2)
	s_barrier
	s_add_i32 s75, s75, 1
	s_cmp_eq_u32 s75, 3
	s_cselect_b32 s75, 0, s75
	s_add_i32 s57, s57, 1
	s_cmp_lt_i32 s57, s74
	s_cbranch_scc1 .Lcmp_top_q0p1
	v_xor_b32_e32 v232, 16, v184
	v_lshlrev_b32_e32 v232, 2, v232
	v_xor_b32_e32 v233, 32, v184
	v_lshlrev_b32_e32 v233, 2, v233
	ds_bpermute_b32 v234, v232, v170
	s_waitcnt lgkmcnt(0)
	v_add_f32_e32 v170, v170, v234
	ds_bpermute_b32 v234, v233, v170
	s_waitcnt lgkmcnt(0)
	v_add_f32_e32 v170, v170, v234
	v_mov_b32_e32 v0, 1.0
	v_div_scale_f32 v232, s[20:21], v170, v170, v0
	v_rcp_f32_e32 v233, v232
	v_div_scale_f32 v234, vcc, v0, v170, v0
	v_fma_f32 v235, -v232, v233, 1.0
	v_fmac_f32_e32 v233, v235, v233
	v_mul_f32_e32 v235, v234, v233
	v_fma_f32 v253, -v232, v235, v234
	v_fmac_f32_e32 v235, v253, v233
	v_fma_f32 v232, -v232, v235, v234
	s_nop 1
	v_div_fmas_f32 v232, v232, v233, v235
	v_div_fixup_f32 v171, v232, v170, v0
	v_cmp_lt_f32_e32 vcc, 0, v170
	s_nop 1
	v_cndmask_b32_e32 v171, 0, v171, vcc
	s_mov_b32 s57, 0
; #define LAS __attribute__((address_space(3)))
; __device__ __forceinline__ bf16_t tobf(float x) { return (bf16_t)pk2(x, 0.f); }
; __device__ __forceinline__ float ex2(float x) { return __builtin_amdgcn_exp2f(x); }
; __device__ __forceinline__ void cmp_sm2(const f32x4 (&sc)[4], int gr, int t0, const LAS float* bt, const float (&inv)[4], LAS bf16_t* Pb, LAS float* psum, int r16, int q4) {
; #pragma unroll
;     for (int cc = 0; cc < 4; ++cc) {
;         const int kk = gr * 64 + cc * 16 + r16, cend = kk * 16 + 31;
; #pragma unroll
;         for (int i = 0; i < 4; ++i) { const int dist = t0 + i - cend; float p = dist >= 0 ? ex2(sc[cc][i] + bt[clampd(dist)]) * inv[i] : 0.f;
;             Pb[(4 * q4 + i) * 72 + cc * 16 + r16] = tobf(p); p += __shfl_xor(p, 16); p += __shfl_xor(p, 32); if (q4 == 0) psum[i * 512 + kk] = p; }
;     }
; }
; __device__ __forceinline__ void nsa_quad_pre(int bg, int quad, const bf16_t* Q, const bf16_t* KV, const bf16_t* KCMP, const bf16_t* VCMPT, const float* GN, bf16_t* ONSA, ...
;     ...
;         for (int gr = 0; gr < ngr; ++gr) {
;             const bool more = gr + 1 < ngr;
;             qk_scores(KF, qf, sc);
;             if (more) load_k(KF, KP_C(gr + 1));
;             cmp_sm2(sc, gr, t0, bt, inv, Pb, psum, r16, q4);
;             pv_step(VF, oc, Pb, r16, q4);
;             if (more) load_v(VF, VP_C(gr + 1));
;         }
.Lcmp_top_q0p2:
	s_cmp_ge_i32 s57, s53
	s_cbranch_scc1 .Lcmp_skip_q0p2
	s_lshl_b32 s0, s75, 13
	s_add_i32 s0, s0, 16448
	v_add_u32_e32 v179, s0, v176
	v_add_u32_e32 v226, v179, v178
	ds_read_b128 v[50:53], v179 offset:0
	ds_read_b128 v[54:57], v226 offset:0
	ds_read_b128 v[58:61], v179 offset:512
	ds_read_b128 v[62:65], v226 offset:512
	ds_read_b128 v[66:69], v179 offset:4096
	ds_read_b128 v[70:73], v226 offset:4096
	ds_read_b128 v[74:77], v179 offset:4608
	ds_read_b128 v[78:81], v226 offset:4608
	s_lshl_b32 s0, s92, 13
	s_add_i32 s0, s0, s33
	s_add_i32 m0, s0, 16448
	s_lshl_b32 s1, s93, 13
	s_add_u32 s72, s68, s1
	s_addc_u32 s73, s69, 0
	global_load_lds_dwordx4 v174, s[72:73]
	s_cmp_eq_u32 s92, 1
	s_cselect_b32 s0, s95, s94
	s_cmp_eq_u32 s92, 2
	s_cselect_b32 m0, s46, s0
	s_lshl_b32 s1, s93, 7
	s_add_u32 s72, s70, s1
	s_addc_u32 s73, s71, 0
	global_load_lds_dwordx4 v175, s[72:73]
	s_add_i32 s93, s93, 1
	s_cmp_ge_i32 s93, s74
	s_cselect_b32 s93, 0, s93
	s_add_i32 s92, s92, 1
	s_cmp_eq_u32 s92, 3
	s_cselect_b32 s92, 0, s92
	s_cmp_lt_i32 s57, s52
	s_cbranch_scc0 .Lcmp_gen_q0p2
	v_mov_b32_e32 v228, v225
	v_mov_b32_e32 v229, v225
	v_mov_b32_e32 v230, v225
	v_mov_b32_e32 v231, v225
	s_waitcnt lgkmcnt(7)
	s_nop 0
	v_mfma_f32_16x16x32_bf16 v[18:21], v[50:53], v[34:37], v[228:231]
	s_waitcnt lgkmcnt(6)
	v_mfma_f32_16x16x32_bf16 v[18:21], v[54:57], v[38:41], v[18:21]
	s_waitcnt lgkmcnt(5)
	v_mfma_f32_16x16x32_bf16 v[22:25], v[58:61], v[34:37], v[228:231]
	s_waitcnt lgkmcnt(4)
	v_mfma_f32_16x16x32_bf16 v[22:25], v[62:65], v[38:41], v[22:25]
	s_waitcnt lgkmcnt(3)
	v_mfma_f32_16x16x32_bf16 v[26:29], v[66:69], v[34:37], v[228:231]
	s_waitcnt lgkmcnt(2)
	v_mfma_f32_16x16x32_bf16 v[26:29], v[70:73], v[38:41], v[26:29]
	s_waitcnt lgkmcnt(1)
	v_mfma_f32_16x16x32_bf16 v[30:33], v[74:77], v[34:37], v[228:231]
	s_waitcnt lgkmcnt(0)
	v_mfma_f32_16x16x32_bf16 v[30:33], v[78:81], v[38:41], v[30:33]
	s_cmp_eq_u32 s75, 1
	s_cselect_b32 s0, s95, s94
	s_cmp_eq_u32 s75, 2
	s_cselect_b32 s0, s46, s0
	v_add_u32_e32 v179, s0, v177
	v_add_u32_e32 v226, v179, v178
	ds_read_b128 v[82:85], v179 offset:0
	ds_read_b128 v[86:89], v226 offset:0
	ds_read_b128 v[90:93], v179 offset:2048
	ds_read_b128 v[94:97], v226 offset:2048
	ds_read_b128 v[236:239], v179 offset:4096
	ds_read_b128 v[240:243], v226 offset:4096
	ds_read_b128 v[244:247], v179 offset:6144
	ds_read_b128 v[248:251], v226 offset:6144
	v_exp_f32_e32 v18, v18
	v_exp_f32_e32 v19, v19
	v_exp_f32_e32 v20, v20
	v_exp_f32_e32 v21, v21
	v_exp_f32_e32 v22, v22
	v_exp_f32_e32 v23, v23
	v_exp_f32_e32 v24, v24
	v_exp_f32_e32 v25, v25
	v_exp_f32_e32 v26, v26
	v_exp_f32_e32 v27, v27
	v_exp_f32_e32 v28, v28
	v_exp_f32_e32 v29, v29
	v_exp_f32_e32 v30, v30
	v_exp_f32_e32 v31, v31
	v_exp_f32_e32 v32, v32
	v_exp_f32_e32 v33, v33
	v_mul_f32_e32 v18, v18, v171
	v_mul_f32_e32 v19, v19, v171
	v_mul_f32_e32 v20, v20, v171
	v_mul_f32_e32 v21, v21, v171
	v_mul_f32_e32 v22, v22, v171
	v_mul_f32_e32 v23, v23, v171
	v_mul_f32_e32 v24, v24, v171
	v_mul_f32_e32 v25, v25, v171
	v_mul_f32_e32 v26, v26, v171
	v_mul_f32_e32 v27, v27, v171
	v_mul_f32_e32 v28, v28, v171
	v_mul_f32_e32 v29, v29, v171
	v_mul_f32_e32 v30, v30, v171
	v_mul_f32_e32 v31, v31, v171
	v_mul_f32_e32 v32, v32, v171
	v_mul_f32_e32 v33, v33, v171
	v_add_f32_dpp v50, v18, v18 row_shr:4 row_mask:0xf bank_mask:0xf
	v_add_f32_dpp v51, v19, v19 row_shr:4 row_mask:0xf bank_mask:0xf
	v_add_f32_dpp v52, v20, v20 row_shr:4 row_mask:0xf bank_mask:0xf
	v_add_f32_dpp v53, v21, v21 row_shr:4 row_mask:0xf bank_mask:0xf
	v_add_f32_dpp v54, v22, v22 row_shr:4 row_mask:0xf bank_mask:0xf
	v_add_f32_dpp v55, v23, v23 row_shr:4 row_mask:0xf bank_mask:0xf
	v_add_f32_dpp v56, v24, v24 row_shr:4 row_mask:0xf bank_mask:0xf
	v_add_f32_dpp v57, v25, v25 row_shr:4 row_mask:0xf bank_mask:0xf
	v_add_f32_dpp v58, v26, v26 row_shr:4 row_mask:0xf bank_mask:0xf
	v_add_f32_dpp v59, v27, v27 row_shr:4 row_mask:0xf bank_mask:0xf
	v_add_f32_dpp v60, v28, v28 row_shr:4 row_mask:0xf bank_mask:0xf
	v_add_f32_dpp v61, v29, v29 row_shr:4 row_mask:0xf bank_mask:0xf
	v_add_f32_dpp v62, v30, v30 row_shr:4 row_mask:0xf bank_mask:0xf
	v_add_f32_dpp v63, v31, v31 row_shr:4 row_mask:0xf bank_mask:0xf
	v_add_f32_dpp v64, v32, v32 row_shr:4 row_mask:0xf bank_mask:0xf
	v_add_f32_dpp v65, v33, v33 row_shr:4 row_mask:0xf bank_mask:0xf
	v_add_f32_dpp v50, v50, v50 row_shr:8 row_mask:0xf bank_mask:0xf
	v_add_f32_dpp v51, v51, v51 row_shr:8 row_mask:0xf bank_mask:0xf
	v_add_f32_dpp v52, v52, v52 row_shr:8 row_mask:0xf bank_mask:0xf
	v_add_f32_dpp v53, v53, v53 row_shr:8 row_mask:0xf bank_mask:0xf
	v_add_f32_dpp v54, v54, v54 row_shr:8 row_mask:0xf bank_mask:0xf
	v_add_f32_dpp v55, v55, v55 row_shr:8 row_mask:0xf bank_mask:0xf
	v_add_f32_dpp v56, v56, v56 row_shr:8 row_mask:0xf bank_mask:0xf
	v_add_f32_dpp v57, v57, v57 row_shr:8 row_mask:0xf bank_mask:0xf
	v_add_f32_dpp v58, v58, v58 row_shr:8 row_mask:0xf bank_mask:0xf
	v_add_f32_dpp v59, v59, v59 row_shr:8 row_mask:0xf bank_mask:0xf
	v_add_f32_dpp v60, v60, v60 row_shr:8 row_mask:0xf bank_mask:0xf
	v_add_f32_dpp v61, v61, v61 row_shr:8 row_mask:0xf bank_mask:0xf
	v_add_f32_dpp v62, v62, v62 row_shr:8 row_mask:0xf bank_mask:0xf
	v_add_f32_dpp v63, v63, v63 row_shr:8 row_mask:0xf bank_mask:0xf
	v_add_f32_dpp v64, v64, v64 row_shr:8 row_mask:0xf bank_mask:0xf
	v_add_f32_dpp v65, v65, v65 row_shr:8 row_mask:0xf bank_mask:0xf
	s_lshl_b32 s0, s57, 8
	v_add_u32_e32 v232, s0, v215
	v_cmp_lt_u32_e32 vcc, 11, v98
	s_nop 0
	s_and_saveexec_b64 s[20:21], vcc
	ds_write_b128 v232, v[50:53] offset:0
	ds_write_b128 v232, v[54:57] offset:16
	ds_write_b128 v232, v[58:61] offset:128
	ds_write_b128 v232, v[62:65] offset:144
	s_or_b64 exec, exec, s[20:21]
	v_cvt_pk_bf16_f32 v216, v18, v19
	v_cvt_pk_bf16_f32 v217, v20, v21
	v_cvt_pk_bf16_f32 v218, v22, v23
	v_cvt_pk_bf16_f32 v219, v24, v25
	v_cvt_pk_bf16_f32 v220, v26, v27
	v_cvt_pk_bf16_f32 v221, v28, v29
	v_cvt_pk_bf16_f32 v222, v30, v31
	v_cvt_pk_bf16_f32 v223, v32, v33
	s_waitcnt lgkmcnt(11)
	v_mfma_f32_16x16x32_bf16 v[2:5], v[82:85], v[216:219], v[2:5]
	s_waitcnt lgkmcnt(10)
	v_mfma_f32_16x16x32_bf16 v[2:5], v[86:89], v[220:223], v[2:5]
	s_waitcnt lgkmcnt(9)
	v_mfma_f32_16x16x32_bf16 v[6:9], v[90:93], v[216:219], v[6:9]
	s_waitcnt lgkmcnt(8)
	v_mfma_f32_16x16x32_bf16 v[6:9], v[94:97], v[220:223], v[6:9]
	s_waitcnt lgkmcnt(7)
	v_mfma_f32_16x16x32_bf16 v[10:13], v[236:239], v[216:219], v[10:13]
	s_waitcnt lgkmcnt(6)
	v_mfma_f32_16x16x32_bf16 v[10:13], v[240:243], v[220:223], v[10:13]
	s_waitcnt lgkmcnt(5)
	v_mfma_f32_16x16x32_bf16 v[14:17], v[244:247], v[216:219], v[14:17]
	s_waitcnt lgkmcnt(4)
	v_mfma_f32_16x16x32_bf16 v[14:17], v[248:251], v[220:223], v[14:17]
	s_branch .Lcmp_tail_q0p2
; #define LAS __attribute__((address_space(3)))
; __device__ __forceinline__ bf16_t tobf(float x) { return (bf16_t)pk2(x, 0.f); }
; __device__ __forceinline__ float ex2(float x) { return __builtin_amdgcn_exp2f(x); }
; __device__ __forceinline__ void cmp_sm2(const f32x4 (&sc)[4], int gr, int t0, const LAS float* bt, const float (&inv)[4], LAS bf16_t* Pb, LAS float* psum, int r16, int q4) {
; #pragma unroll
;     for (int cc = 0; cc < 4; ++cc) {
;         const int kk = gr * 64 + cc * 16 + r16, cend = kk * 16 + 31;
; #pragma unroll
;         for (int i = 0; i < 4; ++i) { const int dist = t0 + i - cend; float p = dist >= 0 ? ex2(sc[cc][i] + bt[clampd(dist)]) * inv[i] : 0.f;
;             Pb[(4 * q4 + i) * 72 + cc * 16 + r16] = tobf(p); p += __shfl_xor(p, 16); p += __shfl_xor(p, 32); if (q4 == 0) psum[i * 512 + kk] = p; }
; __device__ __forceinline__ void nsa_quad_pre(int bg, int quad, const bf16_t* Q, const bf16_t* KV, const bf16_t* KCMP, const bf16_t* VCMPT, const float* GN, bf16_t* ONSA, ...
;     ...
;         for (int gr = 0; gr < ngr; ++gr) {
;             const bool more = gr + 1 < ngr;
;             qk_scores(KF, qf, sc);
;             if (more) load_k(KF, KP_C(gr + 1));
;             cmp_sm2(sc, gr, t0, bt, inv, Pb, psum, r16, q4);
.Lcmp_gen_q0p2:
	s_nop 1
	s_waitcnt lgkmcnt(7)
	v_mfma_f32_16x16x32_bf16 v[18:21], v[50:53], v[34:37], 0
	s_waitcnt lgkmcnt(6)
	v_mfma_f32_16x16x32_bf16 v[18:21], v[54:57], v[38:41], v[18:21]
	s_waitcnt lgkmcnt(5)
	v_mfma_f32_16x16x32_bf16 v[22:25], v[58:61], v[34:37], 0
	s_waitcnt lgkmcnt(4)
	v_mfma_f32_16x16x32_bf16 v[22:25], v[62:65], v[38:41], v[22:25]
	s_waitcnt lgkmcnt(3)
	v_mfma_f32_16x16x32_bf16 v[26:29], v[66:69], v[34:37], 0
	s_waitcnt lgkmcnt(2)
	v_mfma_f32_16x16x32_bf16 v[26:29], v[70:73], v[38:41], v[26:29]
	s_waitcnt lgkmcnt(1)
	v_mfma_f32_16x16x32_bf16 v[30:33], v[74:77], v[34:37], 0
	s_waitcnt lgkmcnt(0)
	v_mfma_f32_16x16x32_bf16 v[30:33], v[78:81], v[38:41], v[30:33]
	s_lshl_b32 s0, s57, 10
	v_subrev_u32_e32 v224, s0, v99
	v_add_u32_e32 v232, 0x0, v224
	v_min_u32_e32 v232, 0x400, v232
	v_lshl_add_u32 v232, v232, 2, v173
	ds_read_b32 v216, v232
	v_add_u32_e32 v232, 0xfffffff0, v224
	v_min_u32_e32 v232, 0x400, v232
	v_lshl_add_u32 v232, v232, 2, v173
	ds_read_b32 v217, v232
	v_add_u32_e32 v232, 0xffffffe0, v224
	v_min_u32_e32 v232, 0x400, v232
	v_lshl_add_u32 v232, v232, 2, v173
	ds_read_b32 v218, v232
	v_add_u32_e32 v232, 0xffffffd0, v224
	v_min_u32_e32 v232, 0x400, v232
	v_lshl_add_u32 v232, v232, 2, v173
	ds_read_b32 v219, v232
	v_add_u32_e32 v232, 0xffffffc0, v224
	v_min_u32_e32 v232, 0x400, v232
	v_lshl_add_u32 v232, v232, 2, v173
	ds_read_b32 v220, v232
	v_add_u32_e32 v232, 0xffffffb0, v224
	v_min_u32_e32 v232, 0x400, v232
	v_lshl_add_u32 v232, v232, 2, v173
	ds_read_b32 v221, v232
	v_add_u32_e32 v232, 0xffffffa0, v224
	v_min_u32_e32 v232, 0x400, v232
	v_lshl_add_u32 v232, v232, 2, v173
	ds_read_b32 v222, v232
	v_add_u32_e32 v232, 0xffffff90, v224
	v_min_u32_e32 v232, 0x400, v232
	v_lshl_add_u32 v232, v232, 2, v173
	ds_read_b32 v223, v232
	s_waitcnt lgkmcnt(7)
	v_add_u32_e32 v232, 0x0, v224
	v_cmp_le_i32_e32 vcc, 0, v232
	s_nop 1
	v_cndmask_b32_e32 v216, v252, v216, vcc
	v_add_f32_e32 v18, v18, v216
	s_waitcnt lgkmcnt(6)
	v_add_u32_e32 v232, 0xfffffff0, v224
	v_cmp_le_i32_e32 vcc, 0, v232
	s_nop 1
	v_cndmask_b32_e32 v217, v252, v217, vcc
	v_add_f32_e32 v19, v19, v217
	s_waitcnt lgkmcnt(5)
	v_add_u32_e32 v232, 0xffffffe0, v224
	v_cmp_le_i32_e32 vcc, 0, v232
	s_nop 1
	v_cndmask_b32_e32 v218, v252, v218, vcc
	v_add_f32_e32 v20, v20, v218
	s_waitcnt lgkmcnt(4)
	v_add_u32_e32 v232, 0xffffffd0, v224
	v_cmp_le_i32_e32 vcc, 0, v232
	s_nop 1
	v_cndmask_b32_e32 v219, v252, v219, vcc
	v_add_f32_e32 v21, v21, v219
	s_waitcnt lgkmcnt(3)
	v_add_u32_e32 v232, 0xffffffc0, v224
	v_cmp_le_i32_e32 vcc, 0, v232
	s_nop 1
	v_cndmask_b32_e32 v220, v252, v220, vcc
	v_add_f32_e32 v22, v22, v220
	s_waitcnt lgkmcnt(2)
	v_add_u32_e32 v232, 0xffffffb0, v224
	v_cmp_le_i32_e32 vcc, 0, v232
	s_nop 1
	v_cndmask_b32_e32 v221, v252, v221, vcc
	v_add_f32_e32 v23, v23, v221
	s_waitcnt lgkmcnt(1)
	v_add_u32_e32 v232, 0xffffffa0, v224
	v_cmp_le_i32_e32 vcc, 0, v232
	s_nop 1
	v_cndmask_b32_e32 v222, v252, v222, vcc
	v_add_f32_e32 v24, v24, v222
	s_waitcnt lgkmcnt(0)
	v_add_u32_e32 v232, 0xffffff90, v224
	v_cmp_le_i32_e32 vcc, 0, v232
	s_nop 1
	v_cndmask_b32_e32 v223, v252, v223, vcc
	v_add_f32_e32 v25, v25, v223
	v_add_u32_e32 v232, 0xfffffe00, v224
	v_min_u32_e32 v232, 0x400, v232
	v_lshl_add_u32 v232, v232, 2, v173
	ds_read_b32 v216, v232
	v_add_u32_e32 v232, 0xfffffdf0, v224
	v_min_u32_e32 v232, 0x400, v232
	v_lshl_add_u32 v232, v232, 2, v173
	ds_read_b32 v217, v232
	v_add_u32_e32 v232, 0xfffffde0, v224
	v_min_u32_e32 v232, 0x400, v232
	v_lshl_add_u32 v232, v232, 2, v173
	ds_read_b32 v218, v232
	v_add_u32_e32 v232, 0xfffffdd0, v224
	v_min_u32_e32 v232, 0x400, v232
	v_lshl_add_u32 v232, v232, 2, v173
	ds_read_b32 v219, v232
	v_add_u32_e32 v232, 0xfffffdc0, v224
	v_min_u32_e32 v232, 0x400, v232
	v_lshl_add_u32 v232, v232, 2, v173
	ds_read_b32 v220, v232
	v_add_u32_e32 v232, 0xfffffdb0, v224
	v_min_u32_e32 v232, 0x400, v232
	v_lshl_add_u32 v232, v232, 2, v173
	ds_read_b32 v221, v232
	v_add_u32_e32 v232, 0xfffffda0, v224
	v_min_u32_e32 v232, 0x400, v232
	v_lshl_add_u32 v232, v232, 2, v173
	ds_read_b32 v222, v232
	v_add_u32_e32 v232, 0xfffffd90, v224
	v_min_u32_e32 v232, 0x400, v232
	v_lshl_add_u32 v232, v232, 2, v173
	ds_read_b32 v223, v232
	s_waitcnt lgkmcnt(7)
	v_add_u32_e32 v232, 0xfffffe00, v224
	v_cmp_le_i32_e32 vcc, 0, v232
	s_nop 1
	v_cndmask_b32_e32 v216, v252, v216, vcc
	v_add_f32_e32 v26, v26, v216
	s_waitcnt lgkmcnt(6)
	v_add_u32_e32 v232, 0xfffffdf0, v224
	v_cmp_le_i32_e32 vcc, 0, v232
	s_nop 1
	v_cndmask_b32_e32 v217, v252, v217, vcc
	v_add_f32_e32 v27, v27, v217
	s_waitcnt lgkmcnt(5)
	v_add_u32_e32 v232, 0xfffffde0, v224
	v_cmp_le_i32_e32 vcc, 0, v232
	s_nop 1
	v_cndmask_b32_e32 v218, v252, v218, vcc
	v_add_f32_e32 v28, v28, v218
	s_waitcnt lgkmcnt(4)
	v_add_u32_e32 v232, 0xfffffdd0, v224
	v_cmp_le_i32_e32 vcc, 0, v232
	s_nop 1
	v_cndmask_b32_e32 v219, v252, v219, vcc
	v_add_f32_e32 v29, v29, v219
	s_waitcnt lgkmcnt(3)
	v_add_u32_e32 v232, 0xfffffdc0, v224
	v_cmp_le_i32_e32 vcc, 0, v232
	s_nop 1
	v_cndmask_b32_e32 v220, v252, v220, vcc
	v_add_f32_e32 v30, v30, v220
	s_waitcnt lgkmcnt(2)
	v_add_u32_e32 v232, 0xfffffdb0, v224
	v_cmp_le_i32_e32 vcc, 0, v232
	s_nop 1
	v_cndmask_b32_e32 v221, v252, v221, vcc
	v_add_f32_e32 v31, v31, v221
	s_waitcnt lgkmcnt(1)
; #define LAS __attribute__((address_space(3)))
; __device__ __forceinline__ bf16_t tobf(float x) { return (bf16_t)pk2(x, 0.f); }
; __device__ __forceinline__ float ex2(float x) { return __builtin_amdgcn_exp2f(x); }
; __device__ __forceinline__ void cmp_sm2(const f32x4 (&sc)[4], int gr, int t0, const LAS float* bt, const float (&inv)[4], LAS bf16_t* Pb, LAS float* psum, int r16, int q4) {
; #pragma unroll
;     for (int cc = 0; cc < 4; ++cc) {
;         const int kk = gr * 64 + cc * 16 + r16, cend = kk * 16 + 31;
; #pragma unroll
;         for (int i = 0; i < 4; ++i) { const int dist = t0 + i - cend; float p = dist >= 0 ? ex2(sc[cc][i] + bt[clampd(dist)]) * inv[i] : 0.f;
;             Pb[(4 * q4 + i) * 72 + cc * 16 + r16] = tobf(p); p += __shfl_xor(p, 16); p += __shfl_xor(p, 32); if (q4 == 0) psum[i * 512 + kk] = p; }
;     }
; }
; __device__ __forceinline__ void nsa_quad_pre(int bg, int quad, const bf16_t* Q, const bf16_t* KV, const bf16_t* KCMP, const bf16_t* VCMPT, const float* GN, bf16_t* ONSA, ...
;     ...
;         for (int gr = 0; gr < ngr; ++gr) {
;             const bool more = gr + 1 < ngr;
;             qk_scores(KF, qf, sc);
;             if (more) load_k(KF, KP_C(gr + 1));
;             cmp_sm2(sc, gr, t0, bt, inv, Pb, psum, r16, q4);
;             pv_step(VF, oc, Pb, r16, q4);
;             if (more) load_v(VF, VP_C(gr + 1));
;         }
	v_add_u32_e32 v232, 0xfffffda0, v224
	v_cmp_le_i32_e32 vcc, 0, v232
	s_nop 1
	v_cndmask_b32_e32 v222, v252, v222, vcc
	v_add_f32_e32 v32, v32, v222
	s_waitcnt lgkmcnt(0)
	v_add_u32_e32 v232, 0xfffffd90, v224
	v_cmp_le_i32_e32 vcc, 0, v232
	s_nop 1
	v_cndmask_b32_e32 v223, v252, v223, vcc
	v_add_f32_e32 v33, v33, v223
	s_cmp_eq_u32 s75, 1
	s_cselect_b32 s0, s95, s94
	s_cmp_eq_u32 s75, 2
	s_cselect_b32 s0, s46, s0
	v_add_u32_e32 v179, s0, v177
	v_add_u32_e32 v226, v179, v178
	ds_read_b128 v[82:85], v179 offset:0
	ds_read_b128 v[86:89], v226 offset:0
	ds_read_b128 v[90:93], v179 offset:2048
	ds_read_b128 v[94:97], v226 offset:2048
	ds_read_b128 v[236:239], v179 offset:4096
	ds_read_b128 v[240:243], v226 offset:4096
	ds_read_b128 v[244:247], v179 offset:6144
	ds_read_b128 v[248:251], v226 offset:6144
	v_exp_f32_e32 v18, v18
	v_exp_f32_e32 v19, v19
	v_exp_f32_e32 v20, v20
	v_exp_f32_e32 v21, v21
	v_exp_f32_e32 v22, v22
	v_exp_f32_e32 v23, v23
	v_exp_f32_e32 v24, v24
	v_exp_f32_e32 v25, v25
	v_exp_f32_e32 v26, v26
	v_exp_f32_e32 v27, v27
	v_exp_f32_e32 v28, v28
	v_exp_f32_e32 v29, v29
	v_exp_f32_e32 v30, v30
	v_exp_f32_e32 v31, v31
	v_exp_f32_e32 v32, v32
	v_exp_f32_e32 v33, v33
	v_mul_f32_e32 v18, v18, v171
	v_mul_f32_e32 v19, v19, v171
	v_mul_f32_e32 v20, v20, v171
	v_mul_f32_e32 v21, v21, v171
	v_mul_f32_e32 v22, v22, v171
	v_mul_f32_e32 v23, v23, v171
	v_mul_f32_e32 v24, v24, v171
	v_mul_f32_e32 v25, v25, v171
	v_mul_f32_e32 v26, v26, v171
	v_mul_f32_e32 v27, v27, v171
	v_mul_f32_e32 v28, v28, v171
	v_mul_f32_e32 v29, v29, v171
	v_mul_f32_e32 v30, v30, v171
	v_mul_f32_e32 v31, v31, v171
	v_mul_f32_e32 v32, v32, v171
	v_mul_f32_e32 v33, v33, v171
	v_add_f32_dpp v50, v18, v18 row_shr:4 row_mask:0xf bank_mask:0xf
	v_add_f32_dpp v51, v19, v19 row_shr:4 row_mask:0xf bank_mask:0xf
	v_add_f32_dpp v52, v20, v20 row_shr:4 row_mask:0xf bank_mask:0xf
	v_add_f32_dpp v53, v21, v21 row_shr:4 row_mask:0xf bank_mask:0xf
	v_add_f32_dpp v54, v22, v22 row_shr:4 row_mask:0xf bank_mask:0xf
	v_add_f32_dpp v55, v23, v23 row_shr:4 row_mask:0xf bank_mask:0xf
	v_add_f32_dpp v56, v24, v24 row_shr:4 row_mask:0xf bank_mask:0xf
	v_add_f32_dpp v57, v25, v25 row_shr:4 row_mask:0xf bank_mask:0xf
	v_add_f32_dpp v58, v26, v26 row_shr:4 row_mask:0xf bank_mask:0xf
	v_add_f32_dpp v59, v27, v27 row_shr:4 row_mask:0xf bank_mask:0xf
	v_add_f32_dpp v60, v28, v28 row_shr:4 row_mask:0xf bank_mask:0xf
	v_add_f32_dpp v61, v29, v29 row_shr:4 row_mask:0xf bank_mask:0xf
	v_add_f32_dpp v62, v30, v30 row_shr:4 row_mask:0xf bank_mask:0xf
	v_add_f32_dpp v63, v31, v31 row_shr:4 row_mask:0xf bank_mask:0xf
	v_add_f32_dpp v64, v32, v32 row_shr:4 row_mask:0xf bank_mask:0xf
	v_add_f32_dpp v65, v33, v33 row_shr:4 row_mask:0xf bank_mask:0xf
	v_add_f32_dpp v50, v50, v50 row_shr:8 row_mask:0xf bank_mask:0xf
	v_add_f32_dpp v51, v51, v51 row_shr:8 row_mask:0xf bank_mask:0xf
	v_add_f32_dpp v52, v52, v52 row_shr:8 row_mask:0xf bank_mask:0xf
	v_add_f32_dpp v53, v53, v53 row_shr:8 row_mask:0xf bank_mask:0xf
	v_add_f32_dpp v54, v54, v54 row_shr:8 row_mask:0xf bank_mask:0xf
	v_add_f32_dpp v55, v55, v55 row_shr:8 row_mask:0xf bank_mask:0xf
	v_add_f32_dpp v56, v56, v56 row_shr:8 row_mask:0xf bank_mask:0xf
	v_add_f32_dpp v57, v57, v57 row_shr:8 row_mask:0xf bank_mask:0xf
	v_add_f32_dpp v58, v58, v58 row_shr:8 row_mask:0xf bank_mask:0xf
	v_add_f32_dpp v59, v59, v59 row_shr:8 row_mask:0xf bank_mask:0xf
	v_add_f32_dpp v60, v60, v60 row_shr:8 row_mask:0xf bank_mask:0xf
	v_add_f32_dpp v61, v61, v61 row_shr:8 row_mask:0xf bank_mask:0xf
	v_add_f32_dpp v62, v62, v62 row_shr:8 row_mask:0xf bank_mask:0xf
	v_add_f32_dpp v63, v63, v63 row_shr:8 row_mask:0xf bank_mask:0xf
	v_add_f32_dpp v64, v64, v64 row_shr:8 row_mask:0xf bank_mask:0xf
	v_add_f32_dpp v65, v65, v65 row_shr:8 row_mask:0xf bank_mask:0xf
	s_lshl_b32 s0, s57, 8
	v_add_u32_e32 v232, s0, v215
	v_cmp_lt_u32_e32 vcc, 11, v98
	s_nop 0
	s_and_saveexec_b64 s[20:21], vcc
	ds_write_b128 v232, v[50:53] offset:0
	ds_write_b128 v232, v[54:57] offset:16
	ds_write_b128 v232, v[58:61] offset:128
	ds_write_b128 v232, v[62:65] offset:144
	s_or_b64 exec, exec, s[20:21]
	v_cvt_pk_bf16_f32 v216, v18, v19
	v_cvt_pk_bf16_f32 v217, v20, v21
	v_cvt_pk_bf16_f32 v218, v22, v23
	v_cvt_pk_bf16_f32 v219, v24, v25
	v_cvt_pk_bf16_f32 v220, v26, v27
	v_cvt_pk_bf16_f32 v221, v28, v29
	v_cvt_pk_bf16_f32 v222, v30, v31
	v_cvt_pk_bf16_f32 v223, v32, v33
	s_waitcnt lgkmcnt(11)
	v_mfma_f32_16x16x32_bf16 v[2:5], v[82:85], v[216:219], v[2:5]
	s_waitcnt lgkmcnt(10)
	v_mfma_f32_16x16x32_bf16 v[2:5], v[86:89], v[220:223], v[2:5]
	s_waitcnt lgkmcnt(9)
	v_mfma_f32_16x16x32_bf16 v[6:9], v[90:93], v[216:219], v[6:9]
	s_waitcnt lgkmcnt(8)
	v_mfma_f32_16x16x32_bf16 v[6:9], v[94:97], v[220:223], v[6:9]
	s_waitcnt lgkmcnt(7)
	v_mfma_f32_16x16x32_bf16 v[10:13], v[236:239], v[216:219], v[10:13]
	s_waitcnt lgkmcnt(6)
	v_mfma_f32_16x16x32_bf16 v[10:13], v[240:243], v[220:223], v[10:13]
	s_waitcnt lgkmcnt(5)
	v_mfma_f32_16x16x32_bf16 v[14:17], v[244:247], v[216:219], v[14:17]
	s_waitcnt lgkmcnt(4)
	v_mfma_f32_16x16x32_bf16 v[14:17], v[248:251], v[220:223], v[14:17]
	s_branch .Lcmp_tail_q0p2

; #define LAS __attribute__((address_space(3)))
; #define CBAR() asm volatile("" ::: "memory")
; __device__ __forceinline__ bf16_t tobf(float x) { return (bf16_t)pk2(x, 0.f); }
; __device__ __forceinline__ void nsa_quad_pre(int bg, int quad, const bf16_t* Q, const bf16_t* KV, const bf16_t* KCMP, const bf16_t* VCMPT, const float* GN, bf16_t* ONSA, ...
;     ...
;         for (int gr = 0; gr < ngr; ++gr) {
;             const bool more = gr + 1 < ngr;
;             qk_scores(KF, qf, sc);
;             if (more) load_k(KF, KP_C(gr + 1));
;             cmp_sm2(sc, gr, t0, bt, inv, Pb, psum, r16, q4);
;             pv_step(VF, oc, Pb, r16, q4);
;             if (more) load_v(VF, VP_C(gr + 1));
;         }
;     }
;     CBAR();
; #pragma unroll
;     for (int tt = 0; tt < 4; ++tt) {
;         const int tok = t0 + tt, cur = tok >> 6;
;         if (cur < 16) { if (lane < 16) selq[tt * 16 + lane] = lane; }
;         else {
;             unsigned k0 = 0u, k1 = 0u;
;             { const int j = lane; if (j >= 1 && j <= cur - 2) { const LAS float* ps = psum + tt * 512 + 4 * j - 1; const float v = ps[0] + ps[1] + ps[2] + ps[3] + ps[4]; k0 = (__builtin_bit_cast(unsigned, v) & ~127u) | (unsigned)(127 - j); } }
;             { const int j = lane + 64; if (j <= cur - 2) { const LAS float* ps = psum + tt * 512 + 4 * j - 1; const float v = ps[0] + ps[1] + ps[2] + ps[3] + ps[4]; k1 = (__builtin_bit_cast(unsigned, v) & ~127u) | (unsigned)(127 - j); } }
;             for (int it = 0; it < 13; ++it) {
;                 unsigned m = k0 > k1 ? k0 : k1;
; #pragma unroll
;                 for (int off = 32; off >= 1; off >>= 1) { const unsigned o = (unsigned)__shfl_xor((int)m, off); m = o > m ? o : m; }
;                 if (k0 == m) k0 = 0u; if (k1 == m) k1 = 0u;
;                 if (lane == 0) selq[tt * 16 + it] = 127 - (int)(m & 127u);
;             }
;             if (lane == 0) { selq[tt * 16 + 13] = 0; selq[tt * 16 + 14] = cur - 1; selq[tt * 16 + 15] = cur; }
;         }
;     }
;     CBAR();
; #pragma unroll
;     for (int tt = 0; tt < 4; ++tt) { const float gc = GN[(size_t)(b * SEQ + t0 + tt) * 48 + (g * 4 + q4) * 3];
;         bf16_t* op = ONSA + (size_t)(b * SEQ + t0 + tt) * 1024 + (g * 4 + q4) * 64 + r16;
; #pragma unroll
;         for (int nt = 0; nt < 4; ++nt) op[nt * 16] = tobf(gc * oc[nt][tt]); }
.Lcmp_tail_q0p2:
	s_waitcnt vmcnt(2) lgkmcnt(0)
	s_barrier
	s_add_i32 s75, s75, 1
	s_cmp_eq_u32 s75, 3
	s_cselect_b32 s75, 0, s75
	s_add_i32 s57, s57, 1
	s_cmp_lt_i32 s57, s74
	s_cbranch_scc1 .Lcmp_top_q0p2
	s_waitcnt lgkmcnt(0)
	s_nop 7
	s_nop 3
	v_and_b32_e32 v232, 15, v184
	v_lshrrev_b32_e32 v233, 4, v184
	v_and_b32_e32 v234, 3, v232
	v_lshrrev_b32_e32 v235, 2, v232
	s_add_i32 s0, s47, s97
	v_add_u32_e32 v253, s0, v234
	s_and_b32 s1, s88, 3
	s_lshl_b32 s1, s1, 2
	v_add_u32_e32 v0, s1, v235
	v_lshlrev_b32_e32 v98, 7, v0
	v_lshl_add_u32 v98, v253, 11, v98
	v_lshl_add_u32 v98, v233, 3, v98
	v_mul_u32_u24_e32 v99, 0xc0, v253
	v_mul_u32_u24_e32 v0, 12, v0
	v_add_u32_e32 v99, v99, v0
	s_add_u32 s72, s30, 0x38310000
	s_addc_u32 s73, s31, 0
	s_add_u32 s14, s30, 0xf900000
	s_addc_u32 s15, s31, 0
	global_load_dword v232, v99, s[72:73]
	s_waitcnt vmcnt(0)
	v_mul_f32_e32 v2, v2, v232
	v_mul_f32_e32 v3, v3, v232
	v_mul_f32_e32 v4, v4, v232
	v_mul_f32_e32 v5, v5, v232
	v_mul_f32_e32 v6, v6, v232
	v_mul_f32_e32 v7, v7, v232
	v_mul_f32_e32 v8, v8, v232
	v_mul_f32_e32 v9, v9, v232
	v_mul_f32_e32 v10, v10, v232
	v_mul_f32_e32 v11, v11, v232
	v_mul_f32_e32 v12, v12, v232
	v_mul_f32_e32 v13, v13, v232
	v_mul_f32_e32 v14, v14, v232
	v_mul_f32_e32 v15, v15, v232
	v_mul_f32_e32 v16, v16, v232
	v_mul_f32_e32 v17, v17, v232
	v_cvt_pk_bf16_f32 v216, v2, v3
	v_cvt_pk_bf16_f32 v217, v4, v5
	v_cvt_pk_bf16_f32 v218, v6, v7
	v_cvt_pk_bf16_f32 v219, v8, v9
	v_cvt_pk_bf16_f32 v220, v10, v11
	v_cvt_pk_bf16_f32 v221, v12, v13
	v_cvt_pk_bf16_f32 v222, v14, v15
	v_cvt_pk_bf16_f32 v223, v16, v17
	global_store_dwordx2 v98, v[216:217], s[14:15] offset:0
	global_store_dwordx2 v98, v[218:219], s[14:15] offset:32
	global_store_dwordx2 v98, v[220:221], s[14:15] offset:64
	global_store_dwordx2 v98, v[222:223], s[14:15] offset:96
	s_waitcnt lgkmcnt(0)
	s_cmp_gt_i32 s18, 15
	s_cbranch_scc0 .Ltopk_small_q0
	s_lshl_b32 s19, s80, 10
	s_add_i32 s19, s19, 56384
	v_lshlrev_b32_e32 v96, 4, v184
	v_add_u32_e32 v96, s19, v96
	v_add_u32_e32 v97, 0xfffffffc, v96
	v_sub_u32_e32 v94, 127, v184
	v_sub_u32_e32 v95, 63, v184
	s_mov_b32 s54, 0xffffff80
	s_add_i32 s21, s18, -2
	v_add_u32_e32 v236, 64, v184
	ds_read_b32 v86, v97 offset:0
	ds_read_b128 v[50:53], v96 offset:0
	ds_read_b32 v87, v97 offset:1024
	ds_read_b128 v[54:57], v96 offset:1024
	ds_read_b32 v88, v97 offset:2048
	ds_read_b128 v[58:61], v96 offset:2048
	ds_read_b32 v89, v97 offset:3072
	ds_read_b128 v[62:65], v96 offset:3072
	s_waitcnt lgkmcnt(6)
	v_add_f32_e32 v86, v86, v50
	v_add_f32_e32 v86, v86, v51
	v_add_f32_e32 v86, v86, v52
	v_add_f32_e32 v86, v86, v53
	v_and_or_b32 v18, v86, s54, v94
	s_waitcnt lgkmcnt(4)
	v_add_f32_e32 v87, v87, v54
	v_add_f32_e32 v87, v87, v55
	v_add_f32_e32 v87, v87, v56
	v_add_f32_e32 v87, v87, v57
	v_and_or_b32 v22, v87, s54, v95
	s_waitcnt lgkmcnt(2)
	v_add_f32_e32 v88, v88, v58
	v_add_f32_e32 v88, v88, v59
	v_add_f32_e32 v88, v88, v60
	v_add_f32_e32 v88, v88, v61
	v_and_or_b32 v19, v88, s54, v94
	s_waitcnt lgkmcnt(0)
	v_add_f32_e32 v89, v89, v62
	v_add_f32_e32 v89, v89, v63
	v_add_f32_e32 v89, v89, v64
	v_add_f32_e32 v89, v89, v65
	v_and_or_b32 v23, v89, s54, v95
	ds_read_b32 v90, v97 offset:4096
	ds_read_b128 v[66:69], v96 offset:4096
	ds_read_b32 v91, v97 offset:5120
	ds_read_b128 v[70:73], v96 offset:5120
	ds_read_b32 v92, v97 offset:6144
	ds_read_b128 v[74:77], v96 offset:6144
	ds_read_b32 v93, v97 offset:7168
	ds_read_b128 v[78:81], v96 offset:7168
	s_waitcnt lgkmcnt(6)
	v_add_f32_e32 v90, v90, v66
	v_add_f32_e32 v90, v90, v67
	v_add_f32_e32 v90, v90, v68
	v_add_f32_e32 v90, v90, v69
	v_and_or_b32 v20, v90, s54, v94
	s_waitcnt lgkmcnt(4)
	v_add_f32_e32 v91, v91, v70
	v_add_f32_e32 v91, v91, v71
	v_add_f32_e32 v91, v91, v72
	v_add_f32_e32 v91, v91, v73
	v_and_or_b32 v24, v91, s54, v95
	s_waitcnt lgkmcnt(2)
	v_add_f32_e32 v92, v92, v74
	v_add_f32_e32 v92, v92, v75
	v_add_f32_e32 v92, v92, v76
	v_add_f32_e32 v92, v92, v77
	v_and_or_b32 v21, v92, s54, v94
	s_waitcnt lgkmcnt(0)
	v_add_f32_e32 v93, v93, v78
	v_add_f32_e32 v93, v93, v79
	v_add_f32_e32 v93, v93, v80
	v_add_f32_e32 v93, v93, v81
	v_and_or_b32 v25, v93, s54, v95
	v_cmp_le_i32_e64 s[14:15], v184, s21
	v_cmp_lt_i32_e64 s[34:35], 0, v184
	s_nop 0
	s_and_b64 s[14:15], s[14:15], s[34:35]
	v_cmp_le_i32_e64 s[34:35], v236, s21
	v_cndmask_b32_e64 v18, 0, v18, s[14:15]
	s_nop 0
	v_cndmask_b32_e64 v22, 0, v22, s[34:35]
	v_mov_b32_e32 v82, 0
	v_cndmask_b32_e64 v19, 0, v19, s[14:15]
	v_cndmask_b32_e64 v23, 0, v23, s[34:35]
	v_mov_b32_e32 v83, 0
	v_cndmask_b32_e64 v20, 0, v20, s[14:15]
	v_cndmask_b32_e64 v24, 0, v24, s[34:35]
	v_mov_b32_e32 v84, 0
	v_cndmask_b32_e64 v21, 0, v21, s[14:15]
	v_cndmask_b32_e64 v25, 0, v25, s[34:35]
	v_mov_b32_e32 v85, 0
	v_max_u32_e32 v26, v18, v22
	v_max_u32_e32 v27, v19, v23
	v_max_u32_e32 v28, v20, v24
	v_max_u32_e32 v29, v21, v25
	v_max_u32_dpp v26, v26, v26 quad_perm:[1,0,3,2] row_mask:0xf bank_mask:0xf
	v_max_u32_dpp v27, v27, v27 quad_perm:[1,0,3,2] row_mask:0xf bank_mask:0xf
	v_max_u32_dpp v28, v28, v28 quad_perm:[1,0,3,2] row_mask:0xf bank_mask:0xf
	v_max_u32_dpp v29, v29, v29 quad_perm:[1,0,3,2] row_mask:0xf bank_mask:0xf
	v_max_u32_dpp v26, v26, v26 quad_perm:[2,3,0,1] row_mask:0xf bank_mask:0xf
	v_max_u32_dpp v27, v27, v27 quad_perm:[2,3,0,1] row_mask:0xf bank_mask:0xf
	v_max_u32_dpp v28, v28, v28 quad_perm:[2,3,0,1] row_mask:0xf bank_mask:0xf
	v_max_u32_dpp v29, v29, v29 quad_perm:[2,3,0,1] row_mask:0xf bank_mask:0xf
	v_max_u32_dpp v26, v26, v26 row_half_mirror row_mask:0xf bank_mask:0xf
	v_max_u32_dpp v27, v27, v27 row_half_mirror row_mask:0xf bank_mask:0xf
	v_max_u32_dpp v28, v28, v28 row_half_mirror row_mask:0xf bank_mask:0xf
	v_max_u32_dpp v29, v29, v29 row_half_mirror row_mask:0xf bank_mask:0xf
	v_max_u32_dpp v26, v26, v26 row_mirror row_mask:0xf bank_mask:0xf
	v_max_u32_dpp v27, v27, v27 row_mirror row_mask:0xf bank_mask:0xf
	v_max_u32_dpp v28, v28, v28 row_mirror row_mask:0xf bank_mask:0xf
	v_max_u32_dpp v29, v29, v29 row_mirror row_mask:0xf bank_mask:0xf
	ds_swizzle_b32 v30, v26 offset:0x401f
	ds_swizzle_b32 v31, v27 offset:0x401f
	ds_swizzle_b32 v32, v28 offset:0x401f
	ds_swizzle_b32 v33, v29 offset:0x401f
	s_waitcnt lgkmcnt(3)
; __device__ __forceinline__ void nsa_quad_pre(int bg, int quad, const bf16_t* Q, const bf16_t* KV, const bf16_t* KCMP, const bf16_t* VCMPT, const float* GN, bf16_t* ONSA, ...
;     ...
;             for (int it = 0; it < 13; ++it) {
;                 unsigned m = k0 > k1 ? k0 : k1;
; #pragma unroll
;                 for (int off = 32; off >= 1; off >>= 1) { const unsigned o = (unsigned)__shfl_xor((int)m, off); m = o > m ? o : m; }
;                 if (k0 == m) k0 = 0u; if (k1 == m) k1 = 0u;
;                 if (lane == 0) selq[tt * 16 + it] = 127 - (int)(m & 127u);
;             }
	v_max_u32_e32 v26, v26, v30
	s_waitcnt lgkmcnt(2)
	v_max_u32_e32 v27, v27, v31
	s_waitcnt lgkmcnt(1)
	v_max_u32_e32 v28, v28, v32
	s_waitcnt lgkmcnt(0)
	v_max_u32_e32 v29, v29, v33
	v_mov_b32_e32 v30, v26
	v_mov_b32_e32 v31, v27
	v_mov_b32_e32 v32, v28
	v_mov_b32_e32 v33, v29
	v_permlane32_swap_b32_e32 v26, v30
	v_permlane32_swap_b32_e32 v27, v31
	v_permlane32_swap_b32_e32 v28, v32
	v_permlane32_swap_b32_e32 v29, v33
	v_max_u32_e32 v26, v26, v30
	v_max_u32_e32 v27, v27, v31
	v_max_u32_e32 v28, v28, v32
	v_max_u32_e32 v29, v29, v33
	v_cmp_eq_u32_e64 s[0:1], 0, v184
	v_and_b32_e32 v236, 127, v26
	v_sub_u32_e32 v236, 127, v236
	v_and_b32_e32 v237, 127, v27
	v_sub_u32_e32 v237, 127, v237
	v_and_b32_e32 v238, 127, v28
	v_sub_u32_e32 v238, 127, v238
	v_and_b32_e32 v239, 127, v29
	v_sub_u32_e32 v239, 127, v239
	v_cndmask_b32_e64 v82, v82, v236, s[0:1]
	v_cndmask_b32_e64 v83, v83, v237, s[0:1]
	v_cndmask_b32_e64 v84, v84, v238, s[0:1]
	v_cndmask_b32_e64 v85, v85, v239, s[0:1]
	v_cmp_eq_u32_e64 s[14:15], v26, v18
	v_cmp_eq_u32_e64 s[34:35], v26, v22
	v_cmp_eq_u32_e64 s[42:43], v27, v19
	v_cmp_eq_u32_e64 s[66:67], v27, v23
	v_cndmask_b32_e64 v18, v18, 0, s[14:15]
	v_cndmask_b32_e64 v22, v22, 0, s[34:35]
	v_cndmask_b32_e64 v19, v19, 0, s[42:43]
	v_cndmask_b32_e64 v23, v23, 0, s[66:67]
	v_cmp_eq_u32_e64 s[14:15], v28, v20
	v_cmp_eq_u32_e64 s[34:35], v28, v24
	v_cmp_eq_u32_e64 s[42:43], v29, v21
	v_cmp_eq_u32_e64 s[66:67], v29, v25
	v_cndmask_b32_e64 v20, v20, 0, s[14:15]
	v_cndmask_b32_e64 v24, v24, 0, s[34:35]
	v_cndmask_b32_e64 v21, v21, 0, s[42:43]
	v_cndmask_b32_e64 v25, v25, 0, s[66:67]
	v_max_u32_e32 v26, v18, v22
	v_max_u32_e32 v27, v19, v23
	v_max_u32_e32 v28, v20, v24
	v_max_u32_e32 v29, v21, v25
	v_max_u32_dpp v26, v26, v26 quad_perm:[1,0,3,2] row_mask:0xf bank_mask:0xf
	v_max_u32_dpp v27, v27, v27 quad_perm:[1,0,3,2] row_mask:0xf bank_mask:0xf
	v_max_u32_dpp v28, v28, v28 quad_perm:[1,0,3,2] row_mask:0xf bank_mask:0xf
	v_max_u32_dpp v29, v29, v29 quad_perm:[1,0,3,2] row_mask:0xf bank_mask:0xf
	v_max_u32_dpp v26, v26, v26 quad_perm:[2,3,0,1] row_mask:0xf bank_mask:0xf
	v_max_u32_dpp v27, v27, v27 quad_perm:[2,3,0,1] row_mask:0xf bank_mask:0xf
	v_max_u32_dpp v28, v28, v28 quad_perm:[2,3,0,1] row_mask:0xf bank_mask:0xf
	v_max_u32_dpp v29, v29, v29 quad_perm:[2,3,0,1] row_mask:0xf bank_mask:0xf
	v_max_u32_dpp v26, v26, v26 row_half_mirror row_mask:0xf bank_mask:0xf
	v_max_u32_dpp v27, v27, v27 row_half_mirror row_mask:0xf bank_mask:0xf
	v_max_u32_dpp v28, v28, v28 row_half_mirror row_mask:0xf bank_mask:0xf
	v_max_u32_dpp v29, v29, v29 row_half_mirror row_mask:0xf bank_mask:0xf
	v_max_u32_dpp v26, v26, v26 row_mirror row_mask:0xf bank_mask:0xf
	v_max_u32_dpp v27, v27, v27 row_mirror row_mask:0xf bank_mask:0xf
	v_max_u32_dpp v28, v28, v28 row_mirror row_mask:0xf bank_mask:0xf
	v_max_u32_dpp v29, v29, v29 row_mirror row_mask:0xf bank_mask:0xf
	ds_swizzle_b32 v30, v26 offset:0x401f
	ds_swizzle_b32 v31, v27 offset:0x401f
	ds_swizzle_b32 v32, v28 offset:0x401f
	ds_swizzle_b32 v33, v29 offset:0x401f
	s_waitcnt lgkmcnt(3)
	v_max_u32_e32 v26, v26, v30
	s_waitcnt lgkmcnt(2)
	v_max_u32_e32 v27, v27, v31
	s_waitcnt lgkmcnt(1)
	v_max_u32_e32 v28, v28, v32
	s_waitcnt lgkmcnt(0)
	v_max_u32_e32 v29, v29, v33
	v_mov_b32_e32 v30, v26
	v_mov_b32_e32 v31, v27
	v_mov_b32_e32 v32, v28
	v_mov_b32_e32 v33, v29
	v_permlane32_swap_b32_e32 v26, v30
	v_permlane32_swap_b32_e32 v27, v31
	v_permlane32_swap_b32_e32 v28, v32
	v_permlane32_swap_b32_e32 v29, v33
	v_max_u32_e32 v26, v26, v30
	v_max_u32_e32 v27, v27, v31
	v_max_u32_e32 v28, v28, v32
	v_max_u32_e32 v29, v29, v33
	v_cmp_eq_u32_e64 s[0:1], 1, v184
	v_and_b32_e32 v236, 127, v26
	v_sub_u32_e32 v236, 127, v236
	v_and_b32_e32 v237, 127, v27
	v_sub_u32_e32 v237, 127, v237
	v_and_b32_e32 v238, 127, v28
	v_sub_u32_e32 v238, 127, v238
	v_and_b32_e32 v239, 127, v29
	v_sub_u32_e32 v239, 127, v239
	v_cndmask_b32_e64 v82, v82, v236, s[0:1]
	v_cndmask_b32_e64 v83, v83, v237, s[0:1]
	v_cndmask_b32_e64 v84, v84, v238, s[0:1]
	v_cndmask_b32_e64 v85, v85, v239, s[0:1]
	v_cmp_eq_u32_e64 s[14:15], v26, v18
	v_cmp_eq_u32_e64 s[34:35], v26, v22
	v_cmp_eq_u32_e64 s[42:43], v27, v19
	v_cmp_eq_u32_e64 s[66:67], v27, v23
	v_cndmask_b32_e64 v18, v18, 0, s[14:15]
	v_cndmask_b32_e64 v22, v22, 0, s[34:35]
	v_cndmask_b32_e64 v19, v19, 0, s[42:43]
	v_cndmask_b32_e64 v23, v23, 0, s[66:67]
	v_cmp_eq_u32_e64 s[14:15], v28, v20
	v_cmp_eq_u32_e64 s[34:35], v28, v24
	v_cmp_eq_u32_e64 s[42:43], v29, v21
	v_cmp_eq_u32_e64 s[66:67], v29, v25
	v_cndmask_b32_e64 v20, v20, 0, s[14:15]
	v_cndmask_b32_e64 v24, v24, 0, s[34:35]
	v_cndmask_b32_e64 v21, v21, 0, s[42:43]
	v_cndmask_b32_e64 v25, v25, 0, s[66:67]
	v_max_u32_e32 v26, v18, v22
	v_max_u32_e32 v27, v19, v23
	v_max_u32_e32 v28, v20, v24
	v_max_u32_e32 v29, v21, v25
	v_max_u32_dpp v26, v26, v26 quad_perm:[1,0,3,2] row_mask:0xf bank_mask:0xf
	v_max_u32_dpp v27, v27, v27 quad_perm:[1,0,3,2] row_mask:0xf bank_mask:0xf
	v_max_u32_dpp v28, v28, v28 quad_perm:[1,0,3,2] row_mask:0xf bank_mask:0xf
	v_max_u32_dpp v29, v29, v29 quad_perm:[1,0,3,2] row_mask:0xf bank_mask:0xf
	v_max_u32_dpp v26, v26, v26 quad_perm:[2,3,0,1] row_mask:0xf bank_mask:0xf
	v_max_u32_dpp v27, v27, v27 quad_perm:[2,3,0,1] row_mask:0xf bank_mask:0xf
	v_max_u32_dpp v28, v28, v28 quad_perm:[2,3,0,1] row_mask:0xf bank_mask:0xf
	v_max_u32_dpp v29, v29, v29 quad_perm:[2,3,0,1] row_mask:0xf bank_mask:0xf
	v_max_u32_dpp v26, v26, v26 row_half_mirror row_mask:0xf bank_mask:0xf
	v_max_u32_dpp v27, v27, v27 row_half_mirror row_mask:0xf bank_mask:0xf
	v_max_u32_dpp v28, v28, v28 row_half_mirror row_mask:0xf bank_mask:0xf
	v_max_u32_dpp v29, v29, v29 row_half_mirror row_mask:0xf bank_mask:0xf
	v_max_u32_dpp v26, v26, v26 row_mirror row_mask:0xf bank_mask:0xf
	v_max_u32_dpp v27, v27, v27 row_mirror row_mask:0xf bank_mask:0xf
	v_max_u32_dpp v28, v28, v28 row_mirror row_mask:0xf bank_mask:0xf
	v_max_u32_dpp v29, v29, v29 row_mirror row_mask:0xf bank_mask:0xf
	ds_swizzle_b32 v30, v26 offset:0x401f
	ds_swizzle_b32 v31, v27 offset:0x401f
	ds_swizzle_b32 v32, v28 offset:0x401f
	ds_swizzle_b32 v33, v29 offset:0x401f
	s_waitcnt lgkmcnt(3)
; __device__ __forceinline__ void nsa_quad_pre(int bg, int quad, const bf16_t* Q, const bf16_t* KV, const bf16_t* KCMP, const bf16_t* VCMPT, const float* GN, bf16_t* ONSA, ...
;     ...
;             for (int it = 0; it < 13; ++it) {
;                 unsigned m = k0 > k1 ? k0 : k1;
; #pragma unroll
;                 for (int off = 32; off >= 1; off >>= 1) { const unsigned o = (unsigned)__shfl_xor((int)m, off); m = o > m ? o : m; }
;                 if (k0 == m) k0 = 0u; if (k1 == m) k1 = 0u;
;                 if (lane == 0) selq[tt * 16 + it] = 127 - (int)(m & 127u);
;             }
	v_max_u32_e32 v26, v26, v30
	s_waitcnt lgkmcnt(2)
	v_max_u32_e32 v27, v27, v31
	s_waitcnt lgkmcnt(1)
	v_max_u32_e32 v28, v28, v32
	s_waitcnt lgkmcnt(0)
	v_max_u32_e32 v29, v29, v33
	v_mov_b32_e32 v30, v26
	v_mov_b32_e32 v31, v27
	v_mov_b32_e32 v32, v28
	v_mov_b32_e32 v33, v29
	v_permlane32_swap_b32_e32 v26, v30
	v_permlane32_swap_b32_e32 v27, v31
	v_permlane32_swap_b32_e32 v28, v32
	v_permlane32_swap_b32_e32 v29, v33
	v_max_u32_e32 v26, v26, v30
	v_max_u32_e32 v27, v27, v31
	v_max_u32_e32 v28, v28, v32
	v_max_u32_e32 v29, v29, v33
	v_cmp_eq_u32_e64 s[0:1], 2, v184
	v_and_b32_e32 v236, 127, v26
	v_sub_u32_e32 v236, 127, v236
	v_and_b32_e32 v237, 127, v27
	v_sub_u32_e32 v237, 127, v237
	v_and_b32_e32 v238, 127, v28
	v_sub_u32_e32 v238, 127, v238
	v_and_b32_e32 v239, 127, v29
	v_sub_u32_e32 v239, 127, v239
	v_cndmask_b32_e64 v82, v82, v236, s[0:1]
	v_cndmask_b32_e64 v83, v83, v237, s[0:1]
	v_cndmask_b32_e64 v84, v84, v238, s[0:1]
	v_cndmask_b32_e64 v85, v85, v239, s[0:1]
	v_cmp_eq_u32_e64 s[14:15], v26, v18
	v_cmp_eq_u32_e64 s[34:35], v26, v22
	v_cmp_eq_u32_e64 s[42:43], v27, v19
	v_cmp_eq_u32_e64 s[66:67], v27, v23
	v_cndmask_b32_e64 v18, v18, 0, s[14:15]
	v_cndmask_b32_e64 v22, v22, 0, s[34:35]
	v_cndmask_b32_e64 v19, v19, 0, s[42:43]
	v_cndmask_b32_e64 v23, v23, 0, s[66:67]
	v_cmp_eq_u32_e64 s[14:15], v28, v20
	v_cmp_eq_u32_e64 s[34:35], v28, v24
	v_cmp_eq_u32_e64 s[42:43], v29, v21
	v_cmp_eq_u32_e64 s[66:67], v29, v25
	v_cndmask_b32_e64 v20, v20, 0, s[14:15]
	v_cndmask_b32_e64 v24, v24, 0, s[34:35]
	v_cndmask_b32_e64 v21, v21, 0, s[42:43]
	v_cndmask_b32_e64 v25, v25, 0, s[66:67]
	v_max_u32_e32 v26, v18, v22
	v_max_u32_e32 v27, v19, v23
	v_max_u32_e32 v28, v20, v24
	v_max_u32_e32 v29, v21, v25
	v_max_u32_dpp v26, v26, v26 quad_perm:[1,0,3,2] row_mask:0xf bank_mask:0xf
	v_max_u32_dpp v27, v27, v27 quad_perm:[1,0,3,2] row_mask:0xf bank_mask:0xf
	v_max_u32_dpp v28, v28, v28 quad_perm:[1,0,3,2] row_mask:0xf bank_mask:0xf
	v_max_u32_dpp v29, v29, v29 quad_perm:[1,0,3,2] row_mask:0xf bank_mask:0xf
	v_max_u32_dpp v26, v26, v26 quad_perm:[2,3,0,1] row_mask:0xf bank_mask:0xf
	v_max_u32_dpp v27, v27, v27 quad_perm:[2,3,0,1] row_mask:0xf bank_mask:0xf
	v_max_u32_dpp v28, v28, v28 quad_perm:[2,3,0,1] row_mask:0xf bank_mask:0xf
	v_max_u32_dpp v29, v29, v29 quad_perm:[2,3,0,1] row_mask:0xf bank_mask:0xf
	v_max_u32_dpp v26, v26, v26 row_half_mirror row_mask:0xf bank_mask:0xf
	v_max_u32_dpp v27, v27, v27 row_half_mirror row_mask:0xf bank_mask:0xf
	v_max_u32_dpp v28, v28, v28 row_half_mirror row_mask:0xf bank_mask:0xf
	v_max_u32_dpp v29, v29, v29 row_half_mirror row_mask:0xf bank_mask:0xf
	v_max_u32_dpp v26, v26, v26 row_mirror row_mask:0xf bank_mask:0xf
	v_max_u32_dpp v27, v27, v27 row_mirror row_mask:0xf bank_mask:0xf
	v_max_u32_dpp v28, v28, v28 row_mirror row_mask:0xf bank_mask:0xf
	v_max_u32_dpp v29, v29, v29 row_mirror row_mask:0xf bank_mask:0xf
	ds_swizzle_b32 v30, v26 offset:0x401f
	ds_swizzle_b32 v31, v27 offset:0x401f
	ds_swizzle_b32 v32, v28 offset:0x401f
	ds_swizzle_b32 v33, v29 offset:0x401f
	s_waitcnt lgkmcnt(3)
	v_max_u32_e32 v26, v26, v30
	s_waitcnt lgkmcnt(2)
	v_max_u32_e32 v27, v27, v31
	s_waitcnt lgkmcnt(1)
	v_max_u32_e32 v28, v28, v32
	s_waitcnt lgkmcnt(0)
	v_max_u32_e32 v29, v29, v33
	v_mov_b32_e32 v30, v26
	v_mov_b32_e32 v31, v27
	v_mov_b32_e32 v32, v28
	v_mov_b32_e32 v33, v29
	v_permlane32_swap_b32_e32 v26, v30
	v_permlane32_swap_b32_e32 v27, v31
	v_permlane32_swap_b32_e32 v28, v32
	v_permlane32_swap_b32_e32 v29, v33
	v_max_u32_e32 v26, v26, v30
	v_max_u32_e32 v27, v27, v31
	v_max_u32_e32 v28, v28, v32
	v_max_u32_e32 v29, v29, v33
	v_cmp_eq_u32_e64 s[0:1], 3, v184
	v_and_b32_e32 v236, 127, v26
	v_sub_u32_e32 v236, 127, v236
	v_and_b32_e32 v237, 127, v27
	v_sub_u32_e32 v237, 127, v237
	v_and_b32_e32 v238, 127, v28
	v_sub_u32_e32 v238, 127, v238
	v_and_b32_e32 v239, 127, v29
	v_sub_u32_e32 v239, 127, v239
	v_cndmask_b32_e64 v82, v82, v236, s[0:1]
	v_cndmask_b32_e64 v83, v83, v237, s[0:1]
	v_cndmask_b32_e64 v84, v84, v238, s[0:1]
	v_cndmask_b32_e64 v85, v85, v239, s[0:1]
	v_cmp_eq_u32_e64 s[14:15], v26, v18
	v_cmp_eq_u32_e64 s[34:35], v26, v22
	v_cmp_eq_u32_e64 s[42:43], v27, v19
	v_cmp_eq_u32_e64 s[66:67], v27, v23
	v_cndmask_b32_e64 v18, v18, 0, s[14:15]
	v_cndmask_b32_e64 v22, v22, 0, s[34:35]
	v_cndmask_b32_e64 v19, v19, 0, s[42:43]
	v_cndmask_b32_e64 v23, v23, 0, s[66:67]
	v_cmp_eq_u32_e64 s[14:15], v28, v20
	v_cmp_eq_u32_e64 s[34:35], v28, v24
	v_cmp_eq_u32_e64 s[42:43], v29, v21
	v_cmp_eq_u32_e64 s[66:67], v29, v25
	v_cndmask_b32_e64 v20, v20, 0, s[14:15]
	v_cndmask_b32_e64 v24, v24, 0, s[34:35]
	v_cndmask_b32_e64 v21, v21, 0, s[42:43]
	v_cndmask_b32_e64 v25, v25, 0, s[66:67]
	v_max_u32_e32 v26, v18, v22
	v_max_u32_e32 v27, v19, v23
	v_max_u32_e32 v28, v20, v24
	v_max_u32_e32 v29, v21, v25
	v_max_u32_dpp v26, v26, v26 quad_perm:[1,0,3,2] row_mask:0xf bank_mask:0xf
	v_max_u32_dpp v27, v27, v27 quad_perm:[1,0,3,2] row_mask:0xf bank_mask:0xf
	v_max_u32_dpp v28, v28, v28 quad_perm:[1,0,3,2] row_mask:0xf bank_mask:0xf
	v_max_u32_dpp v29, v29, v29 quad_perm:[1,0,3,2] row_mask:0xf bank_mask:0xf
	v_max_u32_dpp v26, v26, v26 quad_perm:[2,3,0,1] row_mask:0xf bank_mask:0xf
	v_max_u32_dpp v27, v27, v27 quad_perm:[2,3,0,1] row_mask:0xf bank_mask:0xf
	v_max_u32_dpp v28, v28, v28 quad_perm:[2,3,0,1] row_mask:0xf bank_mask:0xf
	v_max_u32_dpp v29, v29, v29 quad_perm:[2,3,0,1] row_mask:0xf bank_mask:0xf
	v_max_u32_dpp v26, v26, v26 row_half_mirror row_mask:0xf bank_mask:0xf
	v_max_u32_dpp v27, v27, v27 row_half_mirror row_mask:0xf bank_mask:0xf
	v_max_u32_dpp v28, v28, v28 row_half_mirror row_mask:0xf bank_mask:0xf
	v_max_u32_dpp v29, v29, v29 row_half_mirror row_mask:0xf bank_mask:0xf
	v_max_u32_dpp v26, v26, v26 row_mirror row_mask:0xf bank_mask:0xf
	v_max_u32_dpp v27, v27, v27 row_mirror row_mask:0xf bank_mask:0xf
	v_max_u32_dpp v28, v28, v28 row_mirror row_mask:0xf bank_mask:0xf
	v_max_u32_dpp v29, v29, v29 row_mirror row_mask:0xf bank_mask:0xf
	ds_swizzle_b32 v30, v26 offset:0x401f
	ds_swizzle_b32 v31, v27 offset:0x401f
	ds_swizzle_b32 v32, v28 offset:0x401f
	ds_swizzle_b32 v33, v29 offset:0x401f
	s_waitcnt lgkmcnt(3)
; __device__ __forceinline__ void nsa_quad_pre(int bg, int quad, const bf16_t* Q, const bf16_t* KV, const bf16_t* KCMP, const bf16_t* VCMPT, const float* GN, bf16_t* ONSA, ...
;     ...
;             for (int it = 0; it < 13; ++it) {
;                 unsigned m = k0 > k1 ? k0 : k1;
; #pragma unroll
;                 for (int off = 32; off >= 1; off >>= 1) { const unsigned o = (unsigned)__shfl_xor((int)m, off); m = o > m ? o : m; }
;                 if (k0 == m) k0 = 0u; if (k1 == m) k1 = 0u;
;                 if (lane == 0) selq[tt * 16 + it] = 127 - (int)(m & 127u);
;             }
	v_max_u32_e32 v26, v26, v30
	s_waitcnt lgkmcnt(2)
	v_max_u32_e32 v27, v27, v31
	s_waitcnt lgkmcnt(1)
	v_max_u32_e32 v28, v28, v32
	s_waitcnt lgkmcnt(0)
	v_max_u32_e32 v29, v29, v33
	v_mov_b32_e32 v30, v26
	v_mov_b32_e32 v31, v27
	v_mov_b32_e32 v32, v28
	v_mov_b32_e32 v33, v29
	v_permlane32_swap_b32_e32 v26, v30
	v_permlane32_swap_b32_e32 v27, v31
	v_permlane32_swap_b32_e32 v28, v32
	v_permlane32_swap_b32_e32 v29, v33
	v_max_u32_e32 v26, v26, v30
	v_max_u32_e32 v27, v27, v31
	v_max_u32_e32 v28, v28, v32
	v_max_u32_e32 v29, v29, v33
	v_cmp_eq_u32_e64 s[0:1], 4, v184
	v_and_b32_e32 v236, 127, v26
	v_sub_u32_e32 v236, 127, v236
	v_and_b32_e32 v237, 127, v27
	v_sub_u32_e32 v237, 127, v237
	v_and_b32_e32 v238, 127, v28
	v_sub_u32_e32 v238, 127, v238
	v_and_b32_e32 v239, 127, v29
	v_sub_u32_e32 v239, 127, v239
	v_cndmask_b32_e64 v82, v82, v236, s[0:1]
	v_cndmask_b32_e64 v83, v83, v237, s[0:1]
	v_cndmask_b32_e64 v84, v84, v238, s[0:1]
	v_cndmask_b32_e64 v85, v85, v239, s[0:1]
	v_cmp_eq_u32_e64 s[14:15], v26, v18
	v_cmp_eq_u32_e64 s[34:35], v26, v22
	v_cmp_eq_u32_e64 s[42:43], v27, v19
	v_cmp_eq_u32_e64 s[66:67], v27, v23
	v_cndmask_b32_e64 v18, v18, 0, s[14:15]
	v_cndmask_b32_e64 v22, v22, 0, s[34:35]
	v_cndmask_b32_e64 v19, v19, 0, s[42:43]
	v_cndmask_b32_e64 v23, v23, 0, s[66:67]
	v_cmp_eq_u32_e64 s[14:15], v28, v20
	v_cmp_eq_u32_e64 s[34:35], v28, v24
	v_cmp_eq_u32_e64 s[42:43], v29, v21
	v_cmp_eq_u32_e64 s[66:67], v29, v25
	v_cndmask_b32_e64 v20, v20, 0, s[14:15]
	v_cndmask_b32_e64 v24, v24, 0, s[34:35]
	v_cndmask_b32_e64 v21, v21, 0, s[42:43]
	v_cndmask_b32_e64 v25, v25, 0, s[66:67]
	v_max_u32_e32 v26, v18, v22
	v_max_u32_e32 v27, v19, v23
	v_max_u32_e32 v28, v20, v24
	v_max_u32_e32 v29, v21, v25
	v_max_u32_dpp v26, v26, v26 quad_perm:[1,0,3,2] row_mask:0xf bank_mask:0xf
	v_max_u32_dpp v27, v27, v27 quad_perm:[1,0,3,2] row_mask:0xf bank_mask:0xf
	v_max_u32_dpp v28, v28, v28 quad_perm:[1,0,3,2] row_mask:0xf bank_mask:0xf
	v_max_u32_dpp v29, v29, v29 quad_perm:[1,0,3,2] row_mask:0xf bank_mask:0xf
	v_max_u32_dpp v26, v26, v26 quad_perm:[2,3,0,1] row_mask:0xf bank_mask:0xf
	v_max_u32_dpp v27, v27, v27 quad_perm:[2,3,0,1] row_mask:0xf bank_mask:0xf
	v_max_u32_dpp v28, v28, v28 quad_perm:[2,3,0,1] row_mask:0xf bank_mask:0xf
	v_max_u32_dpp v29, v29, v29 quad_perm:[2,3,0,1] row_mask:0xf bank_mask:0xf
	v_max_u32_dpp v26, v26, v26 row_half_mirror row_mask:0xf bank_mask:0xf
	v_max_u32_dpp v27, v27, v27 row_half_mirror row_mask:0xf bank_mask:0xf
	v_max_u32_dpp v28, v28, v28 row_half_mirror row_mask:0xf bank_mask:0xf
	v_max_u32_dpp v29, v29, v29 row_half_mirror row_mask:0xf bank_mask:0xf
	v_max_u32_dpp v26, v26, v26 row_mirror row_mask:0xf bank_mask:0xf
	v_max_u32_dpp v27, v27, v27 row_mirror row_mask:0xf bank_mask:0xf
	v_max_u32_dpp v28, v28, v28 row_mirror row_mask:0xf bank_mask:0xf
	v_max_u32_dpp v29, v29, v29 row_mirror row_mask:0xf bank_mask:0xf
	ds_swizzle_b32 v30, v26 offset:0x401f
	ds_swizzle_b32 v31, v27 offset:0x401f
	ds_swizzle_b32 v32, v28 offset:0x401f
	ds_swizzle_b32 v33, v29 offset:0x401f
	s_waitcnt lgkmcnt(3)
	v_max_u32_e32 v26, v26, v30
	s_waitcnt lgkmcnt(2)
	v_max_u32_e32 v27, v27, v31
	s_waitcnt lgkmcnt(1)
	v_max_u32_e32 v28, v28, v32
	s_waitcnt lgkmcnt(0)
	v_max_u32_e32 v29, v29, v33
	v_mov_b32_e32 v30, v26
	v_mov_b32_e32 v31, v27
	v_mov_b32_e32 v32, v28
	v_mov_b32_e32 v33, v29
	v_permlane32_swap_b32_e32 v26, v30
	v_permlane32_swap_b32_e32 v27, v31
	v_permlane32_swap_b32_e32 v28, v32
	v_permlane32_swap_b32_e32 v29, v33
	v_max_u32_e32 v26, v26, v30
	v_max_u32_e32 v27, v27, v31
	v_max_u32_e32 v28, v28, v32
	v_max_u32_e32 v29, v29, v33
	v_cmp_eq_u32_e64 s[0:1], 5, v184
	v_and_b32_e32 v236, 127, v26
	v_sub_u32_e32 v236, 127, v236
	v_and_b32_e32 v237, 127, v27
	v_sub_u32_e32 v237, 127, v237
	v_and_b32_e32 v238, 127, v28
	v_sub_u32_e32 v238, 127, v238
	v_and_b32_e32 v239, 127, v29
	v_sub_u32_e32 v239, 127, v239
	v_cndmask_b32_e64 v82, v82, v236, s[0:1]
	v_cndmask_b32_e64 v83, v83, v237, s[0:1]
	v_cndmask_b32_e64 v84, v84, v238, s[0:1]
	v_cndmask_b32_e64 v85, v85, v239, s[0:1]
	v_cmp_eq_u32_e64 s[14:15], v26, v18
	v_cmp_eq_u32_e64 s[34:35], v26, v22
	v_cmp_eq_u32_e64 s[42:43], v27, v19
	v_cmp_eq_u32_e64 s[66:67], v27, v23
	v_cndmask_b32_e64 v18, v18, 0, s[14:15]
	v_cndmask_b32_e64 v22, v22, 0, s[34:35]
	v_cndmask_b32_e64 v19, v19, 0, s[42:43]
	v_cndmask_b32_e64 v23, v23, 0, s[66:67]
	v_cmp_eq_u32_e64 s[14:15], v28, v20
	v_cmp_eq_u32_e64 s[34:35], v28, v24
	v_cmp_eq_u32_e64 s[42:43], v29, v21
	v_cmp_eq_u32_e64 s[66:67], v29, v25
	v_cndmask_b32_e64 v20, v20, 0, s[14:15]
	v_cndmask_b32_e64 v24, v24, 0, s[34:35]
	v_cndmask_b32_e64 v21, v21, 0, s[42:43]
	v_cndmask_b32_e64 v25, v25, 0, s[66:67]
	v_max_u32_e32 v26, v18, v22
	v_max_u32_e32 v27, v19, v23
	v_max_u32_e32 v28, v20, v24
	v_max_u32_e32 v29, v21, v25
	v_max_u32_dpp v26, v26, v26 quad_perm:[1,0,3,2] row_mask:0xf bank_mask:0xf
	v_max_u32_dpp v27, v27, v27 quad_perm:[1,0,3,2] row_mask:0xf bank_mask:0xf
	v_max_u32_dpp v28, v28, v28 quad_perm:[1,0,3,2] row_mask:0xf bank_mask:0xf
	v_max_u32_dpp v29, v29, v29 quad_perm:[1,0,3,2] row_mask:0xf bank_mask:0xf
	v_max_u32_dpp v26, v26, v26 quad_perm:[2,3,0,1] row_mask:0xf bank_mask:0xf
	v_max_u32_dpp v27, v27, v27 quad_perm:[2,3,0,1] row_mask:0xf bank_mask:0xf
	v_max_u32_dpp v28, v28, v28 quad_perm:[2,3,0,1] row_mask:0xf bank_mask:0xf
	v_max_u32_dpp v29, v29, v29 quad_perm:[2,3,0,1] row_mask:0xf bank_mask:0xf
	v_max_u32_dpp v26, v26, v26 row_half_mirror row_mask:0xf bank_mask:0xf
	v_max_u32_dpp v27, v27, v27 row_half_mirror row_mask:0xf bank_mask:0xf
	v_max_u32_dpp v28, v28, v28 row_half_mirror row_mask:0xf bank_mask:0xf
	v_max_u32_dpp v29, v29, v29 row_half_mirror row_mask:0xf bank_mask:0xf
	v_max_u32_dpp v26, v26, v26 row_mirror row_mask:0xf bank_mask:0xf
	v_max_u32_dpp v27, v27, v27 row_mirror row_mask:0xf bank_mask:0xf
	v_max_u32_dpp v28, v28, v28 row_mirror row_mask:0xf bank_mask:0xf
	v_max_u32_dpp v29, v29, v29 row_mirror row_mask:0xf bank_mask:0xf
	ds_swizzle_b32 v30, v26 offset:0x401f
	ds_swizzle_b32 v31, v27 offset:0x401f
	ds_swizzle_b32 v32, v28 offset:0x401f
	ds_swizzle_b32 v33, v29 offset:0x401f
	s_waitcnt lgkmcnt(3)
; __device__ __forceinline__ void nsa_quad_pre(int bg, int quad, const bf16_t* Q, const bf16_t* KV, const bf16_t* KCMP, const bf16_t* VCMPT, const float* GN, bf16_t* ONSA, ...
;     ...
;             for (int it = 0; it < 13; ++it) {
;                 unsigned m = k0 > k1 ? k0 : k1;
; #pragma unroll
;                 for (int off = 32; off >= 1; off >>= 1) { const unsigned o = (unsigned)__shfl_xor((int)m, off); m = o > m ? o : m; }
;                 if (k0 == m) k0 = 0u; if (k1 == m) k1 = 0u;
;                 if (lane == 0) selq[tt * 16 + it] = 127 - (int)(m & 127u);
;             }
	v_max_u32_e32 v26, v26, v30
	s_waitcnt lgkmcnt(2)
	v_max_u32_e32 v27, v27, v31
	s_waitcnt lgkmcnt(1)
	v_max_u32_e32 v28, v28, v32
	s_waitcnt lgkmcnt(0)
	v_max_u32_e32 v29, v29, v33
	v_mov_b32_e32 v30, v26
	v_mov_b32_e32 v31, v27
	v_mov_b32_e32 v32, v28
	v_mov_b32_e32 v33, v29
	v_permlane32_swap_b32_e32 v26, v30
	v_permlane32_swap_b32_e32 v27, v31
	v_permlane32_swap_b32_e32 v28, v32
	v_permlane32_swap_b32_e32 v29, v33
	v_max_u32_e32 v26, v26, v30
	v_max_u32_e32 v27, v27, v31
	v_max_u32_e32 v28, v28, v32
	v_max_u32_e32 v29, v29, v33
	v_cmp_eq_u32_e64 s[0:1], 6, v184
	v_and_b32_e32 v236, 127, v26
	v_sub_u32_e32 v236, 127, v236
	v_and_b32_e32 v237, 127, v27
	v_sub_u32_e32 v237, 127, v237
	v_and_b32_e32 v238, 127, v28
	v_sub_u32_e32 v238, 127, v238
	v_and_b32_e32 v239, 127, v29
	v_sub_u32_e32 v239, 127, v239
	v_cndmask_b32_e64 v82, v82, v236, s[0:1]
	v_cndmask_b32_e64 v83, v83, v237, s[0:1]
	v_cndmask_b32_e64 v84, v84, v238, s[0:1]
	v_cndmask_b32_e64 v85, v85, v239, s[0:1]
	v_cmp_eq_u32_e64 s[14:15], v26, v18
	v_cmp_eq_u32_e64 s[34:35], v26, v22
	v_cmp_eq_u32_e64 s[42:43], v27, v19
	v_cmp_eq_u32_e64 s[66:67], v27, v23
	v_cndmask_b32_e64 v18, v18, 0, s[14:15]
	v_cndmask_b32_e64 v22, v22, 0, s[34:35]
	v_cndmask_b32_e64 v19, v19, 0, s[42:43]
	v_cndmask_b32_e64 v23, v23, 0, s[66:67]
	v_cmp_eq_u32_e64 s[14:15], v28, v20
	v_cmp_eq_u32_e64 s[34:35], v28, v24
	v_cmp_eq_u32_e64 s[42:43], v29, v21
	v_cmp_eq_u32_e64 s[66:67], v29, v25
	v_cndmask_b32_e64 v20, v20, 0, s[14:15]
	v_cndmask_b32_e64 v24, v24, 0, s[34:35]
	v_cndmask_b32_e64 v21, v21, 0, s[42:43]
	v_cndmask_b32_e64 v25, v25, 0, s[66:67]
	v_max_u32_e32 v26, v18, v22
	v_max_u32_e32 v27, v19, v23
	v_max_u32_e32 v28, v20, v24
	v_max_u32_e32 v29, v21, v25
	v_max_u32_dpp v26, v26, v26 quad_perm:[1,0,3,2] row_mask:0xf bank_mask:0xf
	v_max_u32_dpp v27, v27, v27 quad_perm:[1,0,3,2] row_mask:0xf bank_mask:0xf
	v_max_u32_dpp v28, v28, v28 quad_perm:[1,0,3,2] row_mask:0xf bank_mask:0xf
	v_max_u32_dpp v29, v29, v29 quad_perm:[1,0,3,2] row_mask:0xf bank_mask:0xf
	v_max_u32_dpp v26, v26, v26 quad_perm:[2,3,0,1] row_mask:0xf bank_mask:0xf
	v_max_u32_dpp v27, v27, v27 quad_perm:[2,3,0,1] row_mask:0xf bank_mask:0xf
	v_max_u32_dpp v28, v28, v28 quad_perm:[2,3,0,1] row_mask:0xf bank_mask:0xf
	v_max_u32_dpp v29, v29, v29 quad_perm:[2,3,0,1] row_mask:0xf bank_mask:0xf
	v_max_u32_dpp v26, v26, v26 row_half_mirror row_mask:0xf bank_mask:0xf
	v_max_u32_dpp v27, v27, v27 row_half_mirror row_mask:0xf bank_mask:0xf
	v_max_u32_dpp v28, v28, v28 row_half_mirror row_mask:0xf bank_mask:0xf
	v_max_u32_dpp v29, v29, v29 row_half_mirror row_mask:0xf bank_mask:0xf
	v_max_u32_dpp v26, v26, v26 row_mirror row_mask:0xf bank_mask:0xf
	v_max_u32_dpp v27, v27, v27 row_mirror row_mask:0xf bank_mask:0xf
	v_max_u32_dpp v28, v28, v28 row_mirror row_mask:0xf bank_mask:0xf
	v_max_u32_dpp v29, v29, v29 row_mirror row_mask:0xf bank_mask:0xf
	ds_swizzle_b32 v30, v26 offset:0x401f
	ds_swizzle_b32 v31, v27 offset:0x401f
	ds_swizzle_b32 v32, v28 offset:0x401f
	ds_swizzle_b32 v33, v29 offset:0x401f
	s_waitcnt lgkmcnt(3)
	v_max_u32_e32 v26, v26, v30
	s_waitcnt lgkmcnt(2)
	v_max_u32_e32 v27, v27, v31
	s_waitcnt lgkmcnt(1)
	v_max_u32_e32 v28, v28, v32
	s_waitcnt lgkmcnt(0)
	v_max_u32_e32 v29, v29, v33
	v_mov_b32_e32 v30, v26
	v_mov_b32_e32 v31, v27
	v_mov_b32_e32 v32, v28
	v_mov_b32_e32 v33, v29
	v_permlane32_swap_b32_e32 v26, v30
	v_permlane32_swap_b32_e32 v27, v31
	v_permlane32_swap_b32_e32 v28, v32
	v_permlane32_swap_b32_e32 v29, v33
	v_max_u32_e32 v26, v26, v30
	v_max_u32_e32 v27, v27, v31
	v_max_u32_e32 v28, v28, v32
	v_max_u32_e32 v29, v29, v33
	v_cmp_eq_u32_e64 s[0:1], 7, v184
	v_and_b32_e32 v236, 127, v26
	v_sub_u32_e32 v236, 127, v236
	v_and_b32_e32 v237, 127, v27
	v_sub_u32_e32 v237, 127, v237
	v_and_b32_e32 v238, 127, v28
	v_sub_u32_e32 v238, 127, v238
	v_and_b32_e32 v239, 127, v29
	v_sub_u32_e32 v239, 127, v239
	v_cndmask_b32_e64 v82, v82, v236, s[0:1]
	v_cndmask_b32_e64 v83, v83, v237, s[0:1]
	v_cndmask_b32_e64 v84, v84, v238, s[0:1]
	v_cndmask_b32_e64 v85, v85, v239, s[0:1]
	v_cmp_eq_u32_e64 s[14:15], v26, v18
	v_cmp_eq_u32_e64 s[34:35], v26, v22
	v_cmp_eq_u32_e64 s[42:43], v27, v19
	v_cmp_eq_u32_e64 s[66:67], v27, v23
	v_cndmask_b32_e64 v18, v18, 0, s[14:15]
	v_cndmask_b32_e64 v22, v22, 0, s[34:35]
	v_cndmask_b32_e64 v19, v19, 0, s[42:43]
	v_cndmask_b32_e64 v23, v23, 0, s[66:67]
	v_cmp_eq_u32_e64 s[14:15], v28, v20
	v_cmp_eq_u32_e64 s[34:35], v28, v24
	v_cmp_eq_u32_e64 s[42:43], v29, v21
	v_cmp_eq_u32_e64 s[66:67], v29, v25
	v_cndmask_b32_e64 v20, v20, 0, s[14:15]
	v_cndmask_b32_e64 v24, v24, 0, s[34:35]
	v_cndmask_b32_e64 v21, v21, 0, s[42:43]
	v_cndmask_b32_e64 v25, v25, 0, s[66:67]
	v_max_u32_e32 v26, v18, v22
	v_max_u32_e32 v27, v19, v23
	v_max_u32_e32 v28, v20, v24
	v_max_u32_e32 v29, v21, v25
	v_max_u32_dpp v26, v26, v26 quad_perm:[1,0,3,2] row_mask:0xf bank_mask:0xf
	v_max_u32_dpp v27, v27, v27 quad_perm:[1,0,3,2] row_mask:0xf bank_mask:0xf
	v_max_u32_dpp v28, v28, v28 quad_perm:[1,0,3,2] row_mask:0xf bank_mask:0xf
	v_max_u32_dpp v29, v29, v29 quad_perm:[1,0,3,2] row_mask:0xf bank_mask:0xf
	v_max_u32_dpp v26, v26, v26 quad_perm:[2,3,0,1] row_mask:0xf bank_mask:0xf
	v_max_u32_dpp v27, v27, v27 quad_perm:[2,3,0,1] row_mask:0xf bank_mask:0xf
	v_max_u32_dpp v28, v28, v28 quad_perm:[2,3,0,1] row_mask:0xf bank_mask:0xf
	v_max_u32_dpp v29, v29, v29 quad_perm:[2,3,0,1] row_mask:0xf bank_mask:0xf
	v_max_u32_dpp v26, v26, v26 row_half_mirror row_mask:0xf bank_mask:0xf
	v_max_u32_dpp v27, v27, v27 row_half_mirror row_mask:0xf bank_mask:0xf
	v_max_u32_dpp v28, v28, v28 row_half_mirror row_mask:0xf bank_mask:0xf
	v_max_u32_dpp v29, v29, v29 row_half_mirror row_mask:0xf bank_mask:0xf
	v_max_u32_dpp v26, v26, v26 row_mirror row_mask:0xf bank_mask:0xf
	v_max_u32_dpp v27, v27, v27 row_mirror row_mask:0xf bank_mask:0xf
	v_max_u32_dpp v28, v28, v28 row_mirror row_mask:0xf bank_mask:0xf
	v_max_u32_dpp v29, v29, v29 row_mirror row_mask:0xf bank_mask:0xf
	ds_swizzle_b32 v30, v26 offset:0x401f
	ds_swizzle_b32 v31, v27 offset:0x401f
	ds_swizzle_b32 v32, v28 offset:0x401f
	ds_swizzle_b32 v33, v29 offset:0x401f
	s_waitcnt lgkmcnt(3)
; __device__ __forceinline__ void nsa_quad_pre(int bg, int quad, const bf16_t* Q, const bf16_t* KV, const bf16_t* KCMP, const bf16_t* VCMPT, const float* GN, bf16_t* ONSA, ...
;     ...
;             for (int it = 0; it < 13; ++it) {
;                 unsigned m = k0 > k1 ? k0 : k1;
; #pragma unroll
;                 for (int off = 32; off >= 1; off >>= 1) { const unsigned o = (unsigned)__shfl_xor((int)m, off); m = o > m ? o : m; }
;                 if (k0 == m) k0 = 0u; if (k1 == m) k1 = 0u;
;                 if (lane == 0) selq[tt * 16 + it] = 127 - (int)(m & 127u);
;             }
	v_max_u32_e32 v26, v26, v30
	s_waitcnt lgkmcnt(2)
	v_max_u32_e32 v27, v27, v31
	s_waitcnt lgkmcnt(1)
	v_max_u32_e32 v28, v28, v32
	s_waitcnt lgkmcnt(0)
	v_max_u32_e32 v29, v29, v33
	v_mov_b32_e32 v30, v26
	v_mov_b32_e32 v31, v27
	v_mov_b32_e32 v32, v28
	v_mov_b32_e32 v33, v29
	v_permlane32_swap_b32_e32 v26, v30
	v_permlane32_swap_b32_e32 v27, v31
	v_permlane32_swap_b32_e32 v28, v32
	v_permlane32_swap_b32_e32 v29, v33
	v_max_u32_e32 v26, v26, v30
	v_max_u32_e32 v27, v27, v31
	v_max_u32_e32 v28, v28, v32
	v_max_u32_e32 v29, v29, v33
	v_cmp_eq_u32_e64 s[0:1], 8, v184
	v_and_b32_e32 v236, 127, v26
	v_sub_u32_e32 v236, 127, v236
	v_and_b32_e32 v237, 127, v27
	v_sub_u32_e32 v237, 127, v237
	v_and_b32_e32 v238, 127, v28
	v_sub_u32_e32 v238, 127, v238
	v_and_b32_e32 v239, 127, v29
	v_sub_u32_e32 v239, 127, v239
	v_cndmask_b32_e64 v82, v82, v236, s[0:1]
	v_cndmask_b32_e64 v83, v83, v237, s[0:1]
	v_cndmask_b32_e64 v84, v84, v238, s[0:1]
	v_cndmask_b32_e64 v85, v85, v239, s[0:1]
	v_cmp_eq_u32_e64 s[14:15], v26, v18
	v_cmp_eq_u32_e64 s[34:35], v26, v22
	v_cmp_eq_u32_e64 s[42:43], v27, v19
	v_cmp_eq_u32_e64 s[66:67], v27, v23
	v_cndmask_b32_e64 v18, v18, 0, s[14:15]
	v_cndmask_b32_e64 v22, v22, 0, s[34:35]
	v_cndmask_b32_e64 v19, v19, 0, s[42:43]
	v_cndmask_b32_e64 v23, v23, 0, s[66:67]
	v_cmp_eq_u32_e64 s[14:15], v28, v20
	v_cmp_eq_u32_e64 s[34:35], v28, v24
	v_cmp_eq_u32_e64 s[42:43], v29, v21
	v_cmp_eq_u32_e64 s[66:67], v29, v25
	v_cndmask_b32_e64 v20, v20, 0, s[14:15]
	v_cndmask_b32_e64 v24, v24, 0, s[34:35]
	v_cndmask_b32_e64 v21, v21, 0, s[42:43]
	v_cndmask_b32_e64 v25, v25, 0, s[66:67]
	v_max_u32_e32 v26, v18, v22
	v_max_u32_e32 v27, v19, v23
	v_max_u32_e32 v28, v20, v24
	v_max_u32_e32 v29, v21, v25
	v_max_u32_dpp v26, v26, v26 quad_perm:[1,0,3,2] row_mask:0xf bank_mask:0xf
	v_max_u32_dpp v27, v27, v27 quad_perm:[1,0,3,2] row_mask:0xf bank_mask:0xf
	v_max_u32_dpp v28, v28, v28 quad_perm:[1,0,3,2] row_mask:0xf bank_mask:0xf
	v_max_u32_dpp v29, v29, v29 quad_perm:[1,0,3,2] row_mask:0xf bank_mask:0xf
	v_max_u32_dpp v26, v26, v26 quad_perm:[2,3,0,1] row_mask:0xf bank_mask:0xf
	v_max_u32_dpp v27, v27, v27 quad_perm:[2,3,0,1] row_mask:0xf bank_mask:0xf
	v_max_u32_dpp v28, v28, v28 quad_perm:[2,3,0,1] row_mask:0xf bank_mask:0xf
	v_max_u32_dpp v29, v29, v29 quad_perm:[2,3,0,1] row_mask:0xf bank_mask:0xf
	v_max_u32_dpp v26, v26, v26 row_half_mirror row_mask:0xf bank_mask:0xf
	v_max_u32_dpp v27, v27, v27 row_half_mirror row_mask:0xf bank_mask:0xf
	v_max_u32_dpp v28, v28, v28 row_half_mirror row_mask:0xf bank_mask:0xf
	v_max_u32_dpp v29, v29, v29 row_half_mirror row_mask:0xf bank_mask:0xf
	v_max_u32_dpp v26, v26, v26 row_mirror row_mask:0xf bank_mask:0xf
	v_max_u32_dpp v27, v27, v27 row_mirror row_mask:0xf bank_mask:0xf
	v_max_u32_dpp v28, v28, v28 row_mirror row_mask:0xf bank_mask:0xf
	v_max_u32_dpp v29, v29, v29 row_mirror row_mask:0xf bank_mask:0xf
	ds_swizzle_b32 v30, v26 offset:0x401f
	ds_swizzle_b32 v31, v27 offset:0x401f
	ds_swizzle_b32 v32, v28 offset:0x401f
	ds_swizzle_b32 v33, v29 offset:0x401f
	s_waitcnt lgkmcnt(3)
	v_max_u32_e32 v26, v26, v30
	s_waitcnt lgkmcnt(2)
	v_max_u32_e32 v27, v27, v31
	s_waitcnt lgkmcnt(1)
	v_max_u32_e32 v28, v28, v32
	s_waitcnt lgkmcnt(0)
	v_max_u32_e32 v29, v29, v33
	v_mov_b32_e32 v30, v26
	v_mov_b32_e32 v31, v27
	v_mov_b32_e32 v32, v28
	v_mov_b32_e32 v33, v29
	v_permlane32_swap_b32_e32 v26, v30
	v_permlane32_swap_b32_e32 v27, v31
	v_permlane32_swap_b32_e32 v28, v32
	v_permlane32_swap_b32_e32 v29, v33
	v_max_u32_e32 v26, v26, v30
	v_max_u32_e32 v27, v27, v31
	v_max_u32_e32 v28, v28, v32
	v_max_u32_e32 v29, v29, v33
	v_cmp_eq_u32_e64 s[0:1], 9, v184
	v_and_b32_e32 v236, 127, v26
	v_sub_u32_e32 v236, 127, v236
	v_and_b32_e32 v237, 127, v27
	v_sub_u32_e32 v237, 127, v237
	v_and_b32_e32 v238, 127, v28
	v_sub_u32_e32 v238, 127, v238
	v_and_b32_e32 v239, 127, v29
	v_sub_u32_e32 v239, 127, v239
	v_cndmask_b32_e64 v82, v82, v236, s[0:1]
	v_cndmask_b32_e64 v83, v83, v237, s[0:1]
	v_cndmask_b32_e64 v84, v84, v238, s[0:1]
	v_cndmask_b32_e64 v85, v85, v239, s[0:1]
	v_cmp_eq_u32_e64 s[14:15], v26, v18
	v_cmp_eq_u32_e64 s[34:35], v26, v22
	v_cmp_eq_u32_e64 s[42:43], v27, v19
	v_cmp_eq_u32_e64 s[66:67], v27, v23
	v_cndmask_b32_e64 v18, v18, 0, s[14:15]
	v_cndmask_b32_e64 v22, v22, 0, s[34:35]
	v_cndmask_b32_e64 v19, v19, 0, s[42:43]
	v_cndmask_b32_e64 v23, v23, 0, s[66:67]
	v_cmp_eq_u32_e64 s[14:15], v28, v20
	v_cmp_eq_u32_e64 s[34:35], v28, v24
	v_cmp_eq_u32_e64 s[42:43], v29, v21
	v_cmp_eq_u32_e64 s[66:67], v29, v25
	v_cndmask_b32_e64 v20, v20, 0, s[14:15]
	v_cndmask_b32_e64 v24, v24, 0, s[34:35]
	v_cndmask_b32_e64 v21, v21, 0, s[42:43]
	v_cndmask_b32_e64 v25, v25, 0, s[66:67]
	v_max_u32_e32 v26, v18, v22
	v_max_u32_e32 v27, v19, v23
	v_max_u32_e32 v28, v20, v24
	v_max_u32_e32 v29, v21, v25
	v_max_u32_dpp v26, v26, v26 quad_perm:[1,0,3,2] row_mask:0xf bank_mask:0xf
	v_max_u32_dpp v27, v27, v27 quad_perm:[1,0,3,2] row_mask:0xf bank_mask:0xf
	v_max_u32_dpp v28, v28, v28 quad_perm:[1,0,3,2] row_mask:0xf bank_mask:0xf
	v_max_u32_dpp v29, v29, v29 quad_perm:[1,0,3,2] row_mask:0xf bank_mask:0xf
	v_max_u32_dpp v26, v26, v26 quad_perm:[2,3,0,1] row_mask:0xf bank_mask:0xf
	v_max_u32_dpp v27, v27, v27 quad_perm:[2,3,0,1] row_mask:0xf bank_mask:0xf
	v_max_u32_dpp v28, v28, v28 quad_perm:[2,3,0,1] row_mask:0xf bank_mask:0xf
	v_max_u32_dpp v29, v29, v29 quad_perm:[2,3,0,1] row_mask:0xf bank_mask:0xf
	v_max_u32_dpp v26, v26, v26 row_half_mirror row_mask:0xf bank_mask:0xf
	v_max_u32_dpp v27, v27, v27 row_half_mirror row_mask:0xf bank_mask:0xf
	v_max_u32_dpp v28, v28, v28 row_half_mirror row_mask:0xf bank_mask:0xf
	v_max_u32_dpp v29, v29, v29 row_half_mirror row_mask:0xf bank_mask:0xf
	v_max_u32_dpp v26, v26, v26 row_mirror row_mask:0xf bank_mask:0xf
	v_max_u32_dpp v27, v27, v27 row_mirror row_mask:0xf bank_mask:0xf
	v_max_u32_dpp v28, v28, v28 row_mirror row_mask:0xf bank_mask:0xf
	v_max_u32_dpp v29, v29, v29 row_mirror row_mask:0xf bank_mask:0xf
	ds_swizzle_b32 v30, v26 offset:0x401f
	ds_swizzle_b32 v31, v27 offset:0x401f
	ds_swizzle_b32 v32, v28 offset:0x401f
	ds_swizzle_b32 v33, v29 offset:0x401f
	s_waitcnt lgkmcnt(3)
; __device__ __forceinline__ void nsa_quad_pre(int bg, int quad, const bf16_t* Q, const bf16_t* KV, const bf16_t* KCMP, const bf16_t* VCMPT, const float* GN, bf16_t* ONSA, ...
;     ...
;             for (int it = 0; it < 13; ++it) {
;                 unsigned m = k0 > k1 ? k0 : k1;
; #pragma unroll
;                 for (int off = 32; off >= 1; off >>= 1) { const unsigned o = (unsigned)__shfl_xor((int)m, off); m = o > m ? o : m; }
;                 if (k0 == m) k0 = 0u; if (k1 == m) k1 = 0u;
;                 if (lane == 0) selq[tt * 16 + it] = 127 - (int)(m & 127u);
;             }
	v_max_u32_e32 v26, v26, v30
	s_waitcnt lgkmcnt(2)
	v_max_u32_e32 v27, v27, v31
	s_waitcnt lgkmcnt(1)
	v_max_u32_e32 v28, v28, v32
	s_waitcnt lgkmcnt(0)
	v_max_u32_e32 v29, v29, v33
	v_mov_b32_e32 v30, v26
	v_mov_b32_e32 v31, v27
	v_mov_b32_e32 v32, v28
	v_mov_b32_e32 v33, v29
	v_permlane32_swap_b32_e32 v26, v30
	v_permlane32_swap_b32_e32 v27, v31
	v_permlane32_swap_b32_e32 v28, v32
	v_permlane32_swap_b32_e32 v29, v33
	v_max_u32_e32 v26, v26, v30
	v_max_u32_e32 v27, v27, v31
	v_max_u32_e32 v28, v28, v32
	v_max_u32_e32 v29, v29, v33
	v_cmp_eq_u32_e64 s[0:1], 10, v184
	v_and_b32_e32 v236, 127, v26
	v_sub_u32_e32 v236, 127, v236
	v_and_b32_e32 v237, 127, v27
	v_sub_u32_e32 v237, 127, v237
	v_and_b32_e32 v238, 127, v28
	v_sub_u32_e32 v238, 127, v238
	v_and_b32_e32 v239, 127, v29
	v_sub_u32_e32 v239, 127, v239
	v_cndmask_b32_e64 v82, v82, v236, s[0:1]
	v_cndmask_b32_e64 v83, v83, v237, s[0:1]
	v_cndmask_b32_e64 v84, v84, v238, s[0:1]
	v_cndmask_b32_e64 v85, v85, v239, s[0:1]
	v_cmp_eq_u32_e64 s[14:15], v26, v18
	v_cmp_eq_u32_e64 s[34:35], v26, v22
	v_cmp_eq_u32_e64 s[42:43], v27, v19
	v_cmp_eq_u32_e64 s[66:67], v27, v23
	v_cndmask_b32_e64 v18, v18, 0, s[14:15]
	v_cndmask_b32_e64 v22, v22, 0, s[34:35]
	v_cndmask_b32_e64 v19, v19, 0, s[42:43]
	v_cndmask_b32_e64 v23, v23, 0, s[66:67]
	v_cmp_eq_u32_e64 s[14:15], v28, v20
	v_cmp_eq_u32_e64 s[34:35], v28, v24
	v_cmp_eq_u32_e64 s[42:43], v29, v21
	v_cmp_eq_u32_e64 s[66:67], v29, v25
	v_cndmask_b32_e64 v20, v20, 0, s[14:15]
	v_cndmask_b32_e64 v24, v24, 0, s[34:35]
	v_cndmask_b32_e64 v21, v21, 0, s[42:43]
	v_cndmask_b32_e64 v25, v25, 0, s[66:67]
	v_max_u32_e32 v26, v18, v22
	v_max_u32_e32 v27, v19, v23
	v_max_u32_e32 v28, v20, v24
	v_max_u32_e32 v29, v21, v25
	v_max_u32_dpp v26, v26, v26 quad_perm:[1,0,3,2] row_mask:0xf bank_mask:0xf
	v_max_u32_dpp v27, v27, v27 quad_perm:[1,0,3,2] row_mask:0xf bank_mask:0xf
	v_max_u32_dpp v28, v28, v28 quad_perm:[1,0,3,2] row_mask:0xf bank_mask:0xf
	v_max_u32_dpp v29, v29, v29 quad_perm:[1,0,3,2] row_mask:0xf bank_mask:0xf
	v_max_u32_dpp v26, v26, v26 quad_perm:[2,3,0,1] row_mask:0xf bank_mask:0xf
	v_max_u32_dpp v27, v27, v27 quad_perm:[2,3,0,1] row_mask:0xf bank_mask:0xf
	v_max_u32_dpp v28, v28, v28 quad_perm:[2,3,0,1] row_mask:0xf bank_mask:0xf
	v_max_u32_dpp v29, v29, v29 quad_perm:[2,3,0,1] row_mask:0xf bank_mask:0xf
	v_max_u32_dpp v26, v26, v26 row_half_mirror row_mask:0xf bank_mask:0xf
	v_max_u32_dpp v27, v27, v27 row_half_mirror row_mask:0xf bank_mask:0xf
	v_max_u32_dpp v28, v28, v28 row_half_mirror row_mask:0xf bank_mask:0xf
	v_max_u32_dpp v29, v29, v29 row_half_mirror row_mask:0xf bank_mask:0xf
	v_max_u32_dpp v26, v26, v26 row_mirror row_mask:0xf bank_mask:0xf
	v_max_u32_dpp v27, v27, v27 row_mirror row_mask:0xf bank_mask:0xf
	v_max_u32_dpp v28, v28, v28 row_mirror row_mask:0xf bank_mask:0xf
	v_max_u32_dpp v29, v29, v29 row_mirror row_mask:0xf bank_mask:0xf
	ds_swizzle_b32 v30, v26 offset:0x401f
	ds_swizzle_b32 v31, v27 offset:0x401f
	ds_swizzle_b32 v32, v28 offset:0x401f
	ds_swizzle_b32 v33, v29 offset:0x401f
	s_waitcnt lgkmcnt(3)
	v_max_u32_e32 v26, v26, v30
	s_waitcnt lgkmcnt(2)
	v_max_u32_e32 v27, v27, v31
	s_waitcnt lgkmcnt(1)
	v_max_u32_e32 v28, v28, v32
	s_waitcnt lgkmcnt(0)
; __device__ __forceinline__ void nsa_quad_pre(int bg, int quad, const bf16_t* Q, const bf16_t* KV, const bf16_t* KCMP, const bf16_t* VCMPT, const float* GN, bf16_t* ONSA, ...
;     ...
;             for (int it = 0; it < 13; ++it) {
;                 unsigned m = k0 > k1 ? k0 : k1;
; #pragma unroll
;                 for (int off = 32; off >= 1; off >>= 1) { const unsigned o = (unsigned)__shfl_xor((int)m, off); m = o > m ? o : m; }
;                 if (k0 == m) k0 = 0u; if (k1 == m) k1 = 0u;
;                 if (lane == 0) selq[tt * 16 + it] = 127 - (int)(m & 127u);
;             }
;             if (lane == 0) { selq[tt * 16 + 13] = 0; selq[tt * 16 + 14] = cur - 1; selq[tt * 16 + 15] = cur; }
	v_max_u32_e32 v29, v29, v33
	v_mov_b32_e32 v30, v26
	v_mov_b32_e32 v31, v27
	v_mov_b32_e32 v32, v28
	v_mov_b32_e32 v33, v29
	v_permlane32_swap_b32_e32 v26, v30
	v_permlane32_swap_b32_e32 v27, v31
	v_permlane32_swap_b32_e32 v28, v32
	v_permlane32_swap_b32_e32 v29, v33
	v_max_u32_e32 v26, v26, v30
	v_max_u32_e32 v27, v27, v31
	v_max_u32_e32 v28, v28, v32
	v_max_u32_e32 v29, v29, v33
	v_cmp_eq_u32_e64 s[0:1], 11, v184
	v_and_b32_e32 v236, 127, v26
	v_sub_u32_e32 v236, 127, v236
	v_and_b32_e32 v237, 127, v27
	v_sub_u32_e32 v237, 127, v237
	v_and_b32_e32 v238, 127, v28
	v_sub_u32_e32 v238, 127, v238
	v_and_b32_e32 v239, 127, v29
	v_sub_u32_e32 v239, 127, v239
	v_cndmask_b32_e64 v82, v82, v236, s[0:1]
	v_cndmask_b32_e64 v83, v83, v237, s[0:1]
	v_cndmask_b32_e64 v84, v84, v238, s[0:1]
	v_cndmask_b32_e64 v85, v85, v239, s[0:1]
	v_cmp_eq_u32_e64 s[14:15], v26, v18
	v_cmp_eq_u32_e64 s[34:35], v26, v22
	v_cmp_eq_u32_e64 s[42:43], v27, v19
	v_cmp_eq_u32_e64 s[66:67], v27, v23
	v_cndmask_b32_e64 v18, v18, 0, s[14:15]
	v_cndmask_b32_e64 v22, v22, 0, s[34:35]
	v_cndmask_b32_e64 v19, v19, 0, s[42:43]
	v_cndmask_b32_e64 v23, v23, 0, s[66:67]
	v_cmp_eq_u32_e64 s[14:15], v28, v20
	v_cmp_eq_u32_e64 s[34:35], v28, v24
	v_cmp_eq_u32_e64 s[42:43], v29, v21
	v_cmp_eq_u32_e64 s[66:67], v29, v25
	v_cndmask_b32_e64 v20, v20, 0, s[14:15]
	v_cndmask_b32_e64 v24, v24, 0, s[34:35]
	v_cndmask_b32_e64 v21, v21, 0, s[42:43]
	v_cndmask_b32_e64 v25, v25, 0, s[66:67]
	v_max_u32_e32 v26, v18, v22
	v_max_u32_e32 v27, v19, v23
	v_max_u32_e32 v28, v20, v24
	v_max_u32_e32 v29, v21, v25
	v_max_u32_dpp v26, v26, v26 quad_perm:[1,0,3,2] row_mask:0xf bank_mask:0xf
	v_max_u32_dpp v27, v27, v27 quad_perm:[1,0,3,2] row_mask:0xf bank_mask:0xf
	v_max_u32_dpp v28, v28, v28 quad_perm:[1,0,3,2] row_mask:0xf bank_mask:0xf
	v_max_u32_dpp v29, v29, v29 quad_perm:[1,0,3,2] row_mask:0xf bank_mask:0xf
	v_max_u32_dpp v26, v26, v26 quad_perm:[2,3,0,1] row_mask:0xf bank_mask:0xf
	v_max_u32_dpp v27, v27, v27 quad_perm:[2,3,0,1] row_mask:0xf bank_mask:0xf
	v_max_u32_dpp v28, v28, v28 quad_perm:[2,3,0,1] row_mask:0xf bank_mask:0xf
	v_max_u32_dpp v29, v29, v29 quad_perm:[2,3,0,1] row_mask:0xf bank_mask:0xf
	v_max_u32_dpp v26, v26, v26 row_half_mirror row_mask:0xf bank_mask:0xf
	v_max_u32_dpp v27, v27, v27 row_half_mirror row_mask:0xf bank_mask:0xf
	v_max_u32_dpp v28, v28, v28 row_half_mirror row_mask:0xf bank_mask:0xf
	v_max_u32_dpp v29, v29, v29 row_half_mirror row_mask:0xf bank_mask:0xf
	v_max_u32_dpp v26, v26, v26 row_mirror row_mask:0xf bank_mask:0xf
	v_max_u32_dpp v27, v27, v27 row_mirror row_mask:0xf bank_mask:0xf
	v_max_u32_dpp v28, v28, v28 row_mirror row_mask:0xf bank_mask:0xf
	v_max_u32_dpp v29, v29, v29 row_mirror row_mask:0xf bank_mask:0xf
	ds_swizzle_b32 v30, v26 offset:0x401f
	ds_swizzle_b32 v31, v27 offset:0x401f
	ds_swizzle_b32 v32, v28 offset:0x401f
	ds_swizzle_b32 v33, v29 offset:0x401f
	s_waitcnt lgkmcnt(3)
	v_max_u32_e32 v26, v26, v30
	s_waitcnt lgkmcnt(2)
	v_max_u32_e32 v27, v27, v31
	s_waitcnt lgkmcnt(1)
	v_max_u32_e32 v28, v28, v32
	s_waitcnt lgkmcnt(0)
	v_max_u32_e32 v29, v29, v33
	v_mov_b32_e32 v30, v26
	v_mov_b32_e32 v31, v27
	v_mov_b32_e32 v32, v28
	v_mov_b32_e32 v33, v29
	v_permlane32_swap_b32_e32 v26, v30
	v_permlane32_swap_b32_e32 v27, v31
	v_permlane32_swap_b32_e32 v28, v32
	v_permlane32_swap_b32_e32 v29, v33
	v_max_u32_e32 v26, v26, v30
	v_max_u32_e32 v27, v27, v31
	v_max_u32_e32 v28, v28, v32
	v_max_u32_e32 v29, v29, v33
	v_cmp_eq_u32_e64 s[0:1], 12, v184
	v_and_b32_e32 v236, 127, v26
	v_sub_u32_e32 v236, 127, v236
	v_and_b32_e32 v237, 127, v27
	v_sub_u32_e32 v237, 127, v237
	v_and_b32_e32 v238, 127, v28
	v_sub_u32_e32 v238, 127, v238
	v_and_b32_e32 v239, 127, v29
	v_sub_u32_e32 v239, 127, v239
	v_cndmask_b32_e64 v82, v82, v236, s[0:1]
	v_cndmask_b32_e64 v83, v83, v237, s[0:1]
	v_cndmask_b32_e64 v84, v84, v238, s[0:1]
	v_cndmask_b32_e64 v85, v85, v239, s[0:1]
	s_add_i32 s19, s18, -1
	v_mov_b32_e32 v236, s19
	v_mov_b32_e32 v237, s18
	v_cmp_eq_u32_e64 s[14:15], 14, v184
	v_cmp_eq_u32_e64 s[34:35], 15, v184
	s_nop 0
	v_cndmask_b32_e64 v82, v82, v236, s[14:15]
	v_cndmask_b32_e64 v82, v82, v237, s[34:35]
	v_cndmask_b32_e64 v83, v83, v236, s[14:15]
	v_cndmask_b32_e64 v83, v83, v237, s[34:35]
	v_cndmask_b32_e64 v84, v84, v236, s[14:15]
	v_cndmask_b32_e64 v84, v84, v237, s[34:35]
	v_cndmask_b32_e64 v85, v85, v236, s[14:15]
	v_cndmask_b32_e64 v85, v85, v237, s[34:35]
	s_and_saveexec_b64 s[42:43], s[6:7]
	ds_write_b32 v196, v82 offset:51264
	ds_write_b32 v196, v83 offset:51328
	ds_write_b32 v196, v84 offset:51392
	ds_write_b32 v196, v85 offset:51456
	s_or_b64 exec, exec, s[42:43]
	s_branch .Ltopk_done_q0

; #define LAS __attribute__((address_space(3)))
; __device__ __forceinline__ float ex2(float x) { return __builtin_amdgcn_exp2f(x); }
; __device__ __forceinline__ void cmp_sm1(const f32x4 (&sc)[4], int gr, int t0, const LAS float* bt, float (&ls)[4], int r16) {
; #pragma unroll
;     for (int cc = 0; cc < 4; ++cc) {
;         const int cend = (gr * 64 + cc * 16 + r16) * 16 + 31;
; #pragma unroll
;         for (int i = 0; i < 4; ++i) { const int dist = t0 + i - cend; ls[i] += dist >= 0 ? ex2(sc[cc][i] + bt[clampd(dist)]) : 0.f; }
;     }
; }
; __device__ __forceinline__ void nsa_quad_pre(int bg, int quad, const bf16_t* Q, const bf16_t* KV, const bf16_t* KCMP, const bf16_t* VCMPT, const float* GN, bf16_t* ONSA, ...
;     ...
;     const int tl = t0 + 3, nvmax = tl >= 31 ? ((tl - 31) >> 4) + 1 : 0, ngr = (nvmax + 63) >> 6;
;     if (ngr > 0) {
;         float ls[4] = {0.f, 0.f, 0.f, 0.f};
;         load_k(KF, KP_C(0));
;         for (int gr = 0; gr < ngr; ++gr) {
;             qk_scores(KF, qf, sc);
;             load_k(KF, KP_C(gr + 1 < ngr ? gr + 1 : 0));
;             cmp_sm1(sc, gr, t0, bt, ls, r16);
.Ltopk_done_q0:
	s_nop 0
	s_waitcnt lgkmcnt(0)
	s_lshl_b32 s47, s18, 6
	s_add_i32 s47, s47, s80
	s_add_i32 s47, s47, 4
	v_mov_b32_e32 v2, 0
	v_mov_b32_e32 v3, 0
	v_mov_b32_e32 v4, 0
	v_mov_b32_e32 v5, 0
	v_mov_b32_e32 v6, 0
	v_mov_b32_e32 v7, 0
	v_mov_b32_e32 v8, 0
	v_mov_b32_e32 v9, 0
	v_mov_b32_e32 v10, 0
	v_mov_b32_e32 v11, 0
	v_mov_b32_e32 v12, 0
	v_mov_b32_e32 v13, 0
	v_mov_b32_e32 v14, 0
	v_mov_b32_e32 v15, 0
	v_mov_b32_e32 v16, 0
	v_mov_b32_e32 v17, 0
	s_sub_i32 s0, s47, 28
	s_ashr_i32 s0, s0, 4
	s_add_i32 s0, s0, 64
	s_ashr_i32 s53, s0, 6
	s_cmp_gt_i32 s47, 27
	s_cselect_b32 s53, s53, 0
	s_sub_i32 s0, s47, 2063
	s_ashr_i32 s52, s0, 10
	s_add_i32 s52, s52, 1
	s_max_i32 s52, s52, 0
	s_min_i32 s52, s52, s53
	v_add_u32_e32 v99, s47, v172
	v_and_b32_e32 v98, 15, v184
	v_mov_b32_e32 v170, 0
	s_mov_b32 s57, 0
.Lcmp_top_q1p1:
	s_cmp_ge_i32 s57, s53
	s_cbranch_scc1 .Lcmp_skip_q1p1
	s_lshl_b32 s0, s75, 13
	s_add_i32 s0, s0, 16448
	v_add_u32_e32 v179, s0, v176
	v_add_u32_e32 v226, v179, v178
	ds_read_b128 v[50:53], v179 offset:0
	ds_read_b128 v[54:57], v226 offset:0
	ds_read_b128 v[58:61], v179 offset:512
	ds_read_b128 v[62:65], v226 offset:512
	ds_read_b128 v[66:69], v179 offset:4096
	ds_read_b128 v[70:73], v226 offset:4096
	ds_read_b128 v[74:77], v179 offset:4608
	ds_read_b128 v[78:81], v226 offset:4608
	s_lshl_b32 s0, s92, 13
	s_add_i32 s0, s0, s33
	s_add_i32 m0, s0, 16448
	s_lshl_b32 s1, s93, 13
	s_add_u32 s72, s68, s1
	s_addc_u32 s73, s69, 0
	global_load_lds_dwordx4 v174, s[72:73]
	s_cmp_eq_u32 s92, 1
	s_cselect_b32 s0, s95, s94
	s_cmp_eq_u32 s92, 2
	s_cselect_b32 m0, s46, s0
	s_lshl_b32 s1, s93, 7
	s_add_u32 s72, s70, s1
	s_addc_u32 s73, s71, 0
	global_load_lds_dwordx4 v175, s[72:73]
	s_add_i32 s93, s93, 1
	s_cmp_ge_i32 s93, s74
	s_cselect_b32 s93, 0, s93
	s_add_i32 s92, s92, 1
	s_cmp_eq_u32 s92, 3
	s_cselect_b32 s92, 0, s92
	s_cmp_lt_i32 s57, s52
	s_cbranch_scc0 .Lcmp_gen_q1p1
	v_mov_b32_e32 v228, v225
	v_mov_b32_e32 v229, v225
	v_mov_b32_e32 v230, v225
	v_mov_b32_e32 v231, v225
	s_waitcnt lgkmcnt(7)
	s_nop 0
	v_mfma_f32_16x16x32_bf16 v[18:21], v[50:53], v[42:45], v[228:231]
	s_waitcnt lgkmcnt(6)
	v_mfma_f32_16x16x32_bf16 v[18:21], v[54:57], v[46:49], v[18:21]
	s_waitcnt lgkmcnt(5)
	v_mfma_f32_16x16x32_bf16 v[22:25], v[58:61], v[42:45], v[228:231]
	s_waitcnt lgkmcnt(4)
	v_mfma_f32_16x16x32_bf16 v[22:25], v[62:65], v[46:49], v[22:25]
	s_waitcnt lgkmcnt(3)
	v_mfma_f32_16x16x32_bf16 v[26:29], v[66:69], v[42:45], v[228:231]
	s_waitcnt lgkmcnt(2)
	v_mfma_f32_16x16x32_bf16 v[26:29], v[70:73], v[46:49], v[26:29]
	s_waitcnt lgkmcnt(1)
	v_mfma_f32_16x16x32_bf16 v[30:33], v[74:77], v[42:45], v[228:231]
	s_waitcnt lgkmcnt(0)
	v_mfma_f32_16x16x32_bf16 v[30:33], v[78:81], v[46:49], v[30:33]
	v_exp_f32_e32 v18, v18
	v_exp_f32_e32 v19, v19
	v_exp_f32_e32 v20, v20
	v_exp_f32_e32 v21, v21
	v_exp_f32_e32 v22, v22
	v_exp_f32_e32 v23, v23
	v_exp_f32_e32 v24, v24
	v_exp_f32_e32 v25, v25
	v_exp_f32_e32 v26, v26
	v_exp_f32_e32 v27, v27
	v_exp_f32_e32 v28, v28
	v_exp_f32_e32 v29, v29
	v_exp_f32_e32 v30, v30
	v_exp_f32_e32 v31, v31
	v_exp_f32_e32 v32, v32
	v_exp_f32_e32 v33, v33
	v_add_f32_e32 v18, v18, v19
	v_add_f32_e32 v20, v20, v21
	v_add_f32_e32 v22, v22, v23
	v_add_f32_e32 v24, v24, v25
	v_add_f32_e32 v26, v26, v27
	v_add_f32_e32 v28, v28, v29
	v_add_f32_e32 v30, v30, v31
	v_add_f32_e32 v32, v32, v33
	v_add_f32_e32 v18, v18, v20
	v_add_f32_e32 v22, v22, v24
	v_add_f32_e32 v26, v26, v28
	v_add_f32_e32 v30, v30, v32
	v_add_f32_e32 v18, v18, v22
	v_add_f32_e32 v26, v26, v30
	v_add_f32_e32 v18, v18, v26
	v_add_f32_e32 v170, v170, v18
	s_branch .Lcmp_tail_q1p1
; #define LAS __attribute__((address_space(3)))
; __device__ __forceinline__ float ex2(float x) { return __builtin_amdgcn_exp2f(x); }
; __device__ __forceinline__ void cmp_sm1(const f32x4 (&sc)[4], int gr, int t0, const LAS float* bt, float (&ls)[4], int r16) {
; #pragma unroll
;     for (int cc = 0; cc < 4; ++cc) {
;         const int cend = (gr * 64 + cc * 16 + r16) * 16 + 31;
; #pragma unroll
;         for (int i = 0; i < 4; ++i) { const int dist = t0 + i - cend; ls[i] += dist >= 0 ? ex2(sc[cc][i] + bt[clampd(dist)]) : 0.f; }
;     }
; }
; __device__ __forceinline__ void nsa_quad_pre(int bg, int quad, const bf16_t* Q, const bf16_t* KV, const bf16_t* KCMP, const bf16_t* VCMPT, const float* GN, bf16_t* ONSA, ...
;     ...
;         for (int gr = 0; gr < ngr; ++gr) {
;             qk_scores(KF, qf, sc);
;             load_k(KF, KP_C(gr + 1 < ngr ? gr + 1 : 0));
;             cmp_sm1(sc, gr, t0, bt, ls, r16);
;         }
.Lcmp_gen_q1p1:
	s_nop 1
	s_waitcnt lgkmcnt(7)
	v_mfma_f32_16x16x32_bf16 v[18:21], v[50:53], v[42:45], 0
	s_waitcnt lgkmcnt(6)
	v_mfma_f32_16x16x32_bf16 v[18:21], v[54:57], v[46:49], v[18:21]
	s_waitcnt lgkmcnt(5)
	v_mfma_f32_16x16x32_bf16 v[22:25], v[58:61], v[42:45], 0
	s_waitcnt lgkmcnt(4)
	v_mfma_f32_16x16x32_bf16 v[22:25], v[62:65], v[46:49], v[22:25]
	s_waitcnt lgkmcnt(3)
	v_mfma_f32_16x16x32_bf16 v[26:29], v[66:69], v[42:45], 0
	s_waitcnt lgkmcnt(2)
	v_mfma_f32_16x16x32_bf16 v[26:29], v[70:73], v[46:49], v[26:29]
	s_waitcnt lgkmcnt(1)
	v_mfma_f32_16x16x32_bf16 v[30:33], v[74:77], v[42:45], 0
	s_waitcnt lgkmcnt(0)
	v_mfma_f32_16x16x32_bf16 v[30:33], v[78:81], v[46:49], v[30:33]
	s_lshl_b32 s0, s57, 10
	v_subrev_u32_e32 v224, s0, v99
	v_add_u32_e32 v232, 0x0, v224
	v_min_u32_e32 v232, 0x400, v232
	v_lshl_add_u32 v232, v232, 2, v173
	ds_read_b32 v216, v232
	v_add_u32_e32 v232, 0xfffffff0, v224
	v_min_u32_e32 v232, 0x400, v232
	v_lshl_add_u32 v232, v232, 2, v173
	ds_read_b32 v217, v232
	v_add_u32_e32 v232, 0xffffffe0, v224
	v_min_u32_e32 v232, 0x400, v232
	v_lshl_add_u32 v232, v232, 2, v173
	ds_read_b32 v218, v232
	v_add_u32_e32 v232, 0xffffffd0, v224
	v_min_u32_e32 v232, 0x400, v232
	v_lshl_add_u32 v232, v232, 2, v173
	ds_read_b32 v219, v232
	v_add_u32_e32 v232, 0xffffffc0, v224
	v_min_u32_e32 v232, 0x400, v232
	v_lshl_add_u32 v232, v232, 2, v173
	ds_read_b32 v220, v232
	v_add_u32_e32 v232, 0xffffffb0, v224
	v_min_u32_e32 v232, 0x400, v232
	v_lshl_add_u32 v232, v232, 2, v173
	ds_read_b32 v221, v232
	v_add_u32_e32 v232, 0xffffffa0, v224
	v_min_u32_e32 v232, 0x400, v232
	v_lshl_add_u32 v232, v232, 2, v173
	ds_read_b32 v222, v232
	v_add_u32_e32 v232, 0xffffff90, v224
	v_min_u32_e32 v232, 0x400, v232
	v_lshl_add_u32 v232, v232, 2, v173
	ds_read_b32 v223, v232
	s_waitcnt lgkmcnt(7)
	v_add_u32_e32 v232, 0x0, v224
	v_cmp_le_i32_e32 vcc, 0, v232
	s_nop 1
	v_cndmask_b32_e32 v216, v252, v216, vcc
	v_add_f32_e32 v18, v18, v216
	s_waitcnt lgkmcnt(6)
	v_add_u32_e32 v232, 0xfffffff0, v224
	v_cmp_le_i32_e32 vcc, 0, v232
	s_nop 1
	v_cndmask_b32_e32 v217, v252, v217, vcc
	v_add_f32_e32 v19, v19, v217
	s_waitcnt lgkmcnt(5)
	v_add_u32_e32 v232, 0xffffffe0, v224
	v_cmp_le_i32_e32 vcc, 0, v232
	s_nop 1
	v_cndmask_b32_e32 v218, v252, v218, vcc
	v_add_f32_e32 v20, v20, v218
	s_waitcnt lgkmcnt(4)
	v_add_u32_e32 v232, 0xffffffd0, v224
	v_cmp_le_i32_e32 vcc, 0, v232
	s_nop 1
	v_cndmask_b32_e32 v219, v252, v219, vcc
	v_add_f32_e32 v21, v21, v219
	s_waitcnt lgkmcnt(3)
	v_add_u32_e32 v232, 0xffffffc0, v224
	v_cmp_le_i32_e32 vcc, 0, v232
	s_nop 1
	v_cndmask_b32_e32 v220, v252, v220, vcc
	v_add_f32_e32 v22, v22, v220
	s_waitcnt lgkmcnt(2)
	v_add_u32_e32 v232, 0xffffffb0, v224
	v_cmp_le_i32_e32 vcc, 0, v232
	s_nop 1
	v_cndmask_b32_e32 v221, v252, v221, vcc
	v_add_f32_e32 v23, v23, v221
	s_waitcnt lgkmcnt(1)
	v_add_u32_e32 v232, 0xffffffa0, v224
	v_cmp_le_i32_e32 vcc, 0, v232
	s_nop 1
	v_cndmask_b32_e32 v222, v252, v222, vcc
	v_add_f32_e32 v24, v24, v222
	s_waitcnt lgkmcnt(0)
	v_add_u32_e32 v232, 0xffffff90, v224
	v_cmp_le_i32_e32 vcc, 0, v232
	s_nop 1
	v_cndmask_b32_e32 v223, v252, v223, vcc
	v_add_f32_e32 v25, v25, v223
	v_add_u32_e32 v232, 0xfffffe00, v224
	v_min_u32_e32 v232, 0x400, v232
	v_lshl_add_u32 v232, v232, 2, v173
	ds_read_b32 v216, v232
	v_add_u32_e32 v232, 0xfffffdf0, v224
	v_min_u32_e32 v232, 0x400, v232
	v_lshl_add_u32 v232, v232, 2, v173
	ds_read_b32 v217, v232
	v_add_u32_e32 v232, 0xfffffde0, v224
	v_min_u32_e32 v232, 0x400, v232
	v_lshl_add_u32 v232, v232, 2, v173
	ds_read_b32 v218, v232
	v_add_u32_e32 v232, 0xfffffdd0, v224
	v_min_u32_e32 v232, 0x400, v232
	v_lshl_add_u32 v232, v232, 2, v173
	ds_read_b32 v219, v232
	v_add_u32_e32 v232, 0xfffffdc0, v224
	v_min_u32_e32 v232, 0x400, v232
	v_lshl_add_u32 v232, v232, 2, v173
	ds_read_b32 v220, v232
	v_add_u32_e32 v232, 0xfffffdb0, v224
	v_min_u32_e32 v232, 0x400, v232
	v_lshl_add_u32 v232, v232, 2, v173
	ds_read_b32 v221, v232
	v_add_u32_e32 v232, 0xfffffda0, v224
	v_min_u32_e32 v232, 0x400, v232
	v_lshl_add_u32 v232, v232, 2, v173
	ds_read_b32 v222, v232
	v_add_u32_e32 v232, 0xfffffd90, v224
	v_min_u32_e32 v232, 0x400, v232
	v_lshl_add_u32 v232, v232, 2, v173
	ds_read_b32 v223, v232
	s_waitcnt lgkmcnt(7)
	v_add_u32_e32 v232, 0xfffffe00, v224
	v_cmp_le_i32_e32 vcc, 0, v232
	s_nop 1
	v_cndmask_b32_e32 v216, v252, v216, vcc
	v_add_f32_e32 v26, v26, v216
	s_waitcnt lgkmcnt(6)
	v_add_u32_e32 v232, 0xfffffdf0, v224
	v_cmp_le_i32_e32 vcc, 0, v232
	s_nop 1
	v_cndmask_b32_e32 v217, v252, v217, vcc
	v_add_f32_e32 v27, v27, v217
	s_waitcnt lgkmcnt(5)
	v_add_u32_e32 v232, 0xfffffde0, v224
	v_cmp_le_i32_e32 vcc, 0, v232
	s_nop 1
	v_cndmask_b32_e32 v218, v252, v218, vcc
	v_add_f32_e32 v28, v28, v218
	s_waitcnt lgkmcnt(4)
	v_add_u32_e32 v232, 0xfffffdd0, v224
	v_cmp_le_i32_e32 vcc, 0, v232
	s_nop 1
	v_cndmask_b32_e32 v219, v252, v219, vcc
	v_add_f32_e32 v29, v29, v219
	s_waitcnt lgkmcnt(3)
	v_add_u32_e32 v232, 0xfffffdc0, v224
	v_cmp_le_i32_e32 vcc, 0, v232
	s_nop 1
	v_cndmask_b32_e32 v220, v252, v220, vcc
	v_add_f32_e32 v30, v30, v220
	s_waitcnt lgkmcnt(2)
	v_add_u32_e32 v232, 0xfffffdb0, v224
	v_cmp_le_i32_e32 vcc, 0, v232
	s_nop 1
	v_cndmask_b32_e32 v221, v252, v221, vcc
	v_add_f32_e32 v31, v31, v221
	s_waitcnt lgkmcnt(1)
	v_add_u32_e32 v232, 0xfffffda0, v224
	v_cmp_le_i32_e32 vcc, 0, v232
	s_nop 1
	v_cndmask_b32_e32 v222, v252, v222, vcc
	v_add_f32_e32 v32, v32, v222
	s_waitcnt lgkmcnt(0)
	v_add_u32_e32 v232, 0xfffffd90, v224
	v_cmp_le_i32_e32 vcc, 0, v232
	s_nop 1
	v_cndmask_b32_e32 v223, v252, v223, vcc
	v_add_f32_e32 v33, v33, v223
	v_exp_f32_e32 v18, v18
	v_exp_f32_e32 v19, v19
	v_exp_f32_e32 v20, v20
	v_exp_f32_e32 v21, v21
	v_exp_f32_e32 v22, v22
	v_exp_f32_e32 v23, v23
	v_exp_f32_e32 v24, v24
	v_exp_f32_e32 v25, v25
	v_exp_f32_e32 v26, v26
	v_exp_f32_e32 v27, v27
	v_exp_f32_e32 v28, v28
	v_exp_f32_e32 v29, v29
	v_exp_f32_e32 v30, v30
	v_exp_f32_e32 v31, v31
	v_exp_f32_e32 v32, v32
	v_exp_f32_e32 v33, v33
	v_add_f32_e32 v18, v18, v19
	v_add_f32_e32 v20, v20, v21
	v_add_f32_e32 v22, v22, v23
	v_add_f32_e32 v24, v24, v25
	v_add_f32_e32 v26, v26, v27
	v_add_f32_e32 v28, v28, v29
	v_add_f32_e32 v30, v30, v31
	v_add_f32_e32 v32, v32, v33
	v_add_f32_e32 v18, v18, v20
	v_add_f32_e32 v22, v22, v24
	v_add_f32_e32 v26, v26, v28
	v_add_f32_e32 v30, v30, v32
	v_add_f32_e32 v18, v18, v22
	v_add_f32_e32 v26, v26, v30
	v_add_f32_e32 v18, v18, v26
	v_add_f32_e32 v170, v170, v18
	s_branch .Lcmp_tail_q1p1

; #define LAS __attribute__((address_space(3)))
; __device__ __forceinline__ bf16_t tobf(float x) { return (bf16_t)pk2(x, 0.f); }
; __device__ __forceinline__ float ex2(float x) { return __builtin_amdgcn_exp2f(x); }
; __device__ __forceinline__ void cmp_sm2(const f32x4 (&sc)[4], int gr, int t0, const LAS float* bt, const float (&inv)[4], LAS bf16_t* Pb, LAS float* psum, int r16, int q4) {
; #pragma unroll
;     for (int cc = 0; cc < 4; ++cc) {
;         const int kk = gr * 64 + cc * 16 + r16, cend = kk * 16 + 31;
; #pragma unroll
;         for (int i = 0; i < 4; ++i) { const int dist = t0 + i - cend; float p = dist >= 0 ? ex2(sc[cc][i] + bt[clampd(dist)]) * inv[i] : 0.f;
;             Pb[(4 * q4 + i) * 72 + cc * 16 + r16] = tobf(p); p += __shfl_xor(p, 16); p += __shfl_xor(p, 32); if (q4 == 0) psum[i * 512 + kk] = p; }
;     }
; }
; __device__ __forceinline__ void nsa_quad_pre(int bg, int quad, const bf16_t* Q, const bf16_t* KV, const bf16_t* KCMP, const bf16_t* VCMPT, const float* GN, bf16_t* ONSA, ...
;     ...
;         for (int gr = 0; gr < ngr; ++gr) {
;             const bool more = gr + 1 < ngr;
;             qk_scores(KF, qf, sc);
;             if (more) load_k(KF, KP_C(gr + 1));
;             cmp_sm2(sc, gr, t0, bt, inv, Pb, psum, r16, q4);
;             pv_step(VF, oc, Pb, r16, q4);
;             if (more) load_v(VF, VP_C(gr + 1));
.Lcmp_top_q1p2:
	s_cmp_ge_i32 s57, s53
	s_cbranch_scc1 .Lcmp_skip_q1p2
	s_lshl_b32 s0, s75, 13
	s_add_i32 s0, s0, 16448
	v_add_u32_e32 v179, s0, v176
	v_add_u32_e32 v226, v179, v178
	ds_read_b128 v[50:53], v179 offset:0
	ds_read_b128 v[54:57], v226 offset:0
	ds_read_b128 v[58:61], v179 offset:512
	ds_read_b128 v[62:65], v226 offset:512
	ds_read_b128 v[66:69], v179 offset:4096
	ds_read_b128 v[70:73], v226 offset:4096
	ds_read_b128 v[74:77], v179 offset:4608
	ds_read_b128 v[78:81], v226 offset:4608
	s_lshl_b32 s0, s92, 13
	s_add_i32 s0, s0, s33
	s_add_i32 m0, s0, 16448
	s_lshl_b32 s1, s93, 13
	s_add_u32 s72, s68, s1
	s_addc_u32 s73, s69, 0
	global_load_lds_dwordx4 v174, s[72:73]
	s_cmp_eq_u32 s92, 1
	s_cselect_b32 s0, s95, s94
	s_cmp_eq_u32 s92, 2
	s_cselect_b32 m0, s46, s0
	s_lshl_b32 s1, s93, 7
	s_add_u32 s72, s70, s1
	s_addc_u32 s73, s71, 0
	global_load_lds_dwordx4 v175, s[72:73]
	s_add_i32 s93, s93, 1
	s_cmp_ge_i32 s93, s74
	s_cselect_b32 s93, 0, s93
	s_add_i32 s92, s92, 1
	s_cmp_eq_u32 s92, 3
	s_cselect_b32 s92, 0, s92
	s_cmp_lt_i32 s57, s52
	s_cbranch_scc0 .Lcmp_gen_q1p2
	v_mov_b32_e32 v228, v225
	v_mov_b32_e32 v229, v225
	v_mov_b32_e32 v230, v225
	v_mov_b32_e32 v231, v225
	s_waitcnt lgkmcnt(7)
	s_nop 0
	v_mfma_f32_16x16x32_bf16 v[18:21], v[50:53], v[42:45], v[228:231]
	s_waitcnt lgkmcnt(6)
	v_mfma_f32_16x16x32_bf16 v[18:21], v[54:57], v[46:49], v[18:21]
	s_waitcnt lgkmcnt(5)
	v_mfma_f32_16x16x32_bf16 v[22:25], v[58:61], v[42:45], v[228:231]
	s_waitcnt lgkmcnt(4)
	v_mfma_f32_16x16x32_bf16 v[22:25], v[62:65], v[46:49], v[22:25]
	s_waitcnt lgkmcnt(3)
	v_mfma_f32_16x16x32_bf16 v[26:29], v[66:69], v[42:45], v[228:231]
	s_waitcnt lgkmcnt(2)
	v_mfma_f32_16x16x32_bf16 v[26:29], v[70:73], v[46:49], v[26:29]
	s_waitcnt lgkmcnt(1)
	v_mfma_f32_16x16x32_bf16 v[30:33], v[74:77], v[42:45], v[228:231]
	s_waitcnt lgkmcnt(0)
	v_mfma_f32_16x16x32_bf16 v[30:33], v[78:81], v[46:49], v[30:33]
	s_cmp_eq_u32 s75, 1
	s_cselect_b32 s0, s95, s94
	s_cmp_eq_u32 s75, 2
	s_cselect_b32 s0, s46, s0
	v_add_u32_e32 v179, s0, v177
	v_add_u32_e32 v226, v179, v178
	ds_read_b128 v[82:85], v179 offset:0
	ds_read_b128 v[86:89], v226 offset:0
	ds_read_b128 v[90:93], v179 offset:2048
	ds_read_b128 v[94:97], v226 offset:2048
	ds_read_b128 v[236:239], v179 offset:4096
	ds_read_b128 v[240:243], v226 offset:4096
	ds_read_b128 v[244:247], v179 offset:6144
	ds_read_b128 v[248:251], v226 offset:6144
	v_exp_f32_e32 v18, v18
	v_exp_f32_e32 v19, v19
	v_exp_f32_e32 v20, v20
	v_exp_f32_e32 v21, v21
	v_exp_f32_e32 v22, v22
	v_exp_f32_e32 v23, v23
	v_exp_f32_e32 v24, v24
	v_exp_f32_e32 v25, v25
	v_exp_f32_e32 v26, v26
	v_exp_f32_e32 v27, v27
	v_exp_f32_e32 v28, v28
	v_exp_f32_e32 v29, v29
	v_exp_f32_e32 v30, v30
	v_exp_f32_e32 v31, v31
	v_exp_f32_e32 v32, v32
	v_exp_f32_e32 v33, v33
	v_mul_f32_e32 v18, v18, v171
	v_mul_f32_e32 v19, v19, v171
	v_mul_f32_e32 v20, v20, v171
	v_mul_f32_e32 v21, v21, v171
	v_mul_f32_e32 v22, v22, v171
	v_mul_f32_e32 v23, v23, v171
	v_mul_f32_e32 v24, v24, v171
	v_mul_f32_e32 v25, v25, v171
	v_mul_f32_e32 v26, v26, v171
	v_mul_f32_e32 v27, v27, v171
	v_mul_f32_e32 v28, v28, v171
	v_mul_f32_e32 v29, v29, v171
	v_mul_f32_e32 v30, v30, v171
	v_mul_f32_e32 v31, v31, v171
	v_mul_f32_e32 v32, v32, v171
	v_mul_f32_e32 v33, v33, v171
	v_add_f32_dpp v50, v18, v18 row_shr:4 row_mask:0xf bank_mask:0xf
	v_add_f32_dpp v51, v19, v19 row_shr:4 row_mask:0xf bank_mask:0xf
	v_add_f32_dpp v52, v20, v20 row_shr:4 row_mask:0xf bank_mask:0xf
	v_add_f32_dpp v53, v21, v21 row_shr:4 row_mask:0xf bank_mask:0xf
	v_add_f32_dpp v54, v22, v22 row_shr:4 row_mask:0xf bank_mask:0xf
	v_add_f32_dpp v55, v23, v23 row_shr:4 row_mask:0xf bank_mask:0xf
	v_add_f32_dpp v56, v24, v24 row_shr:4 row_mask:0xf bank_mask:0xf
	v_add_f32_dpp v57, v25, v25 row_shr:4 row_mask:0xf bank_mask:0xf
	v_add_f32_dpp v58, v26, v26 row_shr:4 row_mask:0xf bank_mask:0xf
	v_add_f32_dpp v59, v27, v27 row_shr:4 row_mask:0xf bank_mask:0xf
	v_add_f32_dpp v60, v28, v28 row_shr:4 row_mask:0xf bank_mask:0xf
	v_add_f32_dpp v61, v29, v29 row_shr:4 row_mask:0xf bank_mask:0xf
	v_add_f32_dpp v62, v30, v30 row_shr:4 row_mask:0xf bank_mask:0xf
	v_add_f32_dpp v63, v31, v31 row_shr:4 row_mask:0xf bank_mask:0xf
	v_add_f32_dpp v64, v32, v32 row_shr:4 row_mask:0xf bank_mask:0xf
	v_add_f32_dpp v65, v33, v33 row_shr:4 row_mask:0xf bank_mask:0xf
	v_add_f32_dpp v50, v50, v50 row_shr:8 row_mask:0xf bank_mask:0xf
	v_add_f32_dpp v51, v51, v51 row_shr:8 row_mask:0xf bank_mask:0xf
	v_add_f32_dpp v52, v52, v52 row_shr:8 row_mask:0xf bank_mask:0xf
	v_add_f32_dpp v53, v53, v53 row_shr:8 row_mask:0xf bank_mask:0xf
	v_add_f32_dpp v54, v54, v54 row_shr:8 row_mask:0xf bank_mask:0xf
	v_add_f32_dpp v55, v55, v55 row_shr:8 row_mask:0xf bank_mask:0xf
	v_add_f32_dpp v56, v56, v56 row_shr:8 row_mask:0xf bank_mask:0xf
	v_add_f32_dpp v57, v57, v57 row_shr:8 row_mask:0xf bank_mask:0xf
	v_add_f32_dpp v58, v58, v58 row_shr:8 row_mask:0xf bank_mask:0xf
	v_add_f32_dpp v59, v59, v59 row_shr:8 row_mask:0xf bank_mask:0xf
	v_add_f32_dpp v60, v60, v60 row_shr:8 row_mask:0xf bank_mask:0xf
	v_add_f32_dpp v61, v61, v61 row_shr:8 row_mask:0xf bank_mask:0xf
	v_add_f32_dpp v62, v62, v62 row_shr:8 row_mask:0xf bank_mask:0xf
	v_add_f32_dpp v63, v63, v63 row_shr:8 row_mask:0xf bank_mask:0xf
	v_add_f32_dpp v64, v64, v64 row_shr:8 row_mask:0xf bank_mask:0xf
	v_add_f32_dpp v65, v65, v65 row_shr:8 row_mask:0xf bank_mask:0xf
	s_lshl_b32 s0, s57, 8
	v_add_u32_e32 v232, s0, v215
	v_cmp_lt_u32_e32 vcc, 11, v98
	s_nop 0
	s_and_saveexec_b64 s[20:21], vcc
	ds_write_b128 v232, v[50:53] offset:0
	ds_write_b128 v232, v[54:57] offset:16
	ds_write_b128 v232, v[58:61] offset:128
	ds_write_b128 v232, v[62:65] offset:144
	s_or_b64 exec, exec, s[20:21]
	v_cvt_pk_bf16_f32 v216, v18, v19
	v_cvt_pk_bf16_f32 v217, v20, v21
	v_cvt_pk_bf16_f32 v218, v22, v23
	v_cvt_pk_bf16_f32 v219, v24, v25
	v_cvt_pk_bf16_f32 v220, v26, v27
	v_cvt_pk_bf16_f32 v221, v28, v29
	v_cvt_pk_bf16_f32 v222, v30, v31
	v_cvt_pk_bf16_f32 v223, v32, v33
	s_waitcnt lgkmcnt(11)
	v_mfma_f32_16x16x32_bf16 v[2:5], v[82:85], v[216:219], v[2:5]
	s_waitcnt lgkmcnt(10)
	v_mfma_f32_16x16x32_bf16 v[2:5], v[86:89], v[220:223], v[2:5]
	s_waitcnt lgkmcnt(9)
	v_mfma_f32_16x16x32_bf16 v[6:9], v[90:93], v[216:219], v[6:9]
	s_waitcnt lgkmcnt(8)
	v_mfma_f32_16x16x32_bf16 v[6:9], v[94:97], v[220:223], v[6:9]
	s_waitcnt lgkmcnt(7)
	v_mfma_f32_16x16x32_bf16 v[10:13], v[236:239], v[216:219], v[10:13]
	s_waitcnt lgkmcnt(6)
	v_mfma_f32_16x16x32_bf16 v[10:13], v[240:243], v[220:223], v[10:13]
	s_waitcnt lgkmcnt(5)
	v_mfma_f32_16x16x32_bf16 v[14:17], v[244:247], v[216:219], v[14:17]
	s_waitcnt lgkmcnt(4)
	v_mfma_f32_16x16x32_bf16 v[14:17], v[248:251], v[220:223], v[14:17]
	s_branch .Lcmp_tail_q1p2
; #define LAS __attribute__((address_space(3)))
; __device__ __forceinline__ bf16_t tobf(float x) { return (bf16_t)pk2(x, 0.f); }
; __device__ __forceinline__ float ex2(float x) { return __builtin_amdgcn_exp2f(x); }
; __device__ __forceinline__ void cmp_sm2(const f32x4 (&sc)[4], int gr, int t0, const LAS float* bt, const float (&inv)[4], LAS bf16_t* Pb, LAS float* psum, int r16, int q4) {
; #pragma unroll
;     for (int cc = 0; cc < 4; ++cc) {
;         const int kk = gr * 64 + cc * 16 + r16, cend = kk * 16 + 31;
; #pragma unroll
;         for (int i = 0; i < 4; ++i) { const int dist = t0 + i - cend; float p = dist >= 0 ? ex2(sc[cc][i] + bt[clampd(dist)]) * inv[i] : 0.f;
;             Pb[(4 * q4 + i) * 72 + cc * 16 + r16] = tobf(p); p += __shfl_xor(p, 16); p += __shfl_xor(p, 32); if (q4 == 0) psum[i * 512 + kk] = p; }
;     }
; }
; __device__ __forceinline__ void nsa_quad_pre(int bg, int quad, const bf16_t* Q, const bf16_t* KV, const bf16_t* KCMP, const bf16_t* VCMPT, const float* GN, bf16_t* ONSA, ...
;     ...
;         for (int gr = 0; gr < ngr; ++gr) {
;             const bool more = gr + 1 < ngr;
;             qk_scores(KF, qf, sc);
;             if (more) load_k(KF, KP_C(gr + 1));
;             cmp_sm2(sc, gr, t0, bt, inv, Pb, psum, r16, q4);
.Lcmp_gen_q1p2:
	s_nop 1
	s_waitcnt lgkmcnt(7)
	v_mfma_f32_16x16x32_bf16 v[18:21], v[50:53], v[42:45], 0
	s_waitcnt lgkmcnt(6)
	v_mfma_f32_16x16x32_bf16 v[18:21], v[54:57], v[46:49], v[18:21]
	s_waitcnt lgkmcnt(5)
	v_mfma_f32_16x16x32_bf16 v[22:25], v[58:61], v[42:45], 0
	s_waitcnt lgkmcnt(4)
	v_mfma_f32_16x16x32_bf16 v[22:25], v[62:65], v[46:49], v[22:25]
	s_waitcnt lgkmcnt(3)
	v_mfma_f32_16x16x32_bf16 v[26:29], v[66:69], v[42:45], 0
	s_waitcnt lgkmcnt(2)
	v_mfma_f32_16x16x32_bf16 v[26:29], v[70:73], v[46:49], v[26:29]
	s_waitcnt lgkmcnt(1)
	v_mfma_f32_16x16x32_bf16 v[30:33], v[74:77], v[42:45], 0
	s_waitcnt lgkmcnt(0)
	v_mfma_f32_16x16x32_bf16 v[30:33], v[78:81], v[46:49], v[30:33]
	s_lshl_b32 s0, s57, 10
	v_subrev_u32_e32 v224, s0, v99
	v_add_u32_e32 v232, 0x0, v224
	v_min_u32_e32 v232, 0x400, v232
	v_lshl_add_u32 v232, v232, 2, v173
	ds_read_b32 v216, v232
	v_add_u32_e32 v232, 0xfffffff0, v224
	v_min_u32_e32 v232, 0x400, v232
	v_lshl_add_u32 v232, v232, 2, v173
	ds_read_b32 v217, v232
	v_add_u32_e32 v232, 0xffffffe0, v224
	v_min_u32_e32 v232, 0x400, v232
	v_lshl_add_u32 v232, v232, 2, v173
	ds_read_b32 v218, v232
	v_add_u32_e32 v232, 0xffffffd0, v224
	v_min_u32_e32 v232, 0x400, v232
	v_lshl_add_u32 v232, v232, 2, v173
	ds_read_b32 v219, v232
	v_add_u32_e32 v232, 0xffffffc0, v224
	v_min_u32_e32 v232, 0x400, v232
	v_lshl_add_u32 v232, v232, 2, v173
	ds_read_b32 v220, v232
	v_add_u32_e32 v232, 0xffffffb0, v224
	v_min_u32_e32 v232, 0x400, v232
	v_lshl_add_u32 v232, v232, 2, v173
	ds_read_b32 v221, v232
	v_add_u32_e32 v232, 0xffffffa0, v224
	v_min_u32_e32 v232, 0x400, v232
	v_lshl_add_u32 v232, v232, 2, v173
	ds_read_b32 v222, v232
	v_add_u32_e32 v232, 0xffffff90, v224
	v_min_u32_e32 v232, 0x400, v232
	v_lshl_add_u32 v232, v232, 2, v173
	ds_read_b32 v223, v232
	s_waitcnt lgkmcnt(7)
	v_add_u32_e32 v232, 0x0, v224
	v_cmp_le_i32_e32 vcc, 0, v232
	s_nop 1
	v_cndmask_b32_e32 v216, v252, v216, vcc
	v_add_f32_e32 v18, v18, v216
	s_waitcnt lgkmcnt(6)
	v_add_u32_e32 v232, 0xfffffff0, v224
	v_cmp_le_i32_e32 vcc, 0, v232
	s_nop 1
	v_cndmask_b32_e32 v217, v252, v217, vcc
	v_add_f32_e32 v19, v19, v217
	s_waitcnt lgkmcnt(5)
	v_add_u32_e32 v232, 0xffffffe0, v224
	v_cmp_le_i32_e32 vcc, 0, v232
	s_nop 1
	v_cndmask_b32_e32 v218, v252, v218, vcc
	v_add_f32_e32 v20, v20, v218
	s_waitcnt lgkmcnt(4)
	v_add_u32_e32 v232, 0xffffffd0, v224
	v_cmp_le_i32_e32 vcc, 0, v232
	s_nop 1
	v_cndmask_b32_e32 v219, v252, v219, vcc
	v_add_f32_e32 v21, v21, v219
	s_waitcnt lgkmcnt(3)
	v_add_u32_e32 v232, 0xffffffc0, v224
	v_cmp_le_i32_e32 vcc, 0, v232
	s_nop 1
	v_cndmask_b32_e32 v220, v252, v220, vcc
	v_add_f32_e32 v22, v22, v220
	s_waitcnt lgkmcnt(2)
	v_add_u32_e32 v232, 0xffffffb0, v224
	v_cmp_le_i32_e32 vcc, 0, v232
	s_nop 1
	v_cndmask_b32_e32 v221, v252, v221, vcc
	v_add_f32_e32 v23, v23, v221
	s_waitcnt lgkmcnt(1)
	v_add_u32_e32 v232, 0xffffffa0, v224
	v_cmp_le_i32_e32 vcc, 0, v232
	s_nop 1
	v_cndmask_b32_e32 v222, v252, v222, vcc
	v_add_f32_e32 v24, v24, v222
	s_waitcnt lgkmcnt(0)
	v_add_u32_e32 v232, 0xffffff90, v224
	v_cmp_le_i32_e32 vcc, 0, v232
	s_nop 1
	v_cndmask_b32_e32 v223, v252, v223, vcc
	v_add_f32_e32 v25, v25, v223
	v_add_u32_e32 v232, 0xfffffe00, v224
	v_min_u32_e32 v232, 0x400, v232
	v_lshl_add_u32 v232, v232, 2, v173
	ds_read_b32 v216, v232
	v_add_u32_e32 v232, 0xfffffdf0, v224
	v_min_u32_e32 v232, 0x400, v232
	v_lshl_add_u32 v232, v232, 2, v173
	ds_read_b32 v217, v232
	v_add_u32_e32 v232, 0xfffffde0, v224
	v_min_u32_e32 v232, 0x400, v232
	v_lshl_add_u32 v232, v232, 2, v173
	ds_read_b32 v218, v232
	v_add_u32_e32 v232, 0xfffffdd0, v224
	v_min_u32_e32 v232, 0x400, v232
	v_lshl_add_u32 v232, v232, 2, v173
	ds_read_b32 v219, v232
	v_add_u32_e32 v232, 0xfffffdc0, v224
	v_min_u32_e32 v232, 0x400, v232
	v_lshl_add_u32 v232, v232, 2, v173
	ds_read_b32 v220, v232
	v_add_u32_e32 v232, 0xfffffdb0, v224
	v_min_u32_e32 v232, 0x400, v232
	v_lshl_add_u32 v232, v232, 2, v173
	ds_read_b32 v221, v232
	v_add_u32_e32 v232, 0xfffffda0, v224
	v_min_u32_e32 v232, 0x400, v232
	v_lshl_add_u32 v232, v232, 2, v173
	ds_read_b32 v222, v232
	v_add_u32_e32 v232, 0xfffffd90, v224
	v_min_u32_e32 v232, 0x400, v232
	v_lshl_add_u32 v232, v232, 2, v173
	ds_read_b32 v223, v232
	s_waitcnt lgkmcnt(7)
	v_add_u32_e32 v232, 0xfffffe00, v224
	v_cmp_le_i32_e32 vcc, 0, v232
	s_nop 1
	v_cndmask_b32_e32 v216, v252, v216, vcc
	v_add_f32_e32 v26, v26, v216
	s_waitcnt lgkmcnt(6)
	v_add_u32_e32 v232, 0xfffffdf0, v224
	v_cmp_le_i32_e32 vcc, 0, v232
	s_nop 1
	v_cndmask_b32_e32 v217, v252, v217, vcc
	v_add_f32_e32 v27, v27, v217
	s_waitcnt lgkmcnt(5)
	v_add_u32_e32 v232, 0xfffffde0, v224
	v_cmp_le_i32_e32 vcc, 0, v232
	s_nop 1
	v_cndmask_b32_e32 v218, v252, v218, vcc
	v_add_f32_e32 v28, v28, v218
	s_waitcnt lgkmcnt(4)
	v_add_u32_e32 v232, 0xfffffdd0, v224
	v_cmp_le_i32_e32 vcc, 0, v232
	s_nop 1
	v_cndmask_b32_e32 v219, v252, v219, vcc
	v_add_f32_e32 v29, v29, v219
	s_waitcnt lgkmcnt(3)
	v_add_u32_e32 v232, 0xfffffdc0, v224
	v_cmp_le_i32_e32 vcc, 0, v232
	s_nop 1
	v_cndmask_b32_e32 v220, v252, v220, vcc
	v_add_f32_e32 v30, v30, v220
	s_waitcnt lgkmcnt(2)
	v_add_u32_e32 v232, 0xfffffdb0, v224
	v_cmp_le_i32_e32 vcc, 0, v232
	s_nop 1
	v_cndmask_b32_e32 v221, v252, v221, vcc
	v_add_f32_e32 v31, v31, v221
	s_waitcnt lgkmcnt(1)
; #define LAS __attribute__((address_space(3)))
; #define CBAR() asm volatile("" ::: "memory")
; #define MFMA16(a, b, c) __builtin_amdgcn_mfma_f32_16x16x32_bf16(a, b, c, 0, 0, 0)
; __device__ __forceinline__ bf16_t tobf(float x) { return (bf16_t)pk2(x, 0.f); }
; __device__ __forceinline__ float ex2(float x) { return __builtin_amdgcn_exp2f(x); }
; __device__ __forceinline__ void pv_step(const VFrag& f, f32x4 (&o)[4], const LAS bf16_t* Pb, int r16, int q4) {
;     CBAR();
; #pragma unroll
;     for (int ks = 0; ks < 2; ++ks) { const bf16x8 aP = *(const LAS bf16x8*)(Pb + r16 * 72 + ks * 32 + q4 * 8);
; #pragma unroll
;         for (int nt = 0; nt < 4; ++nt) o[nt] = MFMA16(aP, f.v[ks][nt], o[nt]); }
;     CBAR();
; }
; __device__ __forceinline__ void cmp_sm2(const f32x4 (&sc)[4], int gr, int t0, const LAS float* bt, const float (&inv)[4], LAS bf16_t* Pb, LAS float* psum, int r16, int q4) {
; #pragma unroll
;     for (int cc = 0; cc < 4; ++cc) {
;         const int kk = gr * 64 + cc * 16 + r16, cend = kk * 16 + 31;
; #pragma unroll
;         for (int i = 0; i < 4; ++i) { const int dist = t0 + i - cend; float p = dist >= 0 ? ex2(sc[cc][i] + bt[clampd(dist)]) * inv[i] : 0.f;
;             Pb[(4 * q4 + i) * 72 + cc * 16 + r16] = tobf(p); p += __shfl_xor(p, 16); p += __shfl_xor(p, 32); if (q4 == 0) psum[i * 512 + kk] = p; }
;     }
; }
	v_add_u32_e32 v232, 0xfffffda0, v224
	v_cmp_le_i32_e32 vcc, 0, v232
	s_nop 1
	v_cndmask_b32_e32 v222, v252, v222, vcc
	v_add_f32_e32 v32, v32, v222
	s_waitcnt lgkmcnt(0)
	v_add_u32_e32 v232, 0xfffffd90, v224
	v_cmp_le_i32_e32 vcc, 0, v232
	s_nop 1
	v_cndmask_b32_e32 v223, v252, v223, vcc
	v_add_f32_e32 v33, v33, v223
	s_cmp_eq_u32 s75, 1
	s_cselect_b32 s0, s95, s94
	s_cmp_eq_u32 s75, 2
	s_cselect_b32 s0, s46, s0
	v_add_u32_e32 v179, s0, v177
	v_add_u32_e32 v226, v179, v178
	ds_read_b128 v[82:85], v179 offset:0
	ds_read_b128 v[86:89], v226 offset:0
	ds_read_b128 v[90:93], v179 offset:2048
	ds_read_b128 v[94:97], v226 offset:2048
	ds_read_b128 v[236:239], v179 offset:4096
	ds_read_b128 v[240:243], v226 offset:4096
	ds_read_b128 v[244:247], v179 offset:6144
	ds_read_b128 v[248:251], v226 offset:6144
	v_exp_f32_e32 v18, v18
	v_exp_f32_e32 v19, v19
	v_exp_f32_e32 v20, v20
	v_exp_f32_e32 v21, v21
	v_exp_f32_e32 v22, v22
	v_exp_f32_e32 v23, v23
	v_exp_f32_e32 v24, v24
	v_exp_f32_e32 v25, v25
	v_exp_f32_e32 v26, v26
	v_exp_f32_e32 v27, v27
	v_exp_f32_e32 v28, v28
	v_exp_f32_e32 v29, v29
	v_exp_f32_e32 v30, v30
	v_exp_f32_e32 v31, v31
	v_exp_f32_e32 v32, v32
	v_exp_f32_e32 v33, v33
	v_mul_f32_e32 v18, v18, v171
	v_mul_f32_e32 v19, v19, v171
	v_mul_f32_e32 v20, v20, v171
	v_mul_f32_e32 v21, v21, v171
	v_mul_f32_e32 v22, v22, v171
	v_mul_f32_e32 v23, v23, v171
	v_mul_f32_e32 v24, v24, v171
	v_mul_f32_e32 v25, v25, v171
	v_mul_f32_e32 v26, v26, v171
	v_mul_f32_e32 v27, v27, v171
	v_mul_f32_e32 v28, v28, v171
	v_mul_f32_e32 v29, v29, v171
	v_mul_f32_e32 v30, v30, v171
	v_mul_f32_e32 v31, v31, v171
	v_mul_f32_e32 v32, v32, v171
	v_mul_f32_e32 v33, v33, v171
	v_add_f32_dpp v50, v18, v18 row_shr:4 row_mask:0xf bank_mask:0xf
	v_add_f32_dpp v51, v19, v19 row_shr:4 row_mask:0xf bank_mask:0xf
	v_add_f32_dpp v52, v20, v20 row_shr:4 row_mask:0xf bank_mask:0xf
	v_add_f32_dpp v53, v21, v21 row_shr:4 row_mask:0xf bank_mask:0xf
	v_add_f32_dpp v54, v22, v22 row_shr:4 row_mask:0xf bank_mask:0xf
	v_add_f32_dpp v55, v23, v23 row_shr:4 row_mask:0xf bank_mask:0xf
	v_add_f32_dpp v56, v24, v24 row_shr:4 row_mask:0xf bank_mask:0xf
	v_add_f32_dpp v57, v25, v25 row_shr:4 row_mask:0xf bank_mask:0xf
	v_add_f32_dpp v58, v26, v26 row_shr:4 row_mask:0xf bank_mask:0xf
	v_add_f32_dpp v59, v27, v27 row_shr:4 row_mask:0xf bank_mask:0xf
	v_add_f32_dpp v60, v28, v28 row_shr:4 row_mask:0xf bank_mask:0xf
	v_add_f32_dpp v61, v29, v29 row_shr:4 row_mask:0xf bank_mask:0xf
	v_add_f32_dpp v62, v30, v30 row_shr:4 row_mask:0xf bank_mask:0xf
	v_add_f32_dpp v63, v31, v31 row_shr:4 row_mask:0xf bank_mask:0xf
	v_add_f32_dpp v64, v32, v32 row_shr:4 row_mask:0xf bank_mask:0xf
	v_add_f32_dpp v65, v33, v33 row_shr:4 row_mask:0xf bank_mask:0xf
	v_add_f32_dpp v50, v50, v50 row_shr:8 row_mask:0xf bank_mask:0xf
	v_add_f32_dpp v51, v51, v51 row_shr:8 row_mask:0xf bank_mask:0xf
	v_add_f32_dpp v52, v52, v52 row_shr:8 row_mask:0xf bank_mask:0xf
	v_add_f32_dpp v53, v53, v53 row_shr:8 row_mask:0xf bank_mask:0xf
	v_add_f32_dpp v54, v54, v54 row_shr:8 row_mask:0xf bank_mask:0xf
	v_add_f32_dpp v55, v55, v55 row_shr:8 row_mask:0xf bank_mask:0xf
	v_add_f32_dpp v56, v56, v56 row_shr:8 row_mask:0xf bank_mask:0xf
	v_add_f32_dpp v57, v57, v57 row_shr:8 row_mask:0xf bank_mask:0xf
	v_add_f32_dpp v58, v58, v58 row_shr:8 row_mask:0xf bank_mask:0xf
	v_add_f32_dpp v59, v59, v59 row_shr:8 row_mask:0xf bank_mask:0xf
	v_add_f32_dpp v60, v60, v60 row_shr:8 row_mask:0xf bank_mask:0xf
	v_add_f32_dpp v61, v61, v61 row_shr:8 row_mask:0xf bank_mask:0xf
	v_add_f32_dpp v62, v62, v62 row_shr:8 row_mask:0xf bank_mask:0xf
	v_add_f32_dpp v63, v63, v63 row_shr:8 row_mask:0xf bank_mask:0xf
	v_add_f32_dpp v64, v64, v64 row_shr:8 row_mask:0xf bank_mask:0xf
	v_add_f32_dpp v65, v65, v65 row_shr:8 row_mask:0xf bank_mask:0xf
	s_lshl_b32 s0, s57, 8
	v_add_u32_e32 v232, s0, v215
	v_cmp_lt_u32_e32 vcc, 11, v98
	s_nop 0
	s_and_saveexec_b64 s[20:21], vcc
	ds_write_b128 v232, v[50:53] offset:0
	ds_write_b128 v232, v[54:57] offset:16
	ds_write_b128 v232, v[58:61] offset:128
	ds_write_b128 v232, v[62:65] offset:144
	s_or_b64 exec, exec, s[20:21]
	v_cvt_pk_bf16_f32 v216, v18, v19
	v_cvt_pk_bf16_f32 v217, v20, v21
	v_cvt_pk_bf16_f32 v218, v22, v23
	v_cvt_pk_bf16_f32 v219, v24, v25
	v_cvt_pk_bf16_f32 v220, v26, v27
	v_cvt_pk_bf16_f32 v221, v28, v29
	v_cvt_pk_bf16_f32 v222, v30, v31
	v_cvt_pk_bf16_f32 v223, v32, v33
	s_waitcnt lgkmcnt(11)
	v_mfma_f32_16x16x32_bf16 v[2:5], v[82:85], v[216:219], v[2:5]
	s_waitcnt lgkmcnt(10)
	v_mfma_f32_16x16x32_bf16 v[2:5], v[86:89], v[220:223], v[2:5]
	s_waitcnt lgkmcnt(9)
	v_mfma_f32_16x16x32_bf16 v[6:9], v[90:93], v[216:219], v[6:9]
	s_waitcnt lgkmcnt(8)
	v_mfma_f32_16x16x32_bf16 v[6:9], v[94:97], v[220:223], v[6:9]
	s_waitcnt lgkmcnt(7)
	v_mfma_f32_16x16x32_bf16 v[10:13], v[236:239], v[216:219], v[10:13]
	s_waitcnt lgkmcnt(6)
	v_mfma_f32_16x16x32_bf16 v[10:13], v[240:243], v[220:223], v[10:13]
	s_waitcnt lgkmcnt(5)
	v_mfma_f32_16x16x32_bf16 v[14:17], v[244:247], v[216:219], v[14:17]
	s_waitcnt lgkmcnt(4)
	v_mfma_f32_16x16x32_bf16 v[14:17], v[248:251], v[220:223], v[14:17]
	s_branch .Lcmp_tail_q1p2

; #define LAS __attribute__((address_space(3)))
; #define CBAR() asm volatile("" ::: "memory")
; __device__ __forceinline__ bf16_t tobf(float x) { return (bf16_t)pk2(x, 0.f); }
; __device__ __forceinline__ void nsa_quad_pre(int bg, int quad, const bf16_t* Q, const bf16_t* KV, const bf16_t* KCMP, const bf16_t* VCMPT, const float* GN, bf16_t* ONSA, ...
;     ...
;         for (int gr = 0; gr < ngr; ++gr) {
;             const bool more = gr + 1 < ngr;
;             qk_scores(KF, qf, sc);
;             if (more) load_k(KF, KP_C(gr + 1));
;             cmp_sm2(sc, gr, t0, bt, inv, Pb, psum, r16, q4);
;             pv_step(VF, oc, Pb, r16, q4);
;             if (more) load_v(VF, VP_C(gr + 1));
;         }
;     }
;     CBAR();
; #pragma unroll
;     for (int tt = 0; tt < 4; ++tt) {
;         const int tok = t0 + tt, cur = tok >> 6;
;         if (cur < 16) { if (lane < 16) selq[tt * 16 + lane] = lane; }
;         else {
;             unsigned k0 = 0u, k1 = 0u;
;             { const int j = lane; if (j >= 1 && j <= cur - 2) { const LAS float* ps = psum + tt * 512 + 4 * j - 1; const float v = ps[0] + ps[1] + ps[2] + ps[3] + ps[4]; k0 = (__builtin_bit_cast(unsigned, v) & ~127u) | (unsigned)(127 - j); } }
;             { const int j = lane + 64; if (j <= cur - 2) { const LAS float* ps = psum + tt * 512 + 4 * j - 1; const float v = ps[0] + ps[1] + ps[2] + ps[3] + ps[4]; k1 = (__builtin_bit_cast(unsigned, v) & ~127u) | (unsigned)(127 - j); } }
;             for (int it = 0; it < 13; ++it) {
;                 unsigned m = k0 > k1 ? k0 : k1;
; #pragma unroll
;                 for (int off = 32; off >= 1; off >>= 1) { const unsigned o = (unsigned)__shfl_xor((int)m, off); m = o > m ? o : m; }
;                 if (k0 == m) k0 = 0u; if (k1 == m) k1 = 0u;
;                 if (lane == 0) selq[tt * 16 + it] = 127 - (int)(m & 127u);
;             }
;             if (lane == 0) { selq[tt * 16 + 13] = 0; selq[tt * 16 + 14] = cur - 1; selq[tt * 16 + 15] = cur; }
;         }
;     }
;     CBAR();
; #pragma unroll
;     for (int tt = 0; tt < 4; ++tt) { const float gc = GN[(size_t)(b * SEQ + t0 + tt) * 48 + (g * 4 + q4) * 3];
;         bf16_t* op = ONSA + (size_t)(b * SEQ + t0 + tt) * 1024 + (g * 4 + q4) * 64 + r16;
; #pragma unroll
;         for (int nt = 0; nt < 4; ++nt) op[nt * 16] = tobf(gc * oc[nt][tt]); }
.Lcmp_tail_q1p2:
	s_waitcnt vmcnt(2) lgkmcnt(0)
	s_barrier
	s_add_i32 s75, s75, 1
	s_cmp_eq_u32 s75, 3
	s_cselect_b32 s75, 0, s75
	s_add_i32 s57, s57, 1
	s_cmp_lt_i32 s57, s74
	s_cbranch_scc1 .Lcmp_top_q1p2
	s_waitcnt lgkmcnt(0)
	s_nop 7
	s_nop 3
	v_and_b32_e32 v232, 15, v184
	v_lshrrev_b32_e32 v233, 4, v184
	v_and_b32_e32 v234, 3, v232
	v_lshrrev_b32_e32 v235, 2, v232
	s_add_i32 s0, s47, s97
	v_add_u32_e32 v253, s0, v234
	s_and_b32 s1, s88, 3
	s_lshl_b32 s1, s1, 2
	v_add_u32_e32 v0, s1, v235
	v_lshlrev_b32_e32 v98, 7, v0
	v_lshl_add_u32 v98, v253, 11, v98
	v_lshl_add_u32 v98, v233, 3, v98
	v_mul_u32_u24_e32 v99, 0xc0, v253
	v_mul_u32_u24_e32 v0, 12, v0
	v_add_u32_e32 v99, v99, v0
	s_add_u32 s72, s30, 0x38310000
	s_addc_u32 s73, s31, 0
	s_add_u32 s14, s30, 0xf900000
	s_addc_u32 s15, s31, 0
	global_load_dword v232, v99, s[72:73]
	s_waitcnt vmcnt(0)
	v_mul_f32_e32 v2, v2, v232
	v_mul_f32_e32 v3, v3, v232
	v_mul_f32_e32 v4, v4, v232
	v_mul_f32_e32 v5, v5, v232
	v_mul_f32_e32 v6, v6, v232
	v_mul_f32_e32 v7, v7, v232
	v_mul_f32_e32 v8, v8, v232
	v_mul_f32_e32 v9, v9, v232
	v_mul_f32_e32 v10, v10, v232
	v_mul_f32_e32 v11, v11, v232
	v_mul_f32_e32 v12, v12, v232
	v_mul_f32_e32 v13, v13, v232
	v_mul_f32_e32 v14, v14, v232
	v_mul_f32_e32 v15, v15, v232
	v_mul_f32_e32 v16, v16, v232
	v_mul_f32_e32 v17, v17, v232
	v_cvt_pk_bf16_f32 v216, v2, v3
	v_cvt_pk_bf16_f32 v217, v4, v5
	v_cvt_pk_bf16_f32 v218, v6, v7
	v_cvt_pk_bf16_f32 v219, v8, v9
	v_cvt_pk_bf16_f32 v220, v10, v11
	v_cvt_pk_bf16_f32 v221, v12, v13
	v_cvt_pk_bf16_f32 v222, v14, v15
	v_cvt_pk_bf16_f32 v223, v16, v17
	global_store_dwordx2 v98, v[216:217], s[14:15] offset:0
	global_store_dwordx2 v98, v[218:219], s[14:15] offset:32
	global_store_dwordx2 v98, v[220:221], s[14:15] offset:64
	global_store_dwordx2 v98, v[222:223], s[14:15] offset:96
	s_waitcnt lgkmcnt(0)
	s_cmp_gt_i32 s18, 15
	s_cbranch_scc0 .Ltopk_small_q1
	s_lshl_b32 s19, s80, 10
	s_add_i32 s19, s19, 56384
	v_lshlrev_b32_e32 v96, 4, v184
	v_add_u32_e32 v96, s19, v96
	v_add_u32_e32 v97, 0xfffffffc, v96
	v_sub_u32_e32 v94, 127, v184
	v_sub_u32_e32 v95, 63, v184
	s_mov_b32 s54, 0xffffff80
	s_add_i32 s21, s18, -2
	v_add_u32_e32 v236, 64, v184
	ds_read_b32 v86, v97 offset:0
	ds_read_b128 v[50:53], v96 offset:0
	ds_read_b32 v87, v97 offset:1024
	ds_read_b128 v[54:57], v96 offset:1024
	ds_read_b32 v88, v97 offset:2048
	ds_read_b128 v[58:61], v96 offset:2048
	ds_read_b32 v89, v97 offset:3072
	ds_read_b128 v[62:65], v96 offset:3072
	s_waitcnt lgkmcnt(6)
	v_add_f32_e32 v86, v86, v50
	v_add_f32_e32 v86, v86, v51
	v_add_f32_e32 v86, v86, v52
	v_add_f32_e32 v86, v86, v53
	v_and_or_b32 v18, v86, s54, v94
	s_waitcnt lgkmcnt(4)
	v_add_f32_e32 v87, v87, v54
	v_add_f32_e32 v87, v87, v55
	v_add_f32_e32 v87, v87, v56
	v_add_f32_e32 v87, v87, v57
	v_and_or_b32 v22, v87, s54, v95
	s_waitcnt lgkmcnt(2)
	v_add_f32_e32 v88, v88, v58
	v_add_f32_e32 v88, v88, v59
	v_add_f32_e32 v88, v88, v60
	v_add_f32_e32 v88, v88, v61
	v_and_or_b32 v19, v88, s54, v94
	s_waitcnt lgkmcnt(0)
	v_add_f32_e32 v89, v89, v62
	v_add_f32_e32 v89, v89, v63
	v_add_f32_e32 v89, v89, v64
	v_add_f32_e32 v89, v89, v65
	v_and_or_b32 v23, v89, s54, v95
	ds_read_b32 v90, v97 offset:4096
	ds_read_b128 v[66:69], v96 offset:4096
	ds_read_b32 v91, v97 offset:5120
	ds_read_b128 v[70:73], v96 offset:5120
	ds_read_b32 v92, v97 offset:6144
	ds_read_b128 v[74:77], v96 offset:6144
	ds_read_b32 v93, v97 offset:7168
	ds_read_b128 v[78:81], v96 offset:7168
	s_waitcnt lgkmcnt(6)
	v_add_f32_e32 v90, v90, v66
	v_add_f32_e32 v90, v90, v67
	v_add_f32_e32 v90, v90, v68
	v_add_f32_e32 v90, v90, v69
	v_and_or_b32 v20, v90, s54, v94
	s_waitcnt lgkmcnt(4)
	v_add_f32_e32 v91, v91, v70
	v_add_f32_e32 v91, v91, v71
	v_add_f32_e32 v91, v91, v72
	v_add_f32_e32 v91, v91, v73
	v_and_or_b32 v24, v91, s54, v95
	s_waitcnt lgkmcnt(2)
	v_add_f32_e32 v92, v92, v74
	v_add_f32_e32 v92, v92, v75
	v_add_f32_e32 v92, v92, v76
	v_add_f32_e32 v92, v92, v77
	v_and_or_b32 v21, v92, s54, v94
	s_waitcnt lgkmcnt(0)
	v_add_f32_e32 v93, v93, v78
	v_add_f32_e32 v93, v93, v79
	v_add_f32_e32 v93, v93, v80
	v_add_f32_e32 v93, v93, v81
	v_and_or_b32 v25, v93, s54, v95
	v_cmp_le_i32_e64 s[14:15], v184, s21
	v_cmp_lt_i32_e64 s[34:35], 0, v184
	s_nop 0
	s_and_b64 s[14:15], s[14:15], s[34:35]
	v_cmp_le_i32_e64 s[34:35], v236, s21
	v_cndmask_b32_e64 v18, 0, v18, s[14:15]
	s_nop 0
	v_cndmask_b32_e64 v22, 0, v22, s[34:35]
	v_mov_b32_e32 v82, 0
	v_cndmask_b32_e64 v19, 0, v19, s[14:15]
	v_cndmask_b32_e64 v23, 0, v23, s[34:35]
	v_mov_b32_e32 v83, 0
	v_cndmask_b32_e64 v20, 0, v20, s[14:15]
	v_cndmask_b32_e64 v24, 0, v24, s[34:35]
	v_mov_b32_e32 v84, 0
	v_cndmask_b32_e64 v21, 0, v21, s[14:15]
	v_cndmask_b32_e64 v25, 0, v25, s[34:35]
	v_mov_b32_e32 v85, 0
	v_max_u32_e32 v26, v18, v22
	v_max_u32_e32 v27, v19, v23
	v_max_u32_e32 v28, v20, v24
	v_max_u32_e32 v29, v21, v25
	v_max_u32_dpp v26, v26, v26 quad_perm:[1,0,3,2] row_mask:0xf bank_mask:0xf
	v_max_u32_dpp v27, v27, v27 quad_perm:[1,0,3,2] row_mask:0xf bank_mask:0xf
	v_max_u32_dpp v28, v28, v28 quad_perm:[1,0,3,2] row_mask:0xf bank_mask:0xf
	v_max_u32_dpp v29, v29, v29 quad_perm:[1,0,3,2] row_mask:0xf bank_mask:0xf
	v_max_u32_dpp v26, v26, v26 quad_perm:[2,3,0,1] row_mask:0xf bank_mask:0xf
	v_max_u32_dpp v27, v27, v27 quad_perm:[2,3,0,1] row_mask:0xf bank_mask:0xf
	v_max_u32_dpp v28, v28, v28 quad_perm:[2,3,0,1] row_mask:0xf bank_mask:0xf
	v_max_u32_dpp v29, v29, v29 quad_perm:[2,3,0,1] row_mask:0xf bank_mask:0xf
	v_max_u32_dpp v26, v26, v26 row_half_mirror row_mask:0xf bank_mask:0xf
	v_max_u32_dpp v27, v27, v27 row_half_mirror row_mask:0xf bank_mask:0xf
	v_max_u32_dpp v28, v28, v28 row_half_mirror row_mask:0xf bank_mask:0xf
	v_max_u32_dpp v29, v29, v29 row_half_mirror row_mask:0xf bank_mask:0xf
	v_max_u32_dpp v26, v26, v26 row_mirror row_mask:0xf bank_mask:0xf
	v_max_u32_dpp v27, v27, v27 row_mirror row_mask:0xf bank_mask:0xf
	v_max_u32_dpp v28, v28, v28 row_mirror row_mask:0xf bank_mask:0xf
	v_max_u32_dpp v29, v29, v29 row_mirror row_mask:0xf bank_mask:0xf
	ds_swizzle_b32 v30, v26 offset:0x401f
	ds_swizzle_b32 v31, v27 offset:0x401f
	ds_swizzle_b32 v32, v28 offset:0x401f
	ds_swizzle_b32 v33, v29 offset:0x401f
	s_waitcnt lgkmcnt(3)
; __device__ __forceinline__ void nsa_quad_pre(int bg, int quad, const bf16_t* Q, const bf16_t* KV, const bf16_t* KCMP, const bf16_t* VCMPT, const float* GN, bf16_t* ONSA, ...
;     ...
;             for (int it = 0; it < 13; ++it) {
;                 unsigned m = k0 > k1 ? k0 : k1;
; #pragma unroll
;                 for (int off = 32; off >= 1; off >>= 1) { const unsigned o = (unsigned)__shfl_xor((int)m, off); m = o > m ? o : m; }
;                 if (k0 == m) k0 = 0u; if (k1 == m) k1 = 0u;
;                 if (lane == 0) selq[tt * 16 + it] = 127 - (int)(m & 127u);
;             }
;             if (lane == 0) { selq[tt * 16 + 13] = 0; selq[tt * 16 + 14] = cur - 1; selq[tt * 16 + 15] = cur; }
	v_max_u32_e32 v26, v26, v30
	s_waitcnt lgkmcnt(2)
	v_max_u32_e32 v27, v27, v31
	s_waitcnt lgkmcnt(1)
	v_max_u32_e32 v28, v28, v32
	s_waitcnt lgkmcnt(0)
	v_max_u32_e32 v29, v29, v33
	v_mov_b32_e32 v30, v26
	v_mov_b32_e32 v31, v27
	v_mov_b32_e32 v32, v28
	v_mov_b32_e32 v33, v29
	v_permlane32_swap_b32_e32 v26, v30
	v_permlane32_swap_b32_e32 v27, v31
	v_permlane32_swap_b32_e32 v28, v32
	v_permlane32_swap_b32_e32 v29, v33
	v_max_u32_e32 v26, v26, v30
	v_max_u32_e32 v27, v27, v31
	v_max_u32_e32 v28, v28, v32
	v_max_u32_e32 v29, v29, v33
	v_cmp_eq_u32_e64 s[0:1], 0, v184
	v_and_b32_e32 v236, 127, v26
	v_sub_u32_e32 v236, 127, v236
	v_and_b32_e32 v237, 127, v27
	v_sub_u32_e32 v237, 127, v237
	v_and_b32_e32 v238, 127, v28
	v_sub_u32_e32 v238, 127, v238
	v_and_b32_e32 v239, 127, v29
	v_sub_u32_e32 v239, 127, v239
	v_cndmask_b32_e64 v82, v82, v236, s[0:1]
	v_cndmask_b32_e64 v83, v83, v237, s[0:1]
	v_cndmask_b32_e64 v84, v84, v238, s[0:1]
	v_cndmask_b32_e64 v85, v85, v239, s[0:1]
	v_cmp_eq_u32_e64 s[14:15], v26, v18
	v_cmp_eq_u32_e64 s[34:35], v26, v22
	v_cmp_eq_u32_e64 s[42:43], v27, v19
	v_cmp_eq_u32_e64 s[66:67], v27, v23
	v_cndmask_b32_e64 v18, v18, 0, s[14:15]
	v_cndmask_b32_e64 v22, v22, 0, s[34:35]
	v_cndmask_b32_e64 v19, v19, 0, s[42:43]
	v_cndmask_b32_e64 v23, v23, 0, s[66:67]
	v_cmp_eq_u32_e64 s[14:15], v28, v20
	v_cmp_eq_u32_e64 s[34:35], v28, v24
	v_cmp_eq_u32_e64 s[42:43], v29, v21
	v_cmp_eq_u32_e64 s[66:67], v29, v25
	v_cndmask_b32_e64 v20, v20, 0, s[14:15]
	v_cndmask_b32_e64 v24, v24, 0, s[34:35]
	v_cndmask_b32_e64 v21, v21, 0, s[42:43]
	v_cndmask_b32_e64 v25, v25, 0, s[66:67]
	v_max_u32_e32 v26, v18, v22
	v_max_u32_e32 v27, v19, v23
	v_max_u32_e32 v28, v20, v24
	v_max_u32_e32 v29, v21, v25
	v_max_u32_dpp v26, v26, v26 quad_perm:[1,0,3,2] row_mask:0xf bank_mask:0xf
	v_max_u32_dpp v27, v27, v27 quad_perm:[1,0,3,2] row_mask:0xf bank_mask:0xf
	v_max_u32_dpp v28, v28, v28 quad_perm:[1,0,3,2] row_mask:0xf bank_mask:0xf
	v_max_u32_dpp v29, v29, v29 quad_perm:[1,0,3,2] row_mask:0xf bank_mask:0xf
	v_max_u32_dpp v26, v26, v26 quad_perm:[2,3,0,1] row_mask:0xf bank_mask:0xf
	v_max_u32_dpp v27, v27, v27 quad_perm:[2,3,0,1] row_mask:0xf bank_mask:0xf
	v_max_u32_dpp v28, v28, v28 quad_perm:[2,3,0,1] row_mask:0xf bank_mask:0xf
	v_max_u32_dpp v29, v29, v29 quad_perm:[2,3,0,1] row_mask:0xf bank_mask:0xf
	v_max_u32_dpp v26, v26, v26 row_half_mirror row_mask:0xf bank_mask:0xf
	v_max_u32_dpp v27, v27, v27 row_half_mirror row_mask:0xf bank_mask:0xf
	v_max_u32_dpp v28, v28, v28 row_half_mirror row_mask:0xf bank_mask:0xf
	v_max_u32_dpp v29, v29, v29 row_half_mirror row_mask:0xf bank_mask:0xf
	v_max_u32_dpp v26, v26, v26 row_mirror row_mask:0xf bank_mask:0xf
	v_max_u32_dpp v27, v27, v27 row_mirror row_mask:0xf bank_mask:0xf
	v_max_u32_dpp v28, v28, v28 row_mirror row_mask:0xf bank_mask:0xf
	v_max_u32_dpp v29, v29, v29 row_mirror row_mask:0xf bank_mask:0xf
	ds_swizzle_b32 v30, v26 offset:0x401f
	ds_swizzle_b32 v31, v27 offset:0x401f
	ds_swizzle_b32 v32, v28 offset:0x401f
	ds_swizzle_b32 v33, v29 offset:0x401f
	s_waitcnt lgkmcnt(3)
	v_max_u32_e32 v26, v26, v30
	s_waitcnt lgkmcnt(2)
	v_max_u32_e32 v27, v27, v31
	s_waitcnt lgkmcnt(1)
	v_max_u32_e32 v28, v28, v32
	s_waitcnt lgkmcnt(0)
	v_max_u32_e32 v29, v29, v33
	v_mov_b32_e32 v30, v26
	v_mov_b32_e32 v31, v27
	v_mov_b32_e32 v32, v28
	v_mov_b32_e32 v33, v29
	v_permlane32_swap_b32_e32 v26, v30
	v_permlane32_swap_b32_e32 v27, v31
	v_permlane32_swap_b32_e32 v28, v32
	v_permlane32_swap_b32_e32 v29, v33
	v_max_u32_e32 v26, v26, v30
	v_max_u32_e32 v27, v27, v31
	v_max_u32_e32 v28, v28, v32
	v_max_u32_e32 v29, v29, v33
	v_cmp_eq_u32_e64 s[0:1], 1, v184
	v_and_b32_e32 v236, 127, v26
	v_sub_u32_e32 v236, 127, v236
	v_and_b32_e32 v237, 127, v27
	v_sub_u32_e32 v237, 127, v237
	v_and_b32_e32 v238, 127, v28
	v_sub_u32_e32 v238, 127, v238
	v_and_b32_e32 v239, 127, v29
	v_sub_u32_e32 v239, 127, v239
	v_cndmask_b32_e64 v82, v82, v236, s[0:1]
	v_cndmask_b32_e64 v83, v83, v237, s[0:1]
	v_cndmask_b32_e64 v84, v84, v238, s[0:1]
	v_cndmask_b32_e64 v85, v85, v239, s[0:1]
	v_cmp_eq_u32_e64 s[14:15], v26, v18
	v_cmp_eq_u32_e64 s[34:35], v26, v22
	v_cmp_eq_u32_e64 s[42:43], v27, v19
	v_cmp_eq_u32_e64 s[66:67], v27, v23
	v_cndmask_b32_e64 v18, v18, 0, s[14:15]
	v_cndmask_b32_e64 v22, v22, 0, s[34:35]
	v_cndmask_b32_e64 v19, v19, 0, s[42:43]
	v_cndmask_b32_e64 v23, v23, 0, s[66:67]
	v_cmp_eq_u32_e64 s[14:15], v28, v20
	v_cmp_eq_u32_e64 s[34:35], v28, v24
	v_cmp_eq_u32_e64 s[42:43], v29, v21
	v_cmp_eq_u32_e64 s[66:67], v29, v25
	v_cndmask_b32_e64 v20, v20, 0, s[14:15]
	v_cndmask_b32_e64 v24, v24, 0, s[34:35]
	v_cndmask_b32_e64 v21, v21, 0, s[42:43]
	v_cndmask_b32_e64 v25, v25, 0, s[66:67]
	v_max_u32_e32 v26, v18, v22
	v_max_u32_e32 v27, v19, v23
	v_max_u32_e32 v28, v20, v24
	v_max_u32_e32 v29, v21, v25
	v_max_u32_dpp v26, v26, v26 quad_perm:[1,0,3,2] row_mask:0xf bank_mask:0xf
	v_max_u32_dpp v27, v27, v27 quad_perm:[1,0,3,2] row_mask:0xf bank_mask:0xf
	v_max_u32_dpp v28, v28, v28 quad_perm:[1,0,3,2] row_mask:0xf bank_mask:0xf
	v_max_u32_dpp v29, v29, v29 quad_perm:[1,0,3,2] row_mask:0xf bank_mask:0xf
	v_max_u32_dpp v26, v26, v26 quad_perm:[2,3,0,1] row_mask:0xf bank_mask:0xf
	v_max_u32_dpp v27, v27, v27 quad_perm:[2,3,0,1] row_mask:0xf bank_mask:0xf
	v_max_u32_dpp v28, v28, v28 quad_perm:[2,3,0,1] row_mask:0xf bank_mask:0xf
	v_max_u32_dpp v29, v29, v29 quad_perm:[2,3,0,1] row_mask:0xf bank_mask:0xf
	v_max_u32_dpp v26, v26, v26 row_half_mirror row_mask:0xf bank_mask:0xf
	v_max_u32_dpp v27, v27, v27 row_half_mirror row_mask:0xf bank_mask:0xf
	v_max_u32_dpp v28, v28, v28 row_half_mirror row_mask:0xf bank_mask:0xf
	v_max_u32_dpp v29, v29, v29 row_half_mirror row_mask:0xf bank_mask:0xf
	v_max_u32_dpp v26, v26, v26 row_mirror row_mask:0xf bank_mask:0xf
	v_max_u32_dpp v27, v27, v27 row_mirror row_mask:0xf bank_mask:0xf
	v_max_u32_dpp v28, v28, v28 row_mirror row_mask:0xf bank_mask:0xf
	v_max_u32_dpp v29, v29, v29 row_mirror row_mask:0xf bank_mask:0xf
	ds_swizzle_b32 v30, v26 offset:0x401f
	ds_swizzle_b32 v31, v27 offset:0x401f
	ds_swizzle_b32 v32, v28 offset:0x401f
	ds_swizzle_b32 v33, v29 offset:0x401f
	s_waitcnt lgkmcnt(3)
; __device__ __forceinline__ void nsa_quad_pre(int bg, int quad, const bf16_t* Q, const bf16_t* KV, const bf16_t* KCMP, const bf16_t* VCMPT, const float* GN, bf16_t* ONSA, ...
;     ...
;             for (int it = 0; it < 13; ++it) {
;                 unsigned m = k0 > k1 ? k0 : k1;
; #pragma unroll
;                 for (int off = 32; off >= 1; off >>= 1) { const unsigned o = (unsigned)__shfl_xor((int)m, off); m = o > m ? o : m; }
;                 if (k0 == m) k0 = 0u; if (k1 == m) k1 = 0u;
;                 if (lane == 0) selq[tt * 16 + it] = 127 - (int)(m & 127u);
;             }
;             if (lane == 0) { selq[tt * 16 + 13] = 0; selq[tt * 16 + 14] = cur - 1; selq[tt * 16 + 15] = cur; }
	v_max_u32_e32 v26, v26, v30
	s_waitcnt lgkmcnt(2)
	v_max_u32_e32 v27, v27, v31
	s_waitcnt lgkmcnt(1)
	v_max_u32_e32 v28, v28, v32
	s_waitcnt lgkmcnt(0)
	v_max_u32_e32 v29, v29, v33
	v_mov_b32_e32 v30, v26
	v_mov_b32_e32 v31, v27
	v_mov_b32_e32 v32, v28
	v_mov_b32_e32 v33, v29
	v_permlane32_swap_b32_e32 v26, v30
	v_permlane32_swap_b32_e32 v27, v31
	v_permlane32_swap_b32_e32 v28, v32
	v_permlane32_swap_b32_e32 v29, v33
	v_max_u32_e32 v26, v26, v30
	v_max_u32_e32 v27, v27, v31
	v_max_u32_e32 v28, v28, v32
	v_max_u32_e32 v29, v29, v33
	v_cmp_eq_u32_e64 s[0:1], 2, v184
	v_and_b32_e32 v236, 127, v26
	v_sub_u32_e32 v236, 127, v236
	v_and_b32_e32 v237, 127, v27
	v_sub_u32_e32 v237, 127, v237
	v_and_b32_e32 v238, 127, v28
	v_sub_u32_e32 v238, 127, v238
	v_and_b32_e32 v239, 127, v29
	v_sub_u32_e32 v239, 127, v239
	v_cndmask_b32_e64 v82, v82, v236, s[0:1]
	v_cndmask_b32_e64 v83, v83, v237, s[0:1]
	v_cndmask_b32_e64 v84, v84, v238, s[0:1]
	v_cndmask_b32_e64 v85, v85, v239, s[0:1]
	v_cmp_eq_u32_e64 s[14:15], v26, v18
	v_cmp_eq_u32_e64 s[34:35], v26, v22
	v_cmp_eq_u32_e64 s[42:43], v27, v19
	v_cmp_eq_u32_e64 s[66:67], v27, v23
	v_cndmask_b32_e64 v18, v18, 0, s[14:15]
	v_cndmask_b32_e64 v22, v22, 0, s[34:35]
	v_cndmask_b32_e64 v19, v19, 0, s[42:43]
	v_cndmask_b32_e64 v23, v23, 0, s[66:67]
	v_cmp_eq_u32_e64 s[14:15], v28, v20
	v_cmp_eq_u32_e64 s[34:35], v28, v24
	v_cmp_eq_u32_e64 s[42:43], v29, v21
	v_cmp_eq_u32_e64 s[66:67], v29, v25
	v_cndmask_b32_e64 v20, v20, 0, s[14:15]
	v_cndmask_b32_e64 v24, v24, 0, s[34:35]
	v_cndmask_b32_e64 v21, v21, 0, s[42:43]
	v_cndmask_b32_e64 v25, v25, 0, s[66:67]
	v_max_u32_e32 v26, v18, v22
	v_max_u32_e32 v27, v19, v23
	v_max_u32_e32 v28, v20, v24
	v_max_u32_e32 v29, v21, v25
	v_max_u32_dpp v26, v26, v26 quad_perm:[1,0,3,2] row_mask:0xf bank_mask:0xf
	v_max_u32_dpp v27, v27, v27 quad_perm:[1,0,3,2] row_mask:0xf bank_mask:0xf
	v_max_u32_dpp v28, v28, v28 quad_perm:[1,0,3,2] row_mask:0xf bank_mask:0xf
	v_max_u32_dpp v29, v29, v29 quad_perm:[1,0,3,2] row_mask:0xf bank_mask:0xf
	v_max_u32_dpp v26, v26, v26 quad_perm:[2,3,0,1] row_mask:0xf bank_mask:0xf
	v_max_u32_dpp v27, v27, v27 quad_perm:[2,3,0,1] row_mask:0xf bank_mask:0xf
	v_max_u32_dpp v28, v28, v28 quad_perm:[2,3,0,1] row_mask:0xf bank_mask:0xf
	v_max_u32_dpp v29, v29, v29 quad_perm:[2,3,0,1] row_mask:0xf bank_mask:0xf
	v_max_u32_dpp v26, v26, v26 row_half_mirror row_mask:0xf bank_mask:0xf
	v_max_u32_dpp v27, v27, v27 row_half_mirror row_mask:0xf bank_mask:0xf
	v_max_u32_dpp v28, v28, v28 row_half_mirror row_mask:0xf bank_mask:0xf
	v_max_u32_dpp v29, v29, v29 row_half_mirror row_mask:0xf bank_mask:0xf
	v_max_u32_dpp v26, v26, v26 row_mirror row_mask:0xf bank_mask:0xf
	v_max_u32_dpp v27, v27, v27 row_mirror row_mask:0xf bank_mask:0xf
	v_max_u32_dpp v28, v28, v28 row_mirror row_mask:0xf bank_mask:0xf
	v_max_u32_dpp v29, v29, v29 row_mirror row_mask:0xf bank_mask:0xf
	ds_swizzle_b32 v30, v26 offset:0x401f
	ds_swizzle_b32 v31, v27 offset:0x401f
	ds_swizzle_b32 v32, v28 offset:0x401f
	ds_swizzle_b32 v33, v29 offset:0x401f
	s_waitcnt lgkmcnt(3)
	v_max_u32_e32 v26, v26, v30
	s_waitcnt lgkmcnt(2)
	v_max_u32_e32 v27, v27, v31
	s_waitcnt lgkmcnt(1)
	v_max_u32_e32 v28, v28, v32
	s_waitcnt lgkmcnt(0)
	v_max_u32_e32 v29, v29, v33
	v_mov_b32_e32 v30, v26
	v_mov_b32_e32 v31, v27
	v_mov_b32_e32 v32, v28
	v_mov_b32_e32 v33, v29
	v_permlane32_swap_b32_e32 v26, v30
	v_permlane32_swap_b32_e32 v27, v31
	v_permlane32_swap_b32_e32 v28, v32
	v_permlane32_swap_b32_e32 v29, v33
	v_max_u32_e32 v26, v26, v30
	v_max_u32_e32 v27, v27, v31
	v_max_u32_e32 v28, v28, v32
	v_max_u32_e32 v29, v29, v33
	v_cmp_eq_u32_e64 s[0:1], 3, v184
	v_and_b32_e32 v236, 127, v26
	v_sub_u32_e32 v236, 127, v236
	v_and_b32_e32 v237, 127, v27
	v_sub_u32_e32 v237, 127, v237
	v_and_b32_e32 v238, 127, v28
	v_sub_u32_e32 v238, 127, v238
	v_and_b32_e32 v239, 127, v29
	v_sub_u32_e32 v239, 127, v239
	v_cndmask_b32_e64 v82, v82, v236, s[0:1]
	v_cndmask_b32_e64 v83, v83, v237, s[0:1]
	v_cndmask_b32_e64 v84, v84, v238, s[0:1]
	v_cndmask_b32_e64 v85, v85, v239, s[0:1]
	v_cmp_eq_u32_e64 s[14:15], v26, v18
	v_cmp_eq_u32_e64 s[34:35], v26, v22
	v_cmp_eq_u32_e64 s[42:43], v27, v19
	v_cmp_eq_u32_e64 s[66:67], v27, v23
	v_cndmask_b32_e64 v18, v18, 0, s[14:15]
	v_cndmask_b32_e64 v22, v22, 0, s[34:35]
	v_cndmask_b32_e64 v19, v19, 0, s[42:43]
	v_cndmask_b32_e64 v23, v23, 0, s[66:67]
	v_cmp_eq_u32_e64 s[14:15], v28, v20
	v_cmp_eq_u32_e64 s[34:35], v28, v24
	v_cmp_eq_u32_e64 s[42:43], v29, v21
	v_cmp_eq_u32_e64 s[66:67], v29, v25
	v_cndmask_b32_e64 v20, v20, 0, s[14:15]
	v_cndmask_b32_e64 v24, v24, 0, s[34:35]
	v_cndmask_b32_e64 v21, v21, 0, s[42:43]
	v_cndmask_b32_e64 v25, v25, 0, s[66:67]
	v_max_u32_e32 v26, v18, v22
	v_max_u32_e32 v27, v19, v23
	v_max_u32_e32 v28, v20, v24
	v_max_u32_e32 v29, v21, v25
	v_max_u32_dpp v26, v26, v26 quad_perm:[1,0,3,2] row_mask:0xf bank_mask:0xf
	v_max_u32_dpp v27, v27, v27 quad_perm:[1,0,3,2] row_mask:0xf bank_mask:0xf
	v_max_u32_dpp v28, v28, v28 quad_perm:[1,0,3,2] row_mask:0xf bank_mask:0xf
	v_max_u32_dpp v29, v29, v29 quad_perm:[1,0,3,2] row_mask:0xf bank_mask:0xf
	v_max_u32_dpp v26, v26, v26 quad_perm:[2,3,0,1] row_mask:0xf bank_mask:0xf
	v_max_u32_dpp v27, v27, v27 quad_perm:[2,3,0,1] row_mask:0xf bank_mask:0xf
	v_max_u32_dpp v28, v28, v28 quad_perm:[2,3,0,1] row_mask:0xf bank_mask:0xf
	v_max_u32_dpp v29, v29, v29 quad_perm:[2,3,0,1] row_mask:0xf bank_mask:0xf
	v_max_u32_dpp v26, v26, v26 row_half_mirror row_mask:0xf bank_mask:0xf
	v_max_u32_dpp v27, v27, v27 row_half_mirror row_mask:0xf bank_mask:0xf
	v_max_u32_dpp v28, v28, v28 row_half_mirror row_mask:0xf bank_mask:0xf
	v_max_u32_dpp v29, v29, v29 row_half_mirror row_mask:0xf bank_mask:0xf
	v_max_u32_dpp v26, v26, v26 row_mirror row_mask:0xf bank_mask:0xf
	v_max_u32_dpp v27, v27, v27 row_mirror row_mask:0xf bank_mask:0xf
	v_max_u32_dpp v28, v28, v28 row_mirror row_mask:0xf bank_mask:0xf
	v_max_u32_dpp v29, v29, v29 row_mirror row_mask:0xf bank_mask:0xf
	ds_swizzle_b32 v30, v26 offset:0x401f
	ds_swizzle_b32 v31, v27 offset:0x401f
	ds_swizzle_b32 v32, v28 offset:0x401f
	ds_swizzle_b32 v33, v29 offset:0x401f
	s_waitcnt lgkmcnt(3)
; __device__ __forceinline__ void nsa_quad_pre(int bg, int quad, const bf16_t* Q, const bf16_t* KV, const bf16_t* KCMP, const bf16_t* VCMPT, const float* GN, bf16_t* ONSA, ...
;     ...
;             for (int it = 0; it < 13; ++it) {
;                 unsigned m = k0 > k1 ? k0 : k1;
; #pragma unroll
;                 for (int off = 32; off >= 1; off >>= 1) { const unsigned o = (unsigned)__shfl_xor((int)m, off); m = o > m ? o : m; }
;                 if (k0 == m) k0 = 0u; if (k1 == m) k1 = 0u;
;                 if (lane == 0) selq[tt * 16 + it] = 127 - (int)(m & 127u);
;             }
;             if (lane == 0) { selq[tt * 16 + 13] = 0; selq[tt * 16 + 14] = cur - 1; selq[tt * 16 + 15] = cur; }
	v_max_u32_e32 v26, v26, v30
	s_waitcnt lgkmcnt(2)
	v_max_u32_e32 v27, v27, v31
	s_waitcnt lgkmcnt(1)
	v_max_u32_e32 v28, v28, v32
	s_waitcnt lgkmcnt(0)
	v_max_u32_e32 v29, v29, v33
	v_mov_b32_e32 v30, v26
	v_mov_b32_e32 v31, v27
	v_mov_b32_e32 v32, v28
	v_mov_b32_e32 v33, v29
	v_permlane32_swap_b32_e32 v26, v30
	v_permlane32_swap_b32_e32 v27, v31
	v_permlane32_swap_b32_e32 v28, v32
	v_permlane32_swap_b32_e32 v29, v33
	v_max_u32_e32 v26, v26, v30
	v_max_u32_e32 v27, v27, v31
	v_max_u32_e32 v28, v28, v32
	v_max_u32_e32 v29, v29, v33
	v_cmp_eq_u32_e64 s[0:1], 4, v184
	v_and_b32_e32 v236, 127, v26
	v_sub_u32_e32 v236, 127, v236
	v_and_b32_e32 v237, 127, v27
	v_sub_u32_e32 v237, 127, v237
	v_and_b32_e32 v238, 127, v28
	v_sub_u32_e32 v238, 127, v238
	v_and_b32_e32 v239, 127, v29
	v_sub_u32_e32 v239, 127, v239
	v_cndmask_b32_e64 v82, v82, v236, s[0:1]
	v_cndmask_b32_e64 v83, v83, v237, s[0:1]
	v_cndmask_b32_e64 v84, v84, v238, s[0:1]
	v_cndmask_b32_e64 v85, v85, v239, s[0:1]
	v_cmp_eq_u32_e64 s[14:15], v26, v18
	v_cmp_eq_u32_e64 s[34:35], v26, v22
	v_cmp_eq_u32_e64 s[42:43], v27, v19
	v_cmp_eq_u32_e64 s[66:67], v27, v23
	v_cndmask_b32_e64 v18, v18, 0, s[14:15]
	v_cndmask_b32_e64 v22, v22, 0, s[34:35]
	v_cndmask_b32_e64 v19, v19, 0, s[42:43]
	v_cndmask_b32_e64 v23, v23, 0, s[66:67]
	v_cmp_eq_u32_e64 s[14:15], v28, v20
	v_cmp_eq_u32_e64 s[34:35], v28, v24
	v_cmp_eq_u32_e64 s[42:43], v29, v21
	v_cmp_eq_u32_e64 s[66:67], v29, v25
	v_cndmask_b32_e64 v20, v20, 0, s[14:15]
	v_cndmask_b32_e64 v24, v24, 0, s[34:35]
	v_cndmask_b32_e64 v21, v21, 0, s[42:43]
	v_cndmask_b32_e64 v25, v25, 0, s[66:67]
	v_max_u32_e32 v26, v18, v22
	v_max_u32_e32 v27, v19, v23
	v_max_u32_e32 v28, v20, v24
	v_max_u32_e32 v29, v21, v25
	v_max_u32_dpp v26, v26, v26 quad_perm:[1,0,3,2] row_mask:0xf bank_mask:0xf
	v_max_u32_dpp v27, v27, v27 quad_perm:[1,0,3,2] row_mask:0xf bank_mask:0xf
	v_max_u32_dpp v28, v28, v28 quad_perm:[1,0,3,2] row_mask:0xf bank_mask:0xf
	v_max_u32_dpp v29, v29, v29 quad_perm:[1,0,3,2] row_mask:0xf bank_mask:0xf
	v_max_u32_dpp v26, v26, v26 quad_perm:[2,3,0,1] row_mask:0xf bank_mask:0xf
	v_max_u32_dpp v27, v27, v27 quad_perm:[2,3,0,1] row_mask:0xf bank_mask:0xf
	v_max_u32_dpp v28, v28, v28 quad_perm:[2,3,0,1] row_mask:0xf bank_mask:0xf
	v_max_u32_dpp v29, v29, v29 quad_perm:[2,3,0,1] row_mask:0xf bank_mask:0xf
	v_max_u32_dpp v26, v26, v26 row_half_mirror row_mask:0xf bank_mask:0xf
	v_max_u32_dpp v27, v27, v27 row_half_mirror row_mask:0xf bank_mask:0xf
	v_max_u32_dpp v28, v28, v28 row_half_mirror row_mask:0xf bank_mask:0xf
	v_max_u32_dpp v29, v29, v29 row_half_mirror row_mask:0xf bank_mask:0xf
	v_max_u32_dpp v26, v26, v26 row_mirror row_mask:0xf bank_mask:0xf
	v_max_u32_dpp v27, v27, v27 row_mirror row_mask:0xf bank_mask:0xf
	v_max_u32_dpp v28, v28, v28 row_mirror row_mask:0xf bank_mask:0xf
	v_max_u32_dpp v29, v29, v29 row_mirror row_mask:0xf bank_mask:0xf
	ds_swizzle_b32 v30, v26 offset:0x401f
	ds_swizzle_b32 v31, v27 offset:0x401f
	ds_swizzle_b32 v32, v28 offset:0x401f
	ds_swizzle_b32 v33, v29 offset:0x401f
	s_waitcnt lgkmcnt(3)
	v_max_u32_e32 v26, v26, v30
	s_waitcnt lgkmcnt(2)
	v_max_u32_e32 v27, v27, v31
	s_waitcnt lgkmcnt(1)
	v_max_u32_e32 v28, v28, v32
	s_waitcnt lgkmcnt(0)
	v_max_u32_e32 v29, v29, v33
	v_mov_b32_e32 v30, v26
	v_mov_b32_e32 v31, v27
	v_mov_b32_e32 v32, v28
	v_mov_b32_e32 v33, v29
	v_permlane32_swap_b32_e32 v26, v30
	v_permlane32_swap_b32_e32 v27, v31
	v_permlane32_swap_b32_e32 v28, v32
	v_permlane32_swap_b32_e32 v29, v33
	v_max_u32_e32 v26, v26, v30
	v_max_u32_e32 v27, v27, v31
	v_max_u32_e32 v28, v28, v32
	v_max_u32_e32 v29, v29, v33
	v_cmp_eq_u32_e64 s[0:1], 5, v184
	v_and_b32_e32 v236, 127, v26
	v_sub_u32_e32 v236, 127, v236
	v_and_b32_e32 v237, 127, v27
	v_sub_u32_e32 v237, 127, v237
	v_and_b32_e32 v238, 127, v28
	v_sub_u32_e32 v238, 127, v238
	v_and_b32_e32 v239, 127, v29
	v_sub_u32_e32 v239, 127, v239
	v_cndmask_b32_e64 v82, v82, v236, s[0:1]
	v_cndmask_b32_e64 v83, v83, v237, s[0:1]
	v_cndmask_b32_e64 v84, v84, v238, s[0:1]
	v_cndmask_b32_e64 v85, v85, v239, s[0:1]
	v_cmp_eq_u32_e64 s[14:15], v26, v18
	v_cmp_eq_u32_e64 s[34:35], v26, v22
	v_cmp_eq_u32_e64 s[42:43], v27, v19
	v_cmp_eq_u32_e64 s[66:67], v27, v23
	v_cndmask_b32_e64 v18, v18, 0, s[14:15]
	v_cndmask_b32_e64 v22, v22, 0, s[34:35]
	v_cndmask_b32_e64 v19, v19, 0, s[42:43]
	v_cndmask_b32_e64 v23, v23, 0, s[66:67]
	v_cmp_eq_u32_e64 s[14:15], v28, v20
	v_cmp_eq_u32_e64 s[34:35], v28, v24
	v_cmp_eq_u32_e64 s[42:43], v29, v21
	v_cmp_eq_u32_e64 s[66:67], v29, v25
	v_cndmask_b32_e64 v20, v20, 0, s[14:15]
	v_cndmask_b32_e64 v24, v24, 0, s[34:35]
	v_cndmask_b32_e64 v21, v21, 0, s[42:43]
	v_cndmask_b32_e64 v25, v25, 0, s[66:67]
	v_max_u32_e32 v26, v18, v22
	v_max_u32_e32 v27, v19, v23
	v_max_u32_e32 v28, v20, v24
	v_max_u32_e32 v29, v21, v25
	v_max_u32_dpp v26, v26, v26 quad_perm:[1,0,3,2] row_mask:0xf bank_mask:0xf
	v_max_u32_dpp v27, v27, v27 quad_perm:[1,0,3,2] row_mask:0xf bank_mask:0xf
	v_max_u32_dpp v28, v28, v28 quad_perm:[1,0,3,2] row_mask:0xf bank_mask:0xf
	v_max_u32_dpp v29, v29, v29 quad_perm:[1,0,3,2] row_mask:0xf bank_mask:0xf
	v_max_u32_dpp v26, v26, v26 quad_perm:[2,3,0,1] row_mask:0xf bank_mask:0xf
	v_max_u32_dpp v27, v27, v27 quad_perm:[2,3,0,1] row_mask:0xf bank_mask:0xf
	v_max_u32_dpp v28, v28, v28 quad_perm:[2,3,0,1] row_mask:0xf bank_mask:0xf
	v_max_u32_dpp v29, v29, v29 quad_perm:[2,3,0,1] row_mask:0xf bank_mask:0xf
	v_max_u32_dpp v26, v26, v26 row_half_mirror row_mask:0xf bank_mask:0xf
	v_max_u32_dpp v27, v27, v27 row_half_mirror row_mask:0xf bank_mask:0xf
	v_max_u32_dpp v28, v28, v28 row_half_mirror row_mask:0xf bank_mask:0xf
	v_max_u32_dpp v29, v29, v29 row_half_mirror row_mask:0xf bank_mask:0xf
	v_max_u32_dpp v26, v26, v26 row_mirror row_mask:0xf bank_mask:0xf
	v_max_u32_dpp v27, v27, v27 row_mirror row_mask:0xf bank_mask:0xf
	v_max_u32_dpp v28, v28, v28 row_mirror row_mask:0xf bank_mask:0xf
	v_max_u32_dpp v29, v29, v29 row_mirror row_mask:0xf bank_mask:0xf
	ds_swizzle_b32 v30, v26 offset:0x401f
	ds_swizzle_b32 v31, v27 offset:0x401f
	ds_swizzle_b32 v32, v28 offset:0x401f
	ds_swizzle_b32 v33, v29 offset:0x401f
	s_waitcnt lgkmcnt(3)
; __device__ __forceinline__ void nsa_quad_pre(int bg, int quad, const bf16_t* Q, const bf16_t* KV, const bf16_t* KCMP, const bf16_t* VCMPT, const float* GN, bf16_t* ONSA, ...
;     ...
;             for (int it = 0; it < 13; ++it) {
;                 unsigned m = k0 > k1 ? k0 : k1;
; #pragma unroll
;                 for (int off = 32; off >= 1; off >>= 1) { const unsigned o = (unsigned)__shfl_xor((int)m, off); m = o > m ? o : m; }
;                 if (k0 == m) k0 = 0u; if (k1 == m) k1 = 0u;
;                 if (lane == 0) selq[tt * 16 + it] = 127 - (int)(m & 127u);
;             }
;             if (lane == 0) { selq[tt * 16 + 13] = 0; selq[tt * 16 + 14] = cur - 1; selq[tt * 16 + 15] = cur; }
	v_max_u32_e32 v26, v26, v30
	s_waitcnt lgkmcnt(2)
	v_max_u32_e32 v27, v27, v31
	s_waitcnt lgkmcnt(1)
	v_max_u32_e32 v28, v28, v32
	s_waitcnt lgkmcnt(0)
	v_max_u32_e32 v29, v29, v33
	v_mov_b32_e32 v30, v26
	v_mov_b32_e32 v31, v27
	v_mov_b32_e32 v32, v28
	v_mov_b32_e32 v33, v29
	v_permlane32_swap_b32_e32 v26, v30
	v_permlane32_swap_b32_e32 v27, v31
	v_permlane32_swap_b32_e32 v28, v32
	v_permlane32_swap_b32_e32 v29, v33
	v_max_u32_e32 v26, v26, v30
	v_max_u32_e32 v27, v27, v31
	v_max_u32_e32 v28, v28, v32
	v_max_u32_e32 v29, v29, v33
	v_cmp_eq_u32_e64 s[0:1], 6, v184
	v_and_b32_e32 v236, 127, v26
	v_sub_u32_e32 v236, 127, v236
	v_and_b32_e32 v237, 127, v27
	v_sub_u32_e32 v237, 127, v237
	v_and_b32_e32 v238, 127, v28
	v_sub_u32_e32 v238, 127, v238
	v_and_b32_e32 v239, 127, v29
	v_sub_u32_e32 v239, 127, v239
	v_cndmask_b32_e64 v82, v82, v236, s[0:1]
	v_cndmask_b32_e64 v83, v83, v237, s[0:1]
	v_cndmask_b32_e64 v84, v84, v238, s[0:1]
	v_cndmask_b32_e64 v85, v85, v239, s[0:1]
	v_cmp_eq_u32_e64 s[14:15], v26, v18
	v_cmp_eq_u32_e64 s[34:35], v26, v22
	v_cmp_eq_u32_e64 s[42:43], v27, v19
	v_cmp_eq_u32_e64 s[66:67], v27, v23
	v_cndmask_b32_e64 v18, v18, 0, s[14:15]
	v_cndmask_b32_e64 v22, v22, 0, s[34:35]
	v_cndmask_b32_e64 v19, v19, 0, s[42:43]
	v_cndmask_b32_e64 v23, v23, 0, s[66:67]
	v_cmp_eq_u32_e64 s[14:15], v28, v20
	v_cmp_eq_u32_e64 s[34:35], v28, v24
	v_cmp_eq_u32_e64 s[42:43], v29, v21
	v_cmp_eq_u32_e64 s[66:67], v29, v25
	v_cndmask_b32_e64 v20, v20, 0, s[14:15]
	v_cndmask_b32_e64 v24, v24, 0, s[34:35]
	v_cndmask_b32_e64 v21, v21, 0, s[42:43]
	v_cndmask_b32_e64 v25, v25, 0, s[66:67]
	v_max_u32_e32 v26, v18, v22
	v_max_u32_e32 v27, v19, v23
	v_max_u32_e32 v28, v20, v24
	v_max_u32_e32 v29, v21, v25
	v_max_u32_dpp v26, v26, v26 quad_perm:[1,0,3,2] row_mask:0xf bank_mask:0xf
	v_max_u32_dpp v27, v27, v27 quad_perm:[1,0,3,2] row_mask:0xf bank_mask:0xf
	v_max_u32_dpp v28, v28, v28 quad_perm:[1,0,3,2] row_mask:0xf bank_mask:0xf
	v_max_u32_dpp v29, v29, v29 quad_perm:[1,0,3,2] row_mask:0xf bank_mask:0xf
	v_max_u32_dpp v26, v26, v26 quad_perm:[2,3,0,1] row_mask:0xf bank_mask:0xf
	v_max_u32_dpp v27, v27, v27 quad_perm:[2,3,0,1] row_mask:0xf bank_mask:0xf
	v_max_u32_dpp v28, v28, v28 quad_perm:[2,3,0,1] row_mask:0xf bank_mask:0xf
	v_max_u32_dpp v29, v29, v29 quad_perm:[2,3,0,1] row_mask:0xf bank_mask:0xf
	v_max_u32_dpp v26, v26, v26 row_half_mirror row_mask:0xf bank_mask:0xf
	v_max_u32_dpp v27, v27, v27 row_half_mirror row_mask:0xf bank_mask:0xf
	v_max_u32_dpp v28, v28, v28 row_half_mirror row_mask:0xf bank_mask:0xf
	v_max_u32_dpp v29, v29, v29 row_half_mirror row_mask:0xf bank_mask:0xf
	v_max_u32_dpp v26, v26, v26 row_mirror row_mask:0xf bank_mask:0xf
	v_max_u32_dpp v27, v27, v27 row_mirror row_mask:0xf bank_mask:0xf
	v_max_u32_dpp v28, v28, v28 row_mirror row_mask:0xf bank_mask:0xf
	v_max_u32_dpp v29, v29, v29 row_mirror row_mask:0xf bank_mask:0xf
	ds_swizzle_b32 v30, v26 offset:0x401f
	ds_swizzle_b32 v31, v27 offset:0x401f
	ds_swizzle_b32 v32, v28 offset:0x401f
	ds_swizzle_b32 v33, v29 offset:0x401f
	s_waitcnt lgkmcnt(3)
	v_max_u32_e32 v26, v26, v30
	s_waitcnt lgkmcnt(2)
	v_max_u32_e32 v27, v27, v31
	s_waitcnt lgkmcnt(1)
	v_max_u32_e32 v28, v28, v32
	s_waitcnt lgkmcnt(0)
	v_max_u32_e32 v29, v29, v33
	v_mov_b32_e32 v30, v26
	v_mov_b32_e32 v31, v27
	v_mov_b32_e32 v32, v28
	v_mov_b32_e32 v33, v29
	v_permlane32_swap_b32_e32 v26, v30
	v_permlane32_swap_b32_e32 v27, v31
	v_permlane32_swap_b32_e32 v28, v32
	v_permlane32_swap_b32_e32 v29, v33
	v_max_u32_e32 v26, v26, v30
	v_max_u32_e32 v27, v27, v31
	v_max_u32_e32 v28, v28, v32
	v_max_u32_e32 v29, v29, v33
	v_cmp_eq_u32_e64 s[0:1], 7, v184
	v_and_b32_e32 v236, 127, v26
	v_sub_u32_e32 v236, 127, v236
	v_and_b32_e32 v237, 127, v27
	v_sub_u32_e32 v237, 127, v237
	v_and_b32_e32 v238, 127, v28
	v_sub_u32_e32 v238, 127, v238
	v_and_b32_e32 v239, 127, v29
	v_sub_u32_e32 v239, 127, v239
	v_cndmask_b32_e64 v82, v82, v236, s[0:1]
	v_cndmask_b32_e64 v83, v83, v237, s[0:1]
	v_cndmask_b32_e64 v84, v84, v238, s[0:1]
	v_cndmask_b32_e64 v85, v85, v239, s[0:1]
	v_cmp_eq_u32_e64 s[14:15], v26, v18
	v_cmp_eq_u32_e64 s[34:35], v26, v22
	v_cmp_eq_u32_e64 s[42:43], v27, v19
	v_cmp_eq_u32_e64 s[66:67], v27, v23
	v_cndmask_b32_e64 v18, v18, 0, s[14:15]
	v_cndmask_b32_e64 v22, v22, 0, s[34:35]
	v_cndmask_b32_e64 v19, v19, 0, s[42:43]
	v_cndmask_b32_e64 v23, v23, 0, s[66:67]
	v_cmp_eq_u32_e64 s[14:15], v28, v20
	v_cmp_eq_u32_e64 s[34:35], v28, v24
	v_cmp_eq_u32_e64 s[42:43], v29, v21
	v_cmp_eq_u32_e64 s[66:67], v29, v25
	v_cndmask_b32_e64 v20, v20, 0, s[14:15]
	v_cndmask_b32_e64 v24, v24, 0, s[34:35]
	v_cndmask_b32_e64 v21, v21, 0, s[42:43]
	v_cndmask_b32_e64 v25, v25, 0, s[66:67]
	v_max_u32_e32 v26, v18, v22
	v_max_u32_e32 v27, v19, v23
	v_max_u32_e32 v28, v20, v24
	v_max_u32_e32 v29, v21, v25
	v_max_u32_dpp v26, v26, v26 quad_perm:[1,0,3,2] row_mask:0xf bank_mask:0xf
	v_max_u32_dpp v27, v27, v27 quad_perm:[1,0,3,2] row_mask:0xf bank_mask:0xf
	v_max_u32_dpp v28, v28, v28 quad_perm:[1,0,3,2] row_mask:0xf bank_mask:0xf
	v_max_u32_dpp v29, v29, v29 quad_perm:[1,0,3,2] row_mask:0xf bank_mask:0xf
	v_max_u32_dpp v26, v26, v26 quad_perm:[2,3,0,1] row_mask:0xf bank_mask:0xf
	v_max_u32_dpp v27, v27, v27 quad_perm:[2,3,0,1] row_mask:0xf bank_mask:0xf
	v_max_u32_dpp v28, v28, v28 quad_perm:[2,3,0,1] row_mask:0xf bank_mask:0xf
	v_max_u32_dpp v29, v29, v29 quad_perm:[2,3,0,1] row_mask:0xf bank_mask:0xf
	v_max_u32_dpp v26, v26, v26 row_half_mirror row_mask:0xf bank_mask:0xf
	v_max_u32_dpp v27, v27, v27 row_half_mirror row_mask:0xf bank_mask:0xf
	v_max_u32_dpp v28, v28, v28 row_half_mirror row_mask:0xf bank_mask:0xf
	v_max_u32_dpp v29, v29, v29 row_half_mirror row_mask:0xf bank_mask:0xf
	v_max_u32_dpp v26, v26, v26 row_mirror row_mask:0xf bank_mask:0xf
	v_max_u32_dpp v27, v27, v27 row_mirror row_mask:0xf bank_mask:0xf
	v_max_u32_dpp v28, v28, v28 row_mirror row_mask:0xf bank_mask:0xf
	v_max_u32_dpp v29, v29, v29 row_mirror row_mask:0xf bank_mask:0xf
	ds_swizzle_b32 v30, v26 offset:0x401f
	ds_swizzle_b32 v31, v27 offset:0x401f
	ds_swizzle_b32 v32, v28 offset:0x401f
	ds_swizzle_b32 v33, v29 offset:0x401f
	s_waitcnt lgkmcnt(3)
; __device__ __forceinline__ void nsa_quad_pre(int bg, int quad, const bf16_t* Q, const bf16_t* KV, const bf16_t* KCMP, const bf16_t* VCMPT, const float* GN, bf16_t* ONSA, ...
;     ...
;             for (int it = 0; it < 13; ++it) {
;                 unsigned m = k0 > k1 ? k0 : k1;
; #pragma unroll
;                 for (int off = 32; off >= 1; off >>= 1) { const unsigned o = (unsigned)__shfl_xor((int)m, off); m = o > m ? o : m; }
;                 if (k0 == m) k0 = 0u; if (k1 == m) k1 = 0u;
;                 if (lane == 0) selq[tt * 16 + it] = 127 - (int)(m & 127u);
;             }
;             if (lane == 0) { selq[tt * 16 + 13] = 0; selq[tt * 16 + 14] = cur - 1; selq[tt * 16 + 15] = cur; }
	v_max_u32_e32 v26, v26, v30
	s_waitcnt lgkmcnt(2)
	v_max_u32_e32 v27, v27, v31
	s_waitcnt lgkmcnt(1)
	v_max_u32_e32 v28, v28, v32
	s_waitcnt lgkmcnt(0)
	v_max_u32_e32 v29, v29, v33
	v_mov_b32_e32 v30, v26
	v_mov_b32_e32 v31, v27
	v_mov_b32_e32 v32, v28
	v_mov_b32_e32 v33, v29
	v_permlane32_swap_b32_e32 v26, v30
	v_permlane32_swap_b32_e32 v27, v31
	v_permlane32_swap_b32_e32 v28, v32
	v_permlane32_swap_b32_e32 v29, v33
	v_max_u32_e32 v26, v26, v30
	v_max_u32_e32 v27, v27, v31
	v_max_u32_e32 v28, v28, v32
	v_max_u32_e32 v29, v29, v33
	v_cmp_eq_u32_e64 s[0:1], 8, v184
	v_and_b32_e32 v236, 127, v26
	v_sub_u32_e32 v236, 127, v236
	v_and_b32_e32 v237, 127, v27
	v_sub_u32_e32 v237, 127, v237
	v_and_b32_e32 v238, 127, v28
	v_sub_u32_e32 v238, 127, v238
	v_and_b32_e32 v239, 127, v29
	v_sub_u32_e32 v239, 127, v239
	v_cndmask_b32_e64 v82, v82, v236, s[0:1]
	v_cndmask_b32_e64 v83, v83, v237, s[0:1]
	v_cndmask_b32_e64 v84, v84, v238, s[0:1]
	v_cndmask_b32_e64 v85, v85, v239, s[0:1]
	v_cmp_eq_u32_e64 s[14:15], v26, v18
	v_cmp_eq_u32_e64 s[34:35], v26, v22
	v_cmp_eq_u32_e64 s[42:43], v27, v19
	v_cmp_eq_u32_e64 s[66:67], v27, v23
	v_cndmask_b32_e64 v18, v18, 0, s[14:15]
	v_cndmask_b32_e64 v22, v22, 0, s[34:35]
	v_cndmask_b32_e64 v19, v19, 0, s[42:43]
	v_cndmask_b32_e64 v23, v23, 0, s[66:67]
	v_cmp_eq_u32_e64 s[14:15], v28, v20
	v_cmp_eq_u32_e64 s[34:35], v28, v24
	v_cmp_eq_u32_e64 s[42:43], v29, v21
	v_cmp_eq_u32_e64 s[66:67], v29, v25
	v_cndmask_b32_e64 v20, v20, 0, s[14:15]
	v_cndmask_b32_e64 v24, v24, 0, s[34:35]
	v_cndmask_b32_e64 v21, v21, 0, s[42:43]
	v_cndmask_b32_e64 v25, v25, 0, s[66:67]
	v_max_u32_e32 v26, v18, v22
	v_max_u32_e32 v27, v19, v23
	v_max_u32_e32 v28, v20, v24
	v_max_u32_e32 v29, v21, v25
	v_max_u32_dpp v26, v26, v26 quad_perm:[1,0,3,2] row_mask:0xf bank_mask:0xf
	v_max_u32_dpp v27, v27, v27 quad_perm:[1,0,3,2] row_mask:0xf bank_mask:0xf
	v_max_u32_dpp v28, v28, v28 quad_perm:[1,0,3,2] row_mask:0xf bank_mask:0xf
	v_max_u32_dpp v29, v29, v29 quad_perm:[1,0,3,2] row_mask:0xf bank_mask:0xf
	v_max_u32_dpp v26, v26, v26 quad_perm:[2,3,0,1] row_mask:0xf bank_mask:0xf
	v_max_u32_dpp v27, v27, v27 quad_perm:[2,3,0,1] row_mask:0xf bank_mask:0xf
	v_max_u32_dpp v28, v28, v28 quad_perm:[2,3,0,1] row_mask:0xf bank_mask:0xf
	v_max_u32_dpp v29, v29, v29 quad_perm:[2,3,0,1] row_mask:0xf bank_mask:0xf
	v_max_u32_dpp v26, v26, v26 row_half_mirror row_mask:0xf bank_mask:0xf
	v_max_u32_dpp v27, v27, v27 row_half_mirror row_mask:0xf bank_mask:0xf
	v_max_u32_dpp v28, v28, v28 row_half_mirror row_mask:0xf bank_mask:0xf
	v_max_u32_dpp v29, v29, v29 row_half_mirror row_mask:0xf bank_mask:0xf
	v_max_u32_dpp v26, v26, v26 row_mirror row_mask:0xf bank_mask:0xf
	v_max_u32_dpp v27, v27, v27 row_mirror row_mask:0xf bank_mask:0xf
	v_max_u32_dpp v28, v28, v28 row_mirror row_mask:0xf bank_mask:0xf
	v_max_u32_dpp v29, v29, v29 row_mirror row_mask:0xf bank_mask:0xf
	ds_swizzle_b32 v30, v26 offset:0x401f
	ds_swizzle_b32 v31, v27 offset:0x401f
	ds_swizzle_b32 v32, v28 offset:0x401f
	ds_swizzle_b32 v33, v29 offset:0x401f
	s_waitcnt lgkmcnt(3)
	v_max_u32_e32 v26, v26, v30
	s_waitcnt lgkmcnt(2)
	v_max_u32_e32 v27, v27, v31
	s_waitcnt lgkmcnt(1)
	v_max_u32_e32 v28, v28, v32
	s_waitcnt lgkmcnt(0)
	v_max_u32_e32 v29, v29, v33
	v_mov_b32_e32 v30, v26
	v_mov_b32_e32 v31, v27
	v_mov_b32_e32 v32, v28
	v_mov_b32_e32 v33, v29
	v_permlane32_swap_b32_e32 v26, v30
	v_permlane32_swap_b32_e32 v27, v31
	v_permlane32_swap_b32_e32 v28, v32
	v_permlane32_swap_b32_e32 v29, v33
	v_max_u32_e32 v26, v26, v30
	v_max_u32_e32 v27, v27, v31
	v_max_u32_e32 v28, v28, v32
	v_max_u32_e32 v29, v29, v33
	v_cmp_eq_u32_e64 s[0:1], 9, v184
	v_and_b32_e32 v236, 127, v26
	v_sub_u32_e32 v236, 127, v236
	v_and_b32_e32 v237, 127, v27
	v_sub_u32_e32 v237, 127, v237
	v_and_b32_e32 v238, 127, v28
	v_sub_u32_e32 v238, 127, v238
	v_and_b32_e32 v239, 127, v29
	v_sub_u32_e32 v239, 127, v239
	v_cndmask_b32_e64 v82, v82, v236, s[0:1]
	v_cndmask_b32_e64 v83, v83, v237, s[0:1]
	v_cndmask_b32_e64 v84, v84, v238, s[0:1]
	v_cndmask_b32_e64 v85, v85, v239, s[0:1]
	v_cmp_eq_u32_e64 s[14:15], v26, v18
	v_cmp_eq_u32_e64 s[34:35], v26, v22
	v_cmp_eq_u32_e64 s[42:43], v27, v19
	v_cmp_eq_u32_e64 s[66:67], v27, v23
	v_cndmask_b32_e64 v18, v18, 0, s[14:15]
	v_cndmask_b32_e64 v22, v22, 0, s[34:35]
	v_cndmask_b32_e64 v19, v19, 0, s[42:43]
	v_cndmask_b32_e64 v23, v23, 0, s[66:67]
	v_cmp_eq_u32_e64 s[14:15], v28, v20
	v_cmp_eq_u32_e64 s[34:35], v28, v24
	v_cmp_eq_u32_e64 s[42:43], v29, v21
	v_cmp_eq_u32_e64 s[66:67], v29, v25
	v_cndmask_b32_e64 v20, v20, 0, s[14:15]
	v_cndmask_b32_e64 v24, v24, 0, s[34:35]
	v_cndmask_b32_e64 v21, v21, 0, s[42:43]
	v_cndmask_b32_e64 v25, v25, 0, s[66:67]
	v_max_u32_e32 v26, v18, v22
	v_max_u32_e32 v27, v19, v23
	v_max_u32_e32 v28, v20, v24
	v_max_u32_e32 v29, v21, v25
	v_max_u32_dpp v26, v26, v26 quad_perm:[1,0,3,2] row_mask:0xf bank_mask:0xf
	v_max_u32_dpp v27, v27, v27 quad_perm:[1,0,3,2] row_mask:0xf bank_mask:0xf
	v_max_u32_dpp v28, v28, v28 quad_perm:[1,0,3,2] row_mask:0xf bank_mask:0xf
	v_max_u32_dpp v29, v29, v29 quad_perm:[1,0,3,2] row_mask:0xf bank_mask:0xf
	v_max_u32_dpp v26, v26, v26 quad_perm:[2,3,0,1] row_mask:0xf bank_mask:0xf
	v_max_u32_dpp v27, v27, v27 quad_perm:[2,3,0,1] row_mask:0xf bank_mask:0xf
	v_max_u32_dpp v28, v28, v28 quad_perm:[2,3,0,1] row_mask:0xf bank_mask:0xf
	v_max_u32_dpp v29, v29, v29 quad_perm:[2,3,0,1] row_mask:0xf bank_mask:0xf
	v_max_u32_dpp v26, v26, v26 row_half_mirror row_mask:0xf bank_mask:0xf
	v_max_u32_dpp v27, v27, v27 row_half_mirror row_mask:0xf bank_mask:0xf
	v_max_u32_dpp v28, v28, v28 row_half_mirror row_mask:0xf bank_mask:0xf
	v_max_u32_dpp v29, v29, v29 row_half_mirror row_mask:0xf bank_mask:0xf
	v_max_u32_dpp v26, v26, v26 row_mirror row_mask:0xf bank_mask:0xf
	v_max_u32_dpp v27, v27, v27 row_mirror row_mask:0xf bank_mask:0xf
	v_max_u32_dpp v28, v28, v28 row_mirror row_mask:0xf bank_mask:0xf
	v_max_u32_dpp v29, v29, v29 row_mirror row_mask:0xf bank_mask:0xf
	ds_swizzle_b32 v30, v26 offset:0x401f
	ds_swizzle_b32 v31, v27 offset:0x401f
	ds_swizzle_b32 v32, v28 offset:0x401f
	ds_swizzle_b32 v33, v29 offset:0x401f
	s_waitcnt lgkmcnt(3)
; __device__ __forceinline__ void nsa_quad_pre(int bg, int quad, const bf16_t* Q, const bf16_t* KV, const bf16_t* KCMP, const bf16_t* VCMPT, const float* GN, bf16_t* ONSA, ...
;     ...
;             for (int it = 0; it < 13; ++it) {
;                 unsigned m = k0 > k1 ? k0 : k1;
; #pragma unroll
;                 for (int off = 32; off >= 1; off >>= 1) { const unsigned o = (unsigned)__shfl_xor((int)m, off); m = o > m ? o : m; }
;                 if (k0 == m) k0 = 0u; if (k1 == m) k1 = 0u;
;                 if (lane == 0) selq[tt * 16 + it] = 127 - (int)(m & 127u);
;             }
;             if (lane == 0) { selq[tt * 16 + 13] = 0; selq[tt * 16 + 14] = cur - 1; selq[tt * 16 + 15] = cur; }
	v_max_u32_e32 v26, v26, v30
	s_waitcnt lgkmcnt(2)
	v_max_u32_e32 v27, v27, v31
	s_waitcnt lgkmcnt(1)
	v_max_u32_e32 v28, v28, v32
	s_waitcnt lgkmcnt(0)
	v_max_u32_e32 v29, v29, v33
	v_mov_b32_e32 v30, v26
	v_mov_b32_e32 v31, v27
	v_mov_b32_e32 v32, v28
	v_mov_b32_e32 v33, v29
	v_permlane32_swap_b32_e32 v26, v30
	v_permlane32_swap_b32_e32 v27, v31
	v_permlane32_swap_b32_e32 v28, v32
	v_permlane32_swap_b32_e32 v29, v33
	v_max_u32_e32 v26, v26, v30
	v_max_u32_e32 v27, v27, v31
	v_max_u32_e32 v28, v28, v32
	v_max_u32_e32 v29, v29, v33
	v_cmp_eq_u32_e64 s[0:1], 10, v184
	v_and_b32_e32 v236, 127, v26
	v_sub_u32_e32 v236, 127, v236
	v_and_b32_e32 v237, 127, v27
	v_sub_u32_e32 v237, 127, v237
	v_and_b32_e32 v238, 127, v28
	v_sub_u32_e32 v238, 127, v238
	v_and_b32_e32 v239, 127, v29
	v_sub_u32_e32 v239, 127, v239
	v_cndmask_b32_e64 v82, v82, v236, s[0:1]
	v_cndmask_b32_e64 v83, v83, v237, s[0:1]
	v_cndmask_b32_e64 v84, v84, v238, s[0:1]
	v_cndmask_b32_e64 v85, v85, v239, s[0:1]
	v_cmp_eq_u32_e64 s[14:15], v26, v18
	v_cmp_eq_u32_e64 s[34:35], v26, v22
	v_cmp_eq_u32_e64 s[42:43], v27, v19
	v_cmp_eq_u32_e64 s[66:67], v27, v23
	v_cndmask_b32_e64 v18, v18, 0, s[14:15]
	v_cndmask_b32_e64 v22, v22, 0, s[34:35]
	v_cndmask_b32_e64 v19, v19, 0, s[42:43]
	v_cndmask_b32_e64 v23, v23, 0, s[66:67]
	v_cmp_eq_u32_e64 s[14:15], v28, v20
	v_cmp_eq_u32_e64 s[34:35], v28, v24
	v_cmp_eq_u32_e64 s[42:43], v29, v21
	v_cmp_eq_u32_e64 s[66:67], v29, v25
	v_cndmask_b32_e64 v20, v20, 0, s[14:15]
	v_cndmask_b32_e64 v24, v24, 0, s[34:35]
	v_cndmask_b32_e64 v21, v21, 0, s[42:43]
	v_cndmask_b32_e64 v25, v25, 0, s[66:67]
	v_max_u32_e32 v26, v18, v22
	v_max_u32_e32 v27, v19, v23
	v_max_u32_e32 v28, v20, v24
	v_max_u32_e32 v29, v21, v25
	v_max_u32_dpp v26, v26, v26 quad_perm:[1,0,3,2] row_mask:0xf bank_mask:0xf
	v_max_u32_dpp v27, v27, v27 quad_perm:[1,0,3,2] row_mask:0xf bank_mask:0xf
	v_max_u32_dpp v28, v28, v28 quad_perm:[1,0,3,2] row_mask:0xf bank_mask:0xf
	v_max_u32_dpp v29, v29, v29 quad_perm:[1,0,3,2] row_mask:0xf bank_mask:0xf
	v_max_u32_dpp v26, v26, v26 quad_perm:[2,3,0,1] row_mask:0xf bank_mask:0xf
	v_max_u32_dpp v27, v27, v27 quad_perm:[2,3,0,1] row_mask:0xf bank_mask:0xf
	v_max_u32_dpp v28, v28, v28 quad_perm:[2,3,0,1] row_mask:0xf bank_mask:0xf
	v_max_u32_dpp v29, v29, v29 quad_perm:[2,3,0,1] row_mask:0xf bank_mask:0xf
	v_max_u32_dpp v26, v26, v26 row_half_mirror row_mask:0xf bank_mask:0xf
	v_max_u32_dpp v27, v27, v27 row_half_mirror row_mask:0xf bank_mask:0xf
	v_max_u32_dpp v28, v28, v28 row_half_mirror row_mask:0xf bank_mask:0xf
	v_max_u32_dpp v29, v29, v29 row_half_mirror row_mask:0xf bank_mask:0xf
	v_max_u32_dpp v26, v26, v26 row_mirror row_mask:0xf bank_mask:0xf
	v_max_u32_dpp v27, v27, v27 row_mirror row_mask:0xf bank_mask:0xf
	v_max_u32_dpp v28, v28, v28 row_mirror row_mask:0xf bank_mask:0xf
	v_max_u32_dpp v29, v29, v29 row_mirror row_mask:0xf bank_mask:0xf
	ds_swizzle_b32 v30, v26 offset:0x401f
	ds_swizzle_b32 v31, v27 offset:0x401f
	ds_swizzle_b32 v32, v28 offset:0x401f
	ds_swizzle_b32 v33, v29 offset:0x401f
	s_waitcnt lgkmcnt(3)
	v_max_u32_e32 v26, v26, v30
	s_waitcnt lgkmcnt(2)
	v_max_u32_e32 v27, v27, v31
	s_waitcnt lgkmcnt(1)
	v_max_u32_e32 v28, v28, v32
	s_waitcnt lgkmcnt(0)
; __device__ __forceinline__ void nsa_quad_pre(int bg, int quad, const bf16_t* Q, const bf16_t* KV, const bf16_t* KCMP, const bf16_t* VCMPT, const float* GN, bf16_t* ONSA, ...
;     ...
;             for (int it = 0; it < 13; ++it) {
;                 unsigned m = k0 > k1 ? k0 : k1;
; #pragma unroll
;                 for (int off = 32; off >= 1; off >>= 1) { const unsigned o = (unsigned)__shfl_xor((int)m, off); m = o > m ? o : m; }
;                 if (k0 == m) k0 = 0u; if (k1 == m) k1 = 0u;
;                 if (lane == 0) selq[tt * 16 + it] = 127 - (int)(m & 127u);
;             }
;             if (lane == 0) { selq[tt * 16 + 13] = 0; selq[tt * 16 + 14] = cur - 1; selq[tt * 16 + 15] = cur; }
	v_max_u32_e32 v29, v29, v33
	v_mov_b32_e32 v30, v26
	v_mov_b32_e32 v31, v27
	v_mov_b32_e32 v32, v28
	v_mov_b32_e32 v33, v29
	v_permlane32_swap_b32_e32 v26, v30
	v_permlane32_swap_b32_e32 v27, v31
	v_permlane32_swap_b32_e32 v28, v32
	v_permlane32_swap_b32_e32 v29, v33
	v_max_u32_e32 v26, v26, v30
	v_max_u32_e32 v27, v27, v31
	v_max_u32_e32 v28, v28, v32
	v_max_u32_e32 v29, v29, v33
	v_cmp_eq_u32_e64 s[0:1], 11, v184
	v_and_b32_e32 v236, 127, v26
	v_sub_u32_e32 v236, 127, v236
	v_and_b32_e32 v237, 127, v27
	v_sub_u32_e32 v237, 127, v237
	v_and_b32_e32 v238, 127, v28
	v_sub_u32_e32 v238, 127, v238
	v_and_b32_e32 v239, 127, v29
	v_sub_u32_e32 v239, 127, v239
	v_cndmask_b32_e64 v82, v82, v236, s[0:1]
	v_cndmask_b32_e64 v83, v83, v237, s[0:1]
	v_cndmask_b32_e64 v84, v84, v238, s[0:1]
	v_cndmask_b32_e64 v85, v85, v239, s[0:1]
	v_cmp_eq_u32_e64 s[14:15], v26, v18
	v_cmp_eq_u32_e64 s[34:35], v26, v22
	v_cmp_eq_u32_e64 s[42:43], v27, v19
	v_cmp_eq_u32_e64 s[66:67], v27, v23
	v_cndmask_b32_e64 v18, v18, 0, s[14:15]
	v_cndmask_b32_e64 v22, v22, 0, s[34:35]
	v_cndmask_b32_e64 v19, v19, 0, s[42:43]
	v_cndmask_b32_e64 v23, v23, 0, s[66:67]
	v_cmp_eq_u32_e64 s[14:15], v28, v20
	v_cmp_eq_u32_e64 s[34:35], v28, v24
	v_cmp_eq_u32_e64 s[42:43], v29, v21
	v_cmp_eq_u32_e64 s[66:67], v29, v25
	v_cndmask_b32_e64 v20, v20, 0, s[14:15]
	v_cndmask_b32_e64 v24, v24, 0, s[34:35]
	v_cndmask_b32_e64 v21, v21, 0, s[42:43]
	v_cndmask_b32_e64 v25, v25, 0, s[66:67]
	v_max_u32_e32 v26, v18, v22
	v_max_u32_e32 v27, v19, v23
	v_max_u32_e32 v28, v20, v24
	v_max_u32_e32 v29, v21, v25
	v_max_u32_dpp v26, v26, v26 quad_perm:[1,0,3,2] row_mask:0xf bank_mask:0xf
	v_max_u32_dpp v27, v27, v27 quad_perm:[1,0,3,2] row_mask:0xf bank_mask:0xf
	v_max_u32_dpp v28, v28, v28 quad_perm:[1,0,3,2] row_mask:0xf bank_mask:0xf
	v_max_u32_dpp v29, v29, v29 quad_perm:[1,0,3,2] row_mask:0xf bank_mask:0xf
	v_max_u32_dpp v26, v26, v26 quad_perm:[2,3,0,1] row_mask:0xf bank_mask:0xf
	v_max_u32_dpp v27, v27, v27 quad_perm:[2,3,0,1] row_mask:0xf bank_mask:0xf
	v_max_u32_dpp v28, v28, v28 quad_perm:[2,3,0,1] row_mask:0xf bank_mask:0xf
	v_max_u32_dpp v29, v29, v29 quad_perm:[2,3,0,1] row_mask:0xf bank_mask:0xf
	v_max_u32_dpp v26, v26, v26 row_half_mirror row_mask:0xf bank_mask:0xf
	v_max_u32_dpp v27, v27, v27 row_half_mirror row_mask:0xf bank_mask:0xf
	v_max_u32_dpp v28, v28, v28 row_half_mirror row_mask:0xf bank_mask:0xf
	v_max_u32_dpp v29, v29, v29 row_half_mirror row_mask:0xf bank_mask:0xf
	v_max_u32_dpp v26, v26, v26 row_mirror row_mask:0xf bank_mask:0xf
	v_max_u32_dpp v27, v27, v27 row_mirror row_mask:0xf bank_mask:0xf
	v_max_u32_dpp v28, v28, v28 row_mirror row_mask:0xf bank_mask:0xf
	v_max_u32_dpp v29, v29, v29 row_mirror row_mask:0xf bank_mask:0xf
	ds_swizzle_b32 v30, v26 offset:0x401f
	ds_swizzle_b32 v31, v27 offset:0x401f
	ds_swizzle_b32 v32, v28 offset:0x401f
	ds_swizzle_b32 v33, v29 offset:0x401f
	s_waitcnt lgkmcnt(3)
	v_max_u32_e32 v26, v26, v30
	s_waitcnt lgkmcnt(2)
	v_max_u32_e32 v27, v27, v31
	s_waitcnt lgkmcnt(1)
	v_max_u32_e32 v28, v28, v32
	s_waitcnt lgkmcnt(0)
	v_max_u32_e32 v29, v29, v33
	v_mov_b32_e32 v30, v26
	v_mov_b32_e32 v31, v27
	v_mov_b32_e32 v32, v28
	v_mov_b32_e32 v33, v29
	v_permlane32_swap_b32_e32 v26, v30
	v_permlane32_swap_b32_e32 v27, v31
	v_permlane32_swap_b32_e32 v28, v32
	v_permlane32_swap_b32_e32 v29, v33
	v_max_u32_e32 v26, v26, v30
	v_max_u32_e32 v27, v27, v31
	v_max_u32_e32 v28, v28, v32
	v_max_u32_e32 v29, v29, v33
	v_cmp_eq_u32_e64 s[0:1], 12, v184
	v_and_b32_e32 v236, 127, v26
	v_sub_u32_e32 v236, 127, v236
	v_and_b32_e32 v237, 127, v27
	v_sub_u32_e32 v237, 127, v237
	v_and_b32_e32 v238, 127, v28
	v_sub_u32_e32 v238, 127, v238
	v_and_b32_e32 v239, 127, v29
	v_sub_u32_e32 v239, 127, v239
	v_cndmask_b32_e64 v82, v82, v236, s[0:1]
	v_cndmask_b32_e64 v83, v83, v237, s[0:1]
	v_cndmask_b32_e64 v84, v84, v238, s[0:1]
	v_cndmask_b32_e64 v85, v85, v239, s[0:1]
	s_add_i32 s19, s18, -1
	v_mov_b32_e32 v236, s19
	v_mov_b32_e32 v237, s18
	v_cmp_eq_u32_e64 s[14:15], 14, v184
	v_cmp_eq_u32_e64 s[34:35], 15, v184
	s_nop 0
	v_cndmask_b32_e64 v82, v82, v236, s[14:15]
	v_cndmask_b32_e64 v82, v82, v237, s[34:35]
	v_cndmask_b32_e64 v83, v83, v236, s[14:15]
	v_cndmask_b32_e64 v83, v83, v237, s[34:35]
	v_cndmask_b32_e64 v84, v84, v236, s[14:15]
	v_cndmask_b32_e64 v84, v84, v237, s[34:35]
	v_cndmask_b32_e64 v85, v85, v236, s[14:15]
	v_cndmask_b32_e64 v85, v85, v237, s[34:35]
	s_and_saveexec_b64 s[42:43], s[6:7]
	ds_write_b32 v196, v82 offset:51520
	ds_write_b32 v196, v83 offset:51584
	ds_write_b32 v196, v84 offset:51648
	ds_write_b32 v196, v85 offset:51712
	s_or_b64 exec, exec, s[42:43]
	s_branch .Ltopk_done_q1

; #define LAS __attribute__((address_space(3)))
; template <int MODE> ...
;     ...
;     for (int jA = j0, pp = 0; jA <= qb; jA += 2, pp ^= 1) {
;       for (int sub = 0; sub < 2; ++sub) {
;         const int j = jA + sub; if (j > qb) break;
;         const bool pre = j + 2 <= qb;
;         if (pre) NSA_LD1(j + 2);
;         const LAS bf16_t* Ks = stage + pp * 18432 + sub * 9216; const LAS bf16_t* Vs = Ks + 4608;
;         const bool far = MODE == 0 && (qb - j >= 17);
; #pragma unroll
;         for (int tile = 0; tile < 2; ++tile) {
;             const int tl0 = wave * 8 + tile * 4, t0 = qb * 64 + tl0;
;             unsigned mb[4] = {1u, 1u, 1u, 1u};
;             if (MODE == 0) {
; #pragma unroll
;                 for (int i = 0; i < 4; ++i) mb[i] = (masks[(tl0 + i) * 4 + (j >> 5)] >> (j & 31)) & 1u; }
;             if (MODE == 1 || __builtin_amdgcn_readfirstlane((int)(mb[0] | mb[1] | mb[2] | mb[3]))) {
;                 f32x4 sc[4];
; #pragma unroll
;                 for (int cc = 0; cc < 4; ++cc) { const LAS bf16_t* kp = Ks + (cc * 16 + r16) * 72 + q4 * 8;
;                     sc[cc] = MFMA16(aq[tile][0], *(const LAS bf16x8*)kp, z4); sc[cc] = MFMA16(aq[tile][1], *(const LAS bf16x8*)(kp + 32), sc[cc]); }
;                 if (far) {
; #pragma unroll
;                     for (int cc = 0; cc < 4; ++cc)
; #pragma unroll
;                         for (int i = 0; i < 4; ++i) { const float p = mb[i] ? ex2(sc[cc][i] + bfar) : 0.f; ls[tile][i] += p; Pb[(4 * q4 + i) * 72 + cc * 16 + r16] = tobf(p); }
;                 } else {
; #pragma unroll
;                     for (int cc = 0; cc < 4; ++cc) { const int pos = j * 64 + cc * 16 + r16;
; #pragma unroll
;                         for (int i = 0; i < 4; ++i) { const int dist = t0 + i - pos; const bool ok = MODE ? ((unsigned)dist < 512u) : (dist >= 0 && mb[i]);
;                             const float p = ok ? ex2(sc[cc][i] + bt[clampd(dist)]) : 0.f; ls[tile][i] += p; Pb[(4 * q4 + i) * 72 + cc * 16 + r16] = tobf(p); } }
;                 }
;                 CBAR();
; #pragma unroll
;                 for (int ks = 0; ks < 2; ++ks) { const bf16x8 aP = *(const LAS bf16x8*)(Pb + r16 * 72 + ks * 32 + q4 * 8);
; #pragma unroll
;                     for (int nt = 0; nt < 4; ++nt) os[tile][nt] = MFMA16(aP, *(const LAS bf16x8*)(Vs + (nt * 16 + r16) * 72 + ks * 32 + q4 * 8), os[tile][nt]); }
;                 CBAR();
.Lnsa_blk_loop:
	s_add_i32 s14, s57, 2
	s_min_u32 s15, s14, s19
	v_readlane_b32 s0, v179, s15
	v_readlane_b32 s1, v228, s15
	s_cmp_lt_u32 s15, 64
	s_cselect_b32 s95, s0, s1
	s_and_b32 s73, s95, 255
	s_and_b32 s0, s14, 3
	s_lshl_b32 s0, s0, 14
	s_add_i32 s0, s0, s33
	s_lshl_b32 s1, s73, 13
	s_add_u32 s70, s66, s1
	s_addc_u32 s71, s67, 0
	s_mov_b32 m0, s0
	s_lshl_b32 s1, s73, 7
	global_load_lds_dwordx4 v174, s[70:71]
	s_add_u32 s70, s68, s1
	s_addc_u32 s71, s69, 0
	s_add_i32 m0, s0, 8192
	s_add_i32 s1, s14, 0
	global_load_lds_dwordx4 v175, s[70:71]
	s_cmp_eq_u32 s43, 0
	s_cbranch_scc1 .Lnsa_pvnone_8
	ds_read_b128 v[50:53], v172 offset:0
	ds_read_b128 v[54:57], v173 offset:0
	ds_read_b128 v[58:61], v172 offset:2048
	ds_read_b128 v[62:65], v173 offset:2048
	s_cmp_eq_u32 s43, 3
	s_cbranch_scc0 .Lnsa_pvone_9
	s_waitcnt lgkmcnt(2)
	v_mfma_f32_16x16x32_bf16 v[2:5], v[50:53], v[82:85], v[2:5]
	v_mfma_f32_16x16x32_bf16 v[2:5], v[54:57], v[86:89], v[2:5]
	v_mfma_f32_16x16x32_bf16 v[18:21], v[50:53], v[90:93], v[18:21]
	v_mfma_f32_16x16x32_bf16 v[18:21], v[54:57], v[94:97], v[18:21]
	ds_read_b128 v[50:53], v172 offset:4096
	ds_read_b128 v[54:57], v173 offset:4096
	s_waitcnt lgkmcnt(2)
	v_mfma_f32_16x16x32_bf16 v[6:9], v[58:61], v[82:85], v[6:9]
	v_mfma_f32_16x16x32_bf16 v[6:9], v[62:65], v[86:89], v[6:9]
	v_mfma_f32_16x16x32_bf16 v[22:25], v[58:61], v[90:93], v[22:25]
	v_mfma_f32_16x16x32_bf16 v[22:25], v[62:65], v[94:97], v[22:25]
	ds_read_b128 v[58:61], v172 offset:6144
	ds_read_b128 v[62:65], v173 offset:6144
	s_waitcnt lgkmcnt(2)
	v_mfma_f32_16x16x32_bf16 v[10:13], v[50:53], v[82:85], v[10:13]
	v_mfma_f32_16x16x32_bf16 v[10:13], v[54:57], v[86:89], v[10:13]
	v_mfma_f32_16x16x32_bf16 v[26:29], v[50:53], v[90:93], v[26:29]
	v_mfma_f32_16x16x32_bf16 v[26:29], v[54:57], v[94:97], v[26:29]
	s_waitcnt lgkmcnt(0)
	v_mfma_f32_16x16x32_bf16 v[14:17], v[58:61], v[82:85], v[14:17]
	v_mfma_f32_16x16x32_bf16 v[14:17], v[62:65], v[86:89], v[14:17]
	v_mfma_f32_16x16x32_bf16 v[30:33], v[58:61], v[90:93], v[30:33]
	v_mfma_f32_16x16x32_bf16 v[30:33], v[62:65], v[94:97], v[30:33]
	s_branch .Lnsa_pvend_11

; #define LAS __attribute__((address_space(3)))
; #define MFMA16(a, b, c) __builtin_amdgcn_mfma_f32_16x16x32_bf16(a, b, c, 0, 0, 0)
; __device__ __forceinline__ bf16_t tobf(float x) { return (bf16_t)pk2(x, 0.f); }
; __device__ __forceinline__ float ex2(float x) { return __builtin_amdgcn_exp2f(x); }
; template <int MODE> ...
;     ...
;             if (MODE == 1 || __builtin_amdgcn_readfirstlane((int)(mb[0] | mb[1] | mb[2] | mb[3]))) {
;                 f32x4 sc[4];
; #pragma unroll
;                 for (int cc = 0; cc < 4; ++cc) { const LAS bf16_t* kp = Ks + (cc * 16 + r16) * 72 + q4 * 8;
;                     sc[cc] = MFMA16(aq[tile][0], *(const LAS bf16x8*)kp, z4); sc[cc] = MFMA16(aq[tile][1], *(const LAS bf16x8*)(kp + 32), sc[cc]); }
;                 if (far) {
; #pragma unroll
;                     for (int cc = 0; cc < 4; ++cc)
; #pragma unroll
;                         for (int i = 0; i < 4; ++i) { const float p = mb[i] ? ex2(sc[cc][i] + bfar) : 0.f; ls[tile][i] += p; Pb[(4 * q4 + i) * 72 + cc * 16 + r16] = tobf(p); }
.Lnsa_pfar_16:
	ds_read_b128 v[50:53], v170 offset:0
	ds_read_b128 v[54:57], v171 offset:0
	ds_read_b128 v[58:61], v170 offset:512
	ds_read_b128 v[62:65], v171 offset:512
	v_bfi_b32 v216, v234, v225, v252
	v_bfi_b32 v220, v235, v225, v252
	v_mov_b32_e32 v217, v216
	v_mov_b32_e32 v218, v216
	v_mov_b32_e32 v219, v216
	v_mov_b32_e32 v221, v220
	v_mov_b32_e32 v222, v220
	v_mov_b32_e32 v223, v220
	s_waitcnt lgkmcnt(2)
	v_mfma_f32_16x16x32_bf16 v[66:69], v[50:53], v[34:37], v[216:219]
	v_mfma_f32_16x16x32_bf16 v[66:69], v[54:57], v[38:41], v[66:69]
	v_mfma_f32_16x16x32_bf16 v[236:239], v[50:53], v[42:45], v[220:223]
	v_mfma_f32_16x16x32_bf16 v[236:239], v[54:57], v[46:49], v[236:239]
	ds_read_b128 v[50:53], v170 offset:4096
	ds_read_b128 v[54:57], v171 offset:4096
	s_waitcnt lgkmcnt(2)
	v_mfma_f32_16x16x32_bf16 v[70:73], v[58:61], v[34:37], v[216:219]
	v_mfma_f32_16x16x32_bf16 v[70:73], v[62:65], v[38:41], v[70:73]
	v_mfma_f32_16x16x32_bf16 v[240:243], v[58:61], v[42:45], v[220:223]
	v_mfma_f32_16x16x32_bf16 v[240:243], v[62:65], v[46:49], v[240:243]
	ds_read_b128 v[58:61], v170 offset:4608
	ds_read_b128 v[62:65], v171 offset:4608
	s_waitcnt lgkmcnt(2)
	v_mfma_f32_16x16x32_bf16 v[74:77], v[50:53], v[34:37], v[216:219]
	v_mfma_f32_16x16x32_bf16 v[74:77], v[54:57], v[38:41], v[74:77]
	v_mfma_f32_16x16x32_bf16 v[244:247], v[50:53], v[42:45], v[220:223]
	v_mfma_f32_16x16x32_bf16 v[244:247], v[54:57], v[46:49], v[244:247]
	s_waitcnt lgkmcnt(0)
	v_mfma_f32_16x16x32_bf16 v[78:81], v[58:61], v[34:37], v[216:219]
	v_mfma_f32_16x16x32_bf16 v[78:81], v[62:65], v[38:41], v[78:81]
	v_mfma_f32_16x16x32_bf16 v[248:251], v[58:61], v[42:45], v[220:223]
	v_mfma_f32_16x16x32_bf16 v[248:251], v[62:65], v[46:49], v[248:251]

; template <int MODE> ...
;     ...
;     for (int jA = j0, pp = 0; jA <= qb; jA += 2, pp ^= 1) {
;       for (int sub = 0; sub < 2; ++sub) {
;         const int j = jA + sub; if (j > qb) break;
;         const bool pre = j + 2 <= qb;
;         if (pre) NSA_LD1(j + 2);
;         const LAS bf16_t* Ks = stage + pp * 18432 + sub * 9216; const LAS bf16_t* Vs = Ks + 4608;
;         const bool far = MODE == 0 && (qb - j >= 17);
; #pragma unroll
;         for (int tile = 0; tile < 2; ++tile) {
;             const int tl0 = wave * 8 + tile * 4, t0 = qb * 64 + tl0;
;             unsigned mb[4] = {1u, 1u, 1u, 1u};
;             if (MODE == 0) {
; #pragma unroll
;                 for (int i = 0; i < 4; ++i) mb[i] = (masks[(tl0 + i) * 4 + (j >> 5)] >> (j & 31)) & 1u; }
;             if (MODE == 1 || __builtin_amdgcn_readfirstlane((int)(mb[0] | mb[1] | mb[2] | mb[3]))) {
;                 f32x4 sc[4];
; #pragma unroll
;                 for (int cc = 0; cc < 4; ++cc) { const LAS bf16_t* kp = Ks + (cc * 16 + r16) * 72 + q4 * 8;
;                     sc[cc] = MFMA16(aq[tile][0], *(const LAS bf16x8*)kp, z4); sc[cc] = MFMA16(aq[tile][1], *(const LAS bf16x8*)(kp + 32), sc[cc]); }
;                 if (far) {
; #pragma unroll
;                     for (int cc = 0; cc < 4; ++cc)
; #pragma unroll
;                         for (int i = 0; i < 4; ++i) { const float p = mb[i] ? ex2(sc[cc][i] + bfar) : 0.f; ls[tile][i] += p; Pb[(4 * q4 + i) * 72 + cc * 16 + r16] = tobf(p); }
;                 } else {
; #pragma unroll
;                     for (int cc = 0; cc < 4; ++cc) { const int pos = j * 64 + cc * 16 + r16;
; #pragma unroll
;                         for (int i = 0; i < 4; ++i) { const int dist = t0 + i - pos; const bool ok = MODE ? ((unsigned)dist < 512u) : (dist >= 0 && mb[i]);
;                             const float p = ok ? ex2(sc[cc][i] + bt[clampd(dist)]) : 0.f; ls[tile][i] += p; Pb[(4 * q4 + i) * 72 + cc * 16 + r16] = tobf(p); } }
;                 }
;                 CBAR();
; #pragma unroll
;                 for (int ks = 0; ks < 2; ++ks) { const bf16x8 aP = *(const LAS bf16x8*)(Pb + r16 * 72 + ks * 32 + q4 * 8);
; #pragma unroll
;                     for (int nt = 0; nt < 4; ++nt) os[tile][nt] = MFMA16(aP, *(const LAS bf16x8*)(Vs + (nt * 16 + r16) * 72 + ks * 32 + q4 * 8), os[tile][nt]); }
;                 CBAR();
;             }
;         }
.Lnsa_blkend_15:
	s_waitcnt vmcnt(2) lgkmcnt(0)
	s_barrier
	s_mov_b32 s93, s94
	s_mov_b32 s94, s95
	s_add_i32 s57, s57, 1
	s_cmp_lt_u32 s57, s92
	s_cbranch_scc1 .Lnsa_blk_loop
	s_cmp_eq_u32 s43, 0
	s_cbranch_scc1 .Lnsa_pvnone_24
	ds_read_b128 v[50:53], v172 offset:0
	ds_read_b128 v[54:57], v173 offset:0
	ds_read_b128 v[58:61], v172 offset:2048
	ds_read_b128 v[62:65], v173 offset:2048
	s_cmp_eq_u32 s43, 3
	s_cbranch_scc0 .Lnsa_pvone_25
	s_waitcnt lgkmcnt(2)
	v_mfma_f32_16x16x32_bf16 v[2:5], v[50:53], v[82:85], v[2:5]
	v_mfma_f32_16x16x32_bf16 v[2:5], v[54:57], v[86:89], v[2:5]
	v_mfma_f32_16x16x32_bf16 v[18:21], v[50:53], v[90:93], v[18:21]
	v_mfma_f32_16x16x32_bf16 v[18:21], v[54:57], v[94:97], v[18:21]
	ds_read_b128 v[50:53], v172 offset:4096
	ds_read_b128 v[54:57], v173 offset:4096
	s_waitcnt lgkmcnt(2)
	v_mfma_f32_16x16x32_bf16 v[6:9], v[58:61], v[82:85], v[6:9]
	v_mfma_f32_16x16x32_bf16 v[6:9], v[62:65], v[86:89], v[6:9]
	v_mfma_f32_16x16x32_bf16 v[22:25], v[58:61], v[90:93], v[22:25]
	v_mfma_f32_16x16x32_bf16 v[22:25], v[62:65], v[94:97], v[22:25]
	ds_read_b128 v[58:61], v172 offset:6144
	ds_read_b128 v[62:65], v173 offset:6144
	s_waitcnt lgkmcnt(2)
	v_mfma_f32_16x16x32_bf16 v[10:13], v[50:53], v[82:85], v[10:13]
	v_mfma_f32_16x16x32_bf16 v[10:13], v[54:57], v[86:89], v[10:13]
	v_mfma_f32_16x16x32_bf16 v[26:29], v[50:53], v[90:93], v[26:29]
	v_mfma_f32_16x16x32_bf16 v[26:29], v[54:57], v[94:97], v[26:29]
	s_waitcnt lgkmcnt(0)
	v_mfma_f32_16x16x32_bf16 v[14:17], v[58:61], v[82:85], v[14:17]
	v_mfma_f32_16x16x32_bf16 v[14:17], v[62:65], v[86:89], v[14:17]
	v_mfma_f32_16x16x32_bf16 v[30:33], v[58:61], v[90:93], v[30:33]
	v_mfma_f32_16x16x32_bf16 v[30:33], v[62:65], v[94:97], v[30:33]
	s_branch .Lnsa_pvend_27
